# first K-iteration after each epilogue waits with vmcnt(8+E) so the epilogue stores drain under the first two MFMA segments (prologue drains fully first); P1a plain tiles take a straight-line epilogue
# baseline (speedup 1.0000x reference)
; #define PG8_STAGE(bufoff, gbase, voff) do { _Pragma("unroll") for (int _i = 0; _i < 2; ++_i) \
;         __builtin_amdgcn_global_load_lds((const unsigned*)((const char*)(gbase) + (voff)[_i]), (PG8_LAS unsigned*)(lds + (bufoff) + ldsw + _i * 8192), 16, 0, 0); } while (0)
; #define PG8_WAIT_V(n) asm volatile("s_waitcnt vmcnt(" #n ")" ::: "memory")
; #define PG8_BAR __builtin_amdgcn_s_barrier()
; template <class Epi, class Sched, bool ALIGN_EPI = false, bool SP2 = false>
; __device__ __forceinline__ void gemm_phase(PG8_LAS unsigned char* lds, const Gemm g, const Sched& S, const Epi& E) {
;     ...
;     const char* cA = (const char*)g.A + (size_t)cur.pm * tstepA + (size_t)cur.kz * kzb; const char* cB = (const char*)g.Bt + (size_t)cur.pn * tstepB + (size_t)cur.kz * kzb;
;     S.a_ready(cur);
;     if constexpr (SP2) {
;         PG8_STAGE(PG8_SB(0, 0), cB, voffB); PG8_STAGE(PG8_SB(0, 1), cB + hstepB, voffB); PG8_STAGE(PG8_SA(0, 0), cA, voffA); PG8_STAGE(PG8_SA(0, 1), cA + hstepA, voffA);
;         if (wr == 1) PG8_BAR;
;         PG8_WAIT_V(2); PG8_BAR;
;         PG8_STAGE(PG8_SB(1, 0), cB + kstep, voffB); PG8_STAGE(PG8_SA(1, 0), cA + kstep, voffA); PG8_STAGE(PG8_SB(1, 1), cB + hstepB + kstep, voffB);
;         PG8_WAIT_V(6); PG8_BAR;
.LBB0_305:
	s_add_u32 s40, s26, 0x10800000
	s_addc_u32 s41, s27, 0
	s_add_u32 s42, s26, 0x14820000
	s_mov_b64 s[46:47], 0x80
	s_addc_u32 s43, s27, 0
	s_lshl_b32 s5, s5, 5
	s_add_i32 m0, s9, 0x18000
	v_lshl_add_u64 v[6:7], v[6:7], 0, s[46:47]
	s_lshl_b32 s33, s4, 13
	s_and_b32 s31, s5, 0x60
	s_waitcnt vmcnt(2)
	s_barrier
	global_load_lds_dwordx4 v[6:7], off
	v_lshl_add_u64 v[4:5], v[4:5], 0, s[46:47]
	s_add_i32 m0, s9, 0x1a000
	s_add_i32 s34, s9, 0x8000
	s_add_i32 s35, s9, 0xa000
	global_load_lds_dwordx4 v[4:5], off
	v_lshl_add_u64 v[0:1], v[0:1], 0, s[46:47]
	s_mov_b32 m0, s34
	s_add_u32 s48, s68, 0x80080
	global_load_lds_dwordx4 v[0:1], off
	v_lshl_add_u64 v[0:1], v[2:3], 0, s[46:47]
	s_mov_b32 m0, s35
	s_addc_u32 s49, s69, 0
	global_load_lds_dwordx4 v[0:1], off
	s_add_i32 m0, s9, 0x1c000
	v_lshl_add_u64 v[0:1], s[48:49], 0, v[130:131]
	global_load_lds_dwordx4 v[0:1], off
	v_lshl_add_u64 v[0:1], s[48:49], 0, v[134:135]
	s_add_i32 m0, s9, 0x1e000
	v_lshlrev_b32_e32 v2, 12, v169
	global_load_lds_dwordx4 v[0:1], off
	v_lshlrev_b32_e32 v1, 2, v171
	v_lshl_or_b32 v0, v171, 6, v172
	v_and_b32_e32 v1, 32, v1
	v_bitop3_b32 v0, v0, s33, v1 bitop3:0xde
	v_lshlrev_b32_e32 v1, 9, v162
	v_and_b32_e32 v1, 0x70000, v1
	v_or3_b32 v1, v163, v1, v2
	v_add_u32_e32 v140, v1, v168
	v_lshlrev_b32_e32 v1, 5, v170
	s_waitcnt vmcnt(0)
	s_cmpk_lt_u32 s20, 0x100
	v_and_b32_e32 v1, 0xf0000, v1
	v_lshl_or_b32 v174, s31, 7, v173
	s_cselect_b64 s[48:49], -1, 0
	v_or3_b32 v1, v163, v1, v2
	s_add_i32 s72, 0, 0x10000
	s_add_i32 s73, 0, 0x14000
	s_mov_b32 s50, 0xffa00000
	v_lshl_or_b32 v137, s4, 6, v171
	v_or_b32_e32 v175, s31, v136
	v_mov_b32_e32 v141, v139
	v_add_u32_e32 v142, v1, v168
	v_mov_b32_e32 v143, v139
	v_mov_b64_e32 v[144:145], 0x1290
	v_mov_b64_e32 v[146:147], 0x128f
	v_add_u32_e32 v176, s72, v174
	v_add_u32_e32 v177, s73, v174
	v_add_u32_e32 v178, 0, v0
	s_mov_b32 s51, -1
	s_movk_i32 s74, 0x4800
	s_mov_b32 s75, 0
	s_barrier
	s_branch .LBB0_308

; template <class Epi, class Sched, bool ALIGN_EPI = false, bool SP2 = false>
; __device__ __forceinline__ void gemm_phase(PG8_LAS unsigned char* lds, const Gemm g, const Sched& S, const Epi& E) {
;     ...
;         const bool has_next = S.next(ui + 1, nxt);
;         const char* nA = has_next ? (const char*)g.A + (size_t)nxt.pm * tstepA + (size_t)nxt.kz * kzb : cA; const char* nB = has_next ? (const char*)g.Bt + (size_t)nxt.pn * tstepB + (size_t)nxt.kz * kzb : cB;
;     ...
; #pragma unroll
;         for (int a = 0; a < 2; ++a)
; #pragma unroll
;             for (int b = 0; b < 2; ++b)
; #pragma unroll
;                 for (int m = 0; m < 4; ++m)
; #pragma unroll
;                     for (int n = 0; n < 2; ++n) acc[a][b][m][n] = (f32x4){0.f, 0.f, 0.f, 0.f};
;         cur = nxt; cA = nA; cB = nB; ++ui;
.LBB0_310:
	s_ashr_i32 s61, s60, 31
	s_lshl_b64 s[62:63], s[60:61], 20
	v_readlane_b32 s64, v240, 26
	v_readlane_b32 s65, v240, 27
	s_add_u32 s62, s64, s62
	s_addc_u32 s63, s65, s63
	s_and_b64 s[64:65], s[4:5], exec
	s_cselect_b32 s20, s63, s7
	s_cselect_b32 s33, s62, s6
	s_ashr_i32 s55, s54, 31
	s_lshl_b64 s[64:65], s[54:55], 20
	v_readlane_b32 s76, v240, 3
	v_readlane_b32 s77, v240, 4
	s_add_u32 s64, s76, s64
	s_addc_u32 s65, s77, s65
	s_and_b64 s[70:71], s[4:5], exec
	s_cselect_b32 s55, s65, s69
	s_cselect_b32 s61, s64, s68
	s_add_u32 s6, s6, 0x80080
	s_addc_u32 s7, s7, 0
	v_readlane_b32 s78, v240, 5
	s_add_u32 s76, s68, 0x100
	v_mov_b64_e32 v[0:1], 0
	s_addc_u32 s77, s69, 0
	s_mov_b32 s78, -2
	v_mov_b64_e32 v[2:3], 0
	v_mov_b64_e32 v[4:5], 0
	v_mov_b64_e32 v[6:7], 0
	v_mov_b64_e32 v[16:17], 0
	v_mov_b64_e32 v[18:19], 0
	v_mov_b64_e32 v[20:21], 0
	v_mov_b64_e32 v[22:23], 0
	v_mov_b64_e32 v[32:33], 0
	v_mov_b64_e32 v[34:35], 0
	v_mov_b64_e32 v[36:37], 0
	v_mov_b64_e32 v[38:39], 0
	v_mov_b64_e32 v[48:49], 0
	v_mov_b64_e32 v[50:51], 0
	v_mov_b64_e32 v[52:53], 0
	v_mov_b64_e32 v[54:55], 0
	v_mov_b64_e32 v[8:9], 0
	v_mov_b64_e32 v[10:11], 0
	v_mov_b64_e32 v[12:13], 0
	v_mov_b64_e32 v[14:15], 0
	v_mov_b64_e32 v[24:25], 0
	v_mov_b64_e32 v[26:27], 0
	v_mov_b64_e32 v[28:29], 0
	v_mov_b64_e32 v[30:31], 0
	v_mov_b64_e32 v[40:41], 0
	v_mov_b64_e32 v[42:43], 0
	v_mov_b64_e32 v[44:45], 0
	v_mov_b64_e32 v[46:47], 0
	v_mov_b64_e32 v[56:57], 0
	v_mov_b64_e32 v[58:59], 0
	v_mov_b64_e32 v[60:61], 0
	v_mov_b64_e32 v[62:63], 0
	v_mov_b64_e32 v[64:65], 0
	v_mov_b64_e32 v[66:67], 0
	v_mov_b64_e32 v[68:69], 0
	v_mov_b64_e32 v[70:71], 0
	v_mov_b64_e32 v[80:81], 0
	v_mov_b64_e32 v[82:83], 0
	v_mov_b64_e32 v[84:85], 0
	v_mov_b64_e32 v[86:87], 0
	v_mov_b64_e32 v[96:97], 0
	v_mov_b64_e32 v[98:99], 0
	v_mov_b64_e32 v[100:101], 0
	v_mov_b64_e32 v[102:103], 0
	v_mov_b64_e32 v[112:113], 0
	v_mov_b64_e32 v[114:115], 0
	v_mov_b64_e32 v[116:117], 0
	v_mov_b64_e32 v[118:119], 0
	v_mov_b64_e32 v[72:73], 0
	v_mov_b64_e32 v[74:75], 0
	v_mov_b64_e32 v[76:77], 0
	v_mov_b64_e32 v[78:79], 0
	v_mov_b64_e32 v[88:89], 0
	v_mov_b64_e32 v[90:91], 0
	v_mov_b64_e32 v[92:93], 0
	v_mov_b64_e32 v[94:95], 0
	v_mov_b64_e32 v[104:105], 0
	v_mov_b64_e32 v[106:107], 0
	v_mov_b64_e32 v[108:109], 0
	v_mov_b64_e32 v[110:111], 0
	v_mov_b64_e32 v[120:121], 0
	v_mov_b64_e32 v[122:123], 0
	v_mov_b64_e32 v[124:125], 0
	v_mov_b64_e32 v[126:127], 0
	v_readlane_b32 s79, v240, 6
	s_branch .LBB0_311
.Lrx0_A:
	s_waitcnt vmcnt(16)
	s_branch .Lrx0_A_back

; #define PG8_STAGE(bufoff, gbase, voff) do { _Pragma("unroll") for (int _i = 0; _i < 2; ++_i) \
;         __builtin_amdgcn_global_load_lds((const unsigned*)((const char*)(gbase) + (voff)[_i]), (PG8_LAS unsigned*)(lds + (bufoff) + ldsw + _i * 8192), 16, 0, 0); } while (0)
; #define PG8_LDA(dst, b, h) do { _Pragma("unroll") for (int m = 0; m < 4; ++m) _Pragma("unroll") for (int k = 0; k < 2; ++k) dst[m][k] = *(const PG8_LAS bf16x8*)(lds + PG8_SA(b, h) + aoff + m * 2048 + k * 1024); } while (0)
; #define PG8_LDB(dst, b, h) do { _Pragma("unroll") for (int n = 0; n < 2; ++n) _Pragma("unroll") for (int k = 0; k < 2; ++k) dst[n][k] = *(const PG8_LAS bf16x8*)(lds + PG8_SB(b, h) + boff + n * 2048 + k * 1024); } while (0)
; #define PG8_MMA(ai, bj, At, Bt) do { __builtin_amdgcn_s_setprio(1); _Pragma("unroll") for (int m = 0; m < 4; ++m) _Pragma("unroll") for (int n = 0; n < 2; ++n) _Pragma("unroll") for (int k = 0; k < 2; ++k) \
;         acc[ai][bj][m][n] = __builtin_amdgcn_mfma_f32_16x16x32_bf16(Bt[n][k], At[m][k], acc[ai][bj][m][n], 0, 0, 0); __builtin_amdgcn_s_setprio(0); } while (0)
; #define PG8_WAIT_V(n) asm volatile("s_waitcnt vmcnt(" #n ")" ::: "memory")
; #define PG8_WAIT_L(n) asm volatile("s_waitcnt lgkmcnt(" #n ")" ::: "memory")
; #define PG8_BAR __builtin_amdgcn_s_barrier()
; #define PG8_SCHED __builtin_amdgcn_sched_barrier(0)
; template <class Epi, class Sched, bool ALIGN_EPI = false, bool SP2 = false>
; __device__ __forceinline__ void gemm_phase(PG8_LAS unsigned char* lds, const Gemm g, const Sched& S, const Epi& E) {
;     ...
;             PG8_LDB(B0, 0, 0); PG8_LDB(B1, 0, 1); PG8_SCHED; PG8_LDA(At, 0, 0); PG8_STAGE(PG8_SA(1, 1), a1 + hstepA, voffA);
;             PG8_WAIT_V(8); PG8_WAIT_L(0); PG8_BAR; PG8_MMA(0, 0, At, B0); PG8_MMA(0, 1, At, B1); PG8_BAR; PG8_SCHED;
;             PG8_LDA(At, 0, 1); PG8_STAGE(PG8_SB(0, 0), b2, voffB); PG8_STAGE(PG8_SB(0, 1), b2 + hstepB, voffB); PG8_STAGE(PG8_SA(0, 0), a2, voffA);
.LBB0_311:
	ds_read_b128 v[148:151], v176
	ds_read_b128 v[152:155], v176 offset:1024
	ds_read_b128 v[156:159], v176 offset:2048
	ds_read_b128 v[180:183], v176 offset:3072
	ds_read_b128 v[184:187], v177
	ds_read_b128 v[188:191], v177 offset:1024
	ds_read_b128 v[192:195], v177 offset:2048
	ds_read_b128 v[196:199], v177 offset:3072
	s_add_u32 s68, s6, 0xfff80080
	s_addc_u32 s69, s7, -1
	s_cmp_eq_u32 s78, 28
	s_cselect_b32 s71, s20, s69
	s_cselect_b32 s70, s33, s68
	s_cselect_b32 s69, s55, s77
	s_cselect_b32 s68, s61, s76
	s_add_i32 m0, s9, 0xc000
	ds_read_b128 v[200:203], v178
	ds_read_b128 v[204:207], v178 offset:1024
	ds_read_b128 v[208:211], v178 offset:2048
	ds_read_b128 v[212:215], v178 offset:3072
	ds_read_b128 v[216:219], v178 offset:4096
	ds_read_b128 v[220:223], v178 offset:5120
	ds_read_b128 v[224:227], v178 offset:6144
	ds_read_b128 v[228:231], v178 offset:7168
	global_load_lds_dwordx4 v140, s[6:7]
	s_add_i32 m0, s9, 0xe000
	s_nop 0
	global_load_lds_dwordx4 v142, s[6:7]
	s_cmp_eq_u32 s78, -2
	s_cbranch_scc1 .Lrx0_A
	s_waitcnt vmcnt(8)
.Lrx0_A_back:
	s_waitcnt lgkmcnt(0)
	s_barrier
	s_setprio 0
	s_waitcnt lgkmcnt(0)
	v_mfma_f32_16x16x32_bf16 v[124:127], v[148:151], v[200:203], v[124:127]
	v_mfma_f32_16x16x32_bf16 v[120:123], v[156:159], v[200:203], v[120:123]
	v_mfma_f32_16x16x32_bf16 v[108:111], v[148:151], v[208:211], v[108:111]
	v_mfma_f32_16x16x32_bf16 v[104:107], v[156:159], v[208:211], v[104:107]
	v_mfma_f32_16x16x32_bf16 v[92:95], v[148:151], v[216:219], v[92:95]
	v_mfma_f32_16x16x32_bf16 v[88:91], v[156:159], v[216:219], v[88:91]
	v_mfma_f32_16x16x32_bf16 v[76:79], v[148:151], v[224:227], v[76:79]
	v_mfma_f32_16x16x32_bf16 v[72:75], v[156:159], v[224:227], v[72:75]
	v_mfma_f32_16x16x32_bf16 v[124:127], v[152:155], v[204:207], v[124:127]
	v_mfma_f32_16x16x32_bf16 v[120:123], v[180:183], v[204:207], v[120:123]
	v_mfma_f32_16x16x32_bf16 v[108:111], v[152:155], v[212:215], v[108:111]
	v_mfma_f32_16x16x32_bf16 v[104:107], v[180:183], v[212:215], v[104:107]
	v_mfma_f32_16x16x32_bf16 v[92:95], v[152:155], v[220:223], v[92:95]
	v_mfma_f32_16x16x32_bf16 v[88:91], v[180:183], v[220:223], v[88:91]
	v_mfma_f32_16x16x32_bf16 v[76:79], v[152:155], v[228:231], v[76:79]
	v_mfma_f32_16x16x32_bf16 v[72:75], v[180:183], v[228:231], v[72:75]
	v_mfma_f32_16x16x32_bf16 v[116:119], v[184:187], v[200:203], v[116:119]
	v_mfma_f32_16x16x32_bf16 v[112:115], v[192:195], v[200:203], v[112:115]
	v_mfma_f32_16x16x32_bf16 v[100:103], v[184:187], v[208:211], v[100:103]
	v_mfma_f32_16x16x32_bf16 v[96:99], v[192:195], v[208:211], v[96:99]
	v_mfma_f32_16x16x32_bf16 v[84:87], v[184:187], v[216:219], v[84:87]
	v_mfma_f32_16x16x32_bf16 v[80:83], v[192:195], v[216:219], v[80:83]
	v_mfma_f32_16x16x32_bf16 v[68:71], v[184:187], v[224:227], v[68:71]
	v_mfma_f32_16x16x32_bf16 v[64:67], v[192:195], v[224:227], v[64:67]
	v_mfma_f32_16x16x32_bf16 v[116:119], v[188:191], v[204:207], v[116:119]
	v_mfma_f32_16x16x32_bf16 v[112:115], v[196:199], v[204:207], v[112:115]
	v_mfma_f32_16x16x32_bf16 v[100:103], v[188:191], v[212:215], v[100:103]
	v_mfma_f32_16x16x32_bf16 v[96:99], v[196:199], v[212:215], v[96:99]
	v_mfma_f32_16x16x32_bf16 v[84:87], v[188:191], v[220:223], v[84:87]
	v_mfma_f32_16x16x32_bf16 v[80:83], v[196:199], v[220:223], v[80:83]
	v_mfma_f32_16x16x32_bf16 v[68:71], v[188:191], v[228:231], v[68:71]
	v_mfma_f32_16x16x32_bf16 v[64:67], v[196:199], v[228:231], v[64:67]
	s_setprio 1
	s_barrier
	s_add_i32 s79, s72, s28
	v_lshl_add_u64 v[160:161], s[68:69], 0, v[130:131]
	s_mov_b32 m0, s79
	ds_read_b128 v[200:203], v178 offset:16384
	ds_read_b128 v[204:207], v178 offset:17408
	ds_read_b128 v[208:211], v178 offset:18432
	ds_read_b128 v[212:215], v178 offset:19456
	ds_read_b128 v[216:219], v178 offset:20480
	ds_read_b128 v[220:223], v178 offset:21504
	ds_read_b128 v[224:227], v178 offset:22528
	ds_read_b128 v[228:231], v178 offset:23552
	global_load_lds_dwordx4 v130, s[68:69]
	s_add_i32 m0, s79, 0x2000
	s_add_u32 s80, s68, 0x80000
	v_lshl_add_u64 v[232:233], s[68:69], 0, v[134:135]
	s_addc_u32 s81, s69, 0
	s_add_i32 s79, s73, s28
	global_load_lds_dwordx4 v134, s[68:69]
	s_mov_b32 m0, s79
	v_lshl_add_u64 v[236:237], s[70:71], 0, v[132:133]
	global_load_lds_dwordx4 v130, s[80:81]
	s_add_i32 m0, s79, 0x2000
	s_nop 0
	global_load_lds_dwordx4 v134, s[80:81]
	v_lshl_add_u64 v[234:235], s[70:71], 0, v[128:129]
	s_mov_b32 m0, s9
	s_nop 0
	global_load_lds_dwordx4 v128, s[70:71]
	s_mov_b32 m0, s19
	s_nop 0
	global_load_lds_dwordx4 v132, s[70:71]
	s_cmp_eq_u32 s78, -2
	s_cbranch_scc1 .Lrx0_B
	s_waitcnt vmcnt(8)
; #define PG8_STAGE(bufoff, gbase, voff) do { _Pragma("unroll") for (int _i = 0; _i < 2; ++_i) \
;         __builtin_amdgcn_global_load_lds((const unsigned*)((const char*)(gbase) + (voff)[_i]), (PG8_LAS unsigned*)(lds + (bufoff) + ldsw + _i * 8192), 16, 0, 0); } while (0)
; #define PG8_LDA(dst, b, h) do { _Pragma("unroll") for (int m = 0; m < 4; ++m) _Pragma("unroll") for (int k = 0; k < 2; ++k) dst[m][k] = *(const PG8_LAS bf16x8*)(lds + PG8_SA(b, h) + aoff + m * 2048 + k * 1024); } while (0)
; #define PG8_LDB(dst, b, h) do { _Pragma("unroll") for (int n = 0; n < 2; ++n) _Pragma("unroll") for (int k = 0; k < 2; ++k) dst[n][k] = *(const PG8_LAS bf16x8*)(lds + PG8_SB(b, h) + boff + n * 2048 + k * 1024); } while (0)
; #define PG8_MMA(ai, bj, At, Bt) do { __builtin_amdgcn_s_setprio(1); _Pragma("unroll") for (int m = 0; m < 4; ++m) _Pragma("unroll") for (int n = 0; n < 2; ++n) _Pragma("unroll") for (int k = 0; k < 2; ++k) \
;         acc[ai][bj][m][n] = __builtin_amdgcn_mfma_f32_16x16x32_bf16(Bt[n][k], At[m][k], acc[ai][bj][m][n], 0, 0, 0); __builtin_amdgcn_s_setprio(0); } while (0)
; #define PG8_WAIT_V(n) asm volatile("s_waitcnt vmcnt(" #n ")" ::: "memory")
; #define PG8_WAIT_L(n) asm volatile("s_waitcnt lgkmcnt(" #n ")" ::: "memory")
; #define PG8_BAR __builtin_amdgcn_s_barrier()
; #define PG8_SCHED __builtin_amdgcn_sched_barrier(0)
; template <class Epi, class Sched, bool ALIGN_EPI = false, bool SP2 = false>
; __device__ __forceinline__ void gemm_phase(PG8_LAS unsigned char* lds, const Gemm g, const Sched& S, const Epi& E) {
;     ...
;             PG8_WAIT_V(8); PG8_WAIT_L(0); PG8_BAR; PG8_MMA(1, 0, At, B0); PG8_MMA(1, 1, At, B1); PG8_BAR; PG8_SCHED;
;             PG8_LDB(B0, 1, 0); PG8_LDB(B1, 1, 1); PG8_SCHED; PG8_LDA(At, 1, 0); PG8_STAGE(PG8_SA(0, 1), a2 + hstepA, voffA);
;             PG8_WAIT_V(8); PG8_WAIT_L(0); PG8_BAR; PG8_MMA(0, 0, At, B0); PG8_MMA(0, 1, At, B1); PG8_BAR; PG8_SCHED;
.Lrx0_B_back:
	s_waitcnt lgkmcnt(0)
	s_barrier
	s_setprio 0
	s_waitcnt lgkmcnt(0)
	v_mfma_f32_16x16x32_bf16 v[60:63], v[148:151], v[200:203], v[60:63]
	v_mfma_f32_16x16x32_bf16 v[56:59], v[156:159], v[200:203], v[56:59]
	v_mfma_f32_16x16x32_bf16 v[44:47], v[148:151], v[208:211], v[44:47]
	v_mfma_f32_16x16x32_bf16 v[40:43], v[156:159], v[208:211], v[40:43]
	v_mfma_f32_16x16x32_bf16 v[28:31], v[148:151], v[216:219], v[28:31]
	v_mfma_f32_16x16x32_bf16 v[24:27], v[156:159], v[216:219], v[24:27]
	v_mfma_f32_16x16x32_bf16 v[12:15], v[148:151], v[224:227], v[12:15]
	v_mfma_f32_16x16x32_bf16 v[8:11], v[156:159], v[224:227], v[8:11]
	v_mfma_f32_16x16x32_bf16 v[60:63], v[152:155], v[204:207], v[60:63]
	v_mfma_f32_16x16x32_bf16 v[56:59], v[180:183], v[204:207], v[56:59]
	v_mfma_f32_16x16x32_bf16 v[44:47], v[152:155], v[212:215], v[44:47]
	v_mfma_f32_16x16x32_bf16 v[40:43], v[180:183], v[212:215], v[40:43]
	v_mfma_f32_16x16x32_bf16 v[28:31], v[152:155], v[220:223], v[28:31]
	v_mfma_f32_16x16x32_bf16 v[24:27], v[180:183], v[220:223], v[24:27]
	v_mfma_f32_16x16x32_bf16 v[12:15], v[152:155], v[228:231], v[12:15]
	v_mfma_f32_16x16x32_bf16 v[8:11], v[180:183], v[228:231], v[8:11]
	v_mfma_f32_16x16x32_bf16 v[52:55], v[184:187], v[200:203], v[52:55]
	v_mfma_f32_16x16x32_bf16 v[48:51], v[192:195], v[200:203], v[48:51]
	v_mfma_f32_16x16x32_bf16 v[36:39], v[184:187], v[208:211], v[36:39]
	v_mfma_f32_16x16x32_bf16 v[32:35], v[192:195], v[208:211], v[32:35]
	v_mfma_f32_16x16x32_bf16 v[20:23], v[184:187], v[216:219], v[20:23]
	v_mfma_f32_16x16x32_bf16 v[16:19], v[192:195], v[216:219], v[16:19]
	v_mfma_f32_16x16x32_bf16 v[4:7], v[184:187], v[224:227], v[4:7]
	v_mfma_f32_16x16x32_bf16 v[0:3], v[192:195], v[224:227], v[0:3]
	v_mfma_f32_16x16x32_bf16 v[52:55], v[188:191], v[204:207], v[52:55]
	v_mfma_f32_16x16x32_bf16 v[48:51], v[196:199], v[204:207], v[48:51]
	v_mfma_f32_16x16x32_bf16 v[36:39], v[188:191], v[212:215], v[36:39]
	v_mfma_f32_16x16x32_bf16 v[32:35], v[196:199], v[212:215], v[32:35]
	v_mfma_f32_16x16x32_bf16 v[20:23], v[188:191], v[220:223], v[20:23]
	v_mfma_f32_16x16x32_bf16 v[16:19], v[196:199], v[220:223], v[16:19]
	v_mfma_f32_16x16x32_bf16 v[4:7], v[188:191], v[228:231], v[4:7]
	v_mfma_f32_16x16x32_bf16 v[0:3], v[196:199], v[228:231], v[0:3]
	s_setprio 1
	s_barrier
	s_add_i32 s79, 0, 0x18000
	v_add_u32_e32 v138, s79, v174
	s_add_i32 s80, 0, 0x1c000
	ds_read_b128 v[148:151], v138
	ds_read_b128 v[152:155], v138 offset:1024
	ds_read_b128 v[156:159], v138 offset:2048
	ds_read_b128 v[180:183], v138 offset:3072
	v_add_u32_e32 v138, s80, v174
	ds_read_b128 v[184:187], v138
	ds_read_b128 v[188:191], v138 offset:1024
	ds_read_b128 v[192:195], v138 offset:2048
	ds_read_b128 v[196:199], v138 offset:3072
	s_add_u32 s70, s70, 0x80000
	s_addc_u32 s71, s71, 0
	s_mov_b32 m0, s29
	ds_read_b128 v[200:203], v178 offset:32768
	ds_read_b128 v[204:207], v178 offset:33792
	ds_read_b128 v[208:211], v178 offset:34816
	ds_read_b128 v[212:215], v178 offset:35840
	ds_read_b128 v[216:219], v178 offset:36864
	ds_read_b128 v[220:223], v178 offset:37888
	ds_read_b128 v[224:227], v178 offset:38912
	ds_read_b128 v[228:231], v178 offset:39936
	global_load_lds_dwordx4 v128, s[70:71]
	s_mov_b32 m0, s30
	s_nop 0
	global_load_lds_dwordx4 v132, s[70:71]
	s_waitcnt vmcnt(8)
	s_waitcnt lgkmcnt(0)
	s_barrier
	s_setprio 0
	s_waitcnt lgkmcnt(0)
	v_mfma_f32_16x16x32_bf16 v[124:127], v[148:151], v[200:203], v[124:127]
	v_mfma_f32_16x16x32_bf16 v[120:123], v[156:159], v[200:203], v[120:123]
	v_mfma_f32_16x16x32_bf16 v[108:111], v[148:151], v[208:211], v[108:111]
	v_mfma_f32_16x16x32_bf16 v[104:107], v[156:159], v[208:211], v[104:107]
	v_mfma_f32_16x16x32_bf16 v[92:95], v[148:151], v[216:219], v[92:95]
	v_mfma_f32_16x16x32_bf16 v[88:91], v[156:159], v[216:219], v[88:91]
	v_mfma_f32_16x16x32_bf16 v[76:79], v[148:151], v[224:227], v[76:79]
	v_mfma_f32_16x16x32_bf16 v[72:75], v[156:159], v[224:227], v[72:75]
	v_mfma_f32_16x16x32_bf16 v[124:127], v[152:155], v[204:207], v[124:127]
	v_mfma_f32_16x16x32_bf16 v[120:123], v[180:183], v[204:207], v[120:123]
	v_mfma_f32_16x16x32_bf16 v[108:111], v[152:155], v[212:215], v[108:111]
	v_mfma_f32_16x16x32_bf16 v[104:107], v[180:183], v[212:215], v[104:107]
	v_mfma_f32_16x16x32_bf16 v[92:95], v[152:155], v[220:223], v[92:95]
	v_mfma_f32_16x16x32_bf16 v[88:91], v[180:183], v[220:223], v[88:91]
	v_mfma_f32_16x16x32_bf16 v[76:79], v[152:155], v[228:231], v[76:79]
	v_mfma_f32_16x16x32_bf16 v[72:75], v[180:183], v[228:231], v[72:75]
	v_mfma_f32_16x16x32_bf16 v[116:119], v[184:187], v[200:203], v[116:119]
	v_mfma_f32_16x16x32_bf16 v[112:115], v[192:195], v[200:203], v[112:115]
	v_mfma_f32_16x16x32_bf16 v[100:103], v[184:187], v[208:211], v[100:103]
	v_mfma_f32_16x16x32_bf16 v[96:99], v[192:195], v[208:211], v[96:99]
	v_mfma_f32_16x16x32_bf16 v[84:87], v[184:187], v[216:219], v[84:87]
	v_mfma_f32_16x16x32_bf16 v[80:83], v[192:195], v[216:219], v[80:83]
	v_mfma_f32_16x16x32_bf16 v[68:71], v[184:187], v[224:227], v[68:71]
	v_mfma_f32_16x16x32_bf16 v[64:67], v[192:195], v[224:227], v[64:67]
	v_mfma_f32_16x16x32_bf16 v[116:119], v[188:191], v[204:207], v[116:119]
	v_mfma_f32_16x16x32_bf16 v[112:115], v[196:199], v[204:207], v[112:115]
	v_mfma_f32_16x16x32_bf16 v[100:103], v[188:191], v[212:215], v[100:103]
	v_mfma_f32_16x16x32_bf16 v[96:99], v[196:199], v[212:215], v[96:99]
	v_mfma_f32_16x16x32_bf16 v[84:87], v[188:191], v[220:223], v[84:87]
	v_mfma_f32_16x16x32_bf16 v[80:83], v[196:199], v[220:223], v[80:83]
	v_mfma_f32_16x16x32_bf16 v[68:71], v[188:191], v[228:231], v[68:71]
	v_mfma_f32_16x16x32_bf16 v[64:67], v[196:199], v[228:231], v[64:67]
	s_setprio 1
	s_barrier
; #define PG8_STAGE(bufoff, gbase, voff) do { _Pragma("unroll") for (int _i = 0; _i < 2; ++_i) \
;         __builtin_amdgcn_global_load_lds((const unsigned*)((const char*)(gbase) + (voff)[_i]), (PG8_LAS unsigned*)(lds + (bufoff) + ldsw + _i * 8192), 16, 0, 0); } while (0)
; #define PG8_LDA(dst, b, h) do { _Pragma("unroll") for (int m = 0; m < 4; ++m) _Pragma("unroll") for (int k = 0; k < 2; ++k) dst[m][k] = *(const PG8_LAS bf16x8*)(lds + PG8_SA(b, h) + aoff + m * 2048 + k * 1024); } while (0)
; #define PG8_MMA(ai, bj, At, Bt) do { __builtin_amdgcn_s_setprio(1); _Pragma("unroll") for (int m = 0; m < 4; ++m) _Pragma("unroll") for (int n = 0; n < 2; ++n) _Pragma("unroll") for (int k = 0; k < 2; ++k) \
;         acc[ai][bj][m][n] = __builtin_amdgcn_mfma_f32_16x16x32_bf16(Bt[n][k], At[m][k], acc[ai][bj][m][n], 0, 0, 0); __builtin_amdgcn_s_setprio(0); } while (0)
; #define PG8_WAIT_V(n) asm volatile("s_waitcnt vmcnt(" #n ")" ::: "memory")
; #define PG8_WAIT_L(n) asm volatile("s_waitcnt lgkmcnt(" #n ")" ::: "memory")
; #define PG8_BAR __builtin_amdgcn_s_barrier()
; #define PG8_SCHED __builtin_amdgcn_sched_barrier(0)
;     __device__ __forceinline__ void operator()(const f32x4 (&acc)[2][2][4][2], const Unit& u, int wr, int wc, int fr, int fq) const {
;     ...
;                     if constexpr (MODE == 5) {
;                         if (u.pn >= 12 && u.pn < 20) {
; template <class Epi, class Sched, bool ALIGN_EPI = false, bool SP2 = false>
; __device__ __forceinline__ void gemm_phase(PG8_LAS unsigned char* lds, const Gemm g, const Sched& S, const Epi& E) {
;     ...
;             PG8_LDA(At, 1, 1); PG8_STAGE(PG8_SB(1, 0), b3, voffB); PG8_STAGE(PG8_SB(1, 1), b3 + hstepB, voffB); PG8_STAGE(PG8_SA(1, 0), a3, voffA);
;             PG8_WAIT_V(8); PG8_WAIT_L(0); PG8_BAR; PG8_MMA(1, 0, At, B0); PG8_MMA(1, 1, At, B1); PG8_BAR; PG8_SCHED;
	s_add_i32 s70, s79, s28
	v_lshl_add_u64 v[160:161], v[160:161], 0, s[46:47]
	s_mov_b32 m0, s70
	ds_read_b128 v[200:203], v178 offset:49152
	ds_read_b128 v[204:207], v178 offset:50176
	ds_read_b128 v[208:211], v178 offset:51200
	ds_read_b128 v[212:215], v178 offset:52224
	ds_read_b128 v[216:219], v178 offset:53248
	ds_read_b128 v[220:223], v178 offset:54272
	ds_read_b128 v[224:227], v178 offset:55296
	ds_read_b128 v[228:231], v178 offset:56320
	global_load_lds_dwordx4 v[160:161], off
	s_add_i32 m0, s70, 0x2000
	s_add_u32 s68, s68, 0x80080
	v_lshl_add_u64 v[160:161], v[232:233], 0, s[46:47]
	s_addc_u32 s69, s69, 0
	s_add_i32 s70, s80, s28
	global_load_lds_dwordx4 v[160:161], off
	s_mov_b32 m0, s70
	s_nop 0
	global_load_lds_dwordx4 v130, s[68:69]
	s_add_i32 m0, s70, 0x2000
	s_nop 0
	global_load_lds_dwordx4 v134, s[68:69]
	v_lshl_add_u64 v[160:161], v[234:235], 0, s[46:47]
	s_mov_b32 m0, s34
	s_nop 0
	global_load_lds_dwordx4 v[160:161], off
	v_lshl_add_u64 v[160:161], v[236:237], 0, s[46:47]
	s_mov_b32 m0, s35
	s_nop 0
	global_load_lds_dwordx4 v[160:161], off
	s_waitcnt vmcnt(8)
	s_waitcnt lgkmcnt(0)
	s_barrier
	s_setprio 0
	s_waitcnt lgkmcnt(0)
	v_mfma_f32_16x16x32_bf16 v[60:63], v[148:151], v[200:203], v[60:63]
	v_mfma_f32_16x16x32_bf16 v[56:59], v[156:159], v[200:203], v[56:59]
	v_mfma_f32_16x16x32_bf16 v[44:47], v[148:151], v[208:211], v[44:47]
	v_mfma_f32_16x16x32_bf16 v[40:43], v[156:159], v[208:211], v[40:43]
	v_mfma_f32_16x16x32_bf16 v[28:31], v[148:151], v[216:219], v[28:31]
	v_mfma_f32_16x16x32_bf16 v[24:27], v[156:159], v[216:219], v[24:27]
	v_mfma_f32_16x16x32_bf16 v[12:15], v[148:151], v[224:227], v[12:15]
	v_mfma_f32_16x16x32_bf16 v[8:11], v[156:159], v[224:227], v[8:11]
	v_mfma_f32_16x16x32_bf16 v[60:63], v[152:155], v[204:207], v[60:63]
	v_mfma_f32_16x16x32_bf16 v[56:59], v[180:183], v[204:207], v[56:59]
	v_mfma_f32_16x16x32_bf16 v[44:47], v[152:155], v[212:215], v[44:47]
	v_mfma_f32_16x16x32_bf16 v[40:43], v[180:183], v[212:215], v[40:43]
	v_mfma_f32_16x16x32_bf16 v[28:31], v[152:155], v[220:223], v[28:31]
	v_mfma_f32_16x16x32_bf16 v[24:27], v[180:183], v[220:223], v[24:27]
	v_mfma_f32_16x16x32_bf16 v[12:15], v[152:155], v[228:231], v[12:15]
	v_mfma_f32_16x16x32_bf16 v[8:11], v[180:183], v[228:231], v[8:11]
	v_mfma_f32_16x16x32_bf16 v[52:55], v[184:187], v[200:203], v[52:55]
	v_mfma_f32_16x16x32_bf16 v[48:51], v[192:195], v[200:203], v[48:51]
	v_mfma_f32_16x16x32_bf16 v[36:39], v[184:187], v[208:211], v[36:39]
	v_mfma_f32_16x16x32_bf16 v[32:35], v[192:195], v[208:211], v[32:35]
	v_mfma_f32_16x16x32_bf16 v[20:23], v[184:187], v[216:219], v[20:23]
	v_mfma_f32_16x16x32_bf16 v[16:19], v[192:195], v[216:219], v[16:19]
	v_mfma_f32_16x16x32_bf16 v[4:7], v[184:187], v[224:227], v[4:7]
	v_mfma_f32_16x16x32_bf16 v[0:3], v[192:195], v[224:227], v[0:3]
	v_mfma_f32_16x16x32_bf16 v[52:55], v[188:191], v[204:207], v[52:55]
	v_mfma_f32_16x16x32_bf16 v[48:51], v[196:199], v[204:207], v[48:51]
	v_mfma_f32_16x16x32_bf16 v[36:39], v[188:191], v[212:215], v[36:39]
	v_mfma_f32_16x16x32_bf16 v[32:35], v[196:199], v[212:215], v[32:35]
	v_mfma_f32_16x16x32_bf16 v[20:23], v[188:191], v[220:223], v[20:23]
	v_mfma_f32_16x16x32_bf16 v[16:19], v[196:199], v[220:223], v[16:19]
	v_mfma_f32_16x16x32_bf16 v[4:7], v[188:191], v[228:231], v[4:7]
	v_mfma_f32_16x16x32_bf16 v[0:3], v[196:199], v[228:231], v[0:3]
	s_setprio 1
	s_barrier
	s_add_i32 s78, s78, 2
	s_add_u32 s6, s6, 0x100
	s_addc_u32 s7, s7, 0
	s_add_u32 s76, s76, 0x100
	s_addc_u32 s77, s77, 0
	s_cmp_gt_u32 s78, 29
	s_cbranch_scc0 .LBB0_311
	s_and_b64 vcc, exec, s[48:49]
	s_cbranch_vccz .LBB0_314
	s_barrier
.LBB0_314:
	s_cmp_lt_u32 s18, 4
	s_cbranch_scc1 .Lp1a_plain
	s_cmp_ge_u32 s18, 20
	s_cbranch_scc1 .Lp1a_plain
	s_cmp_lt_u32 s18, 8
	s_cbranch_scc1 .Lp1a_kcheck
	s_cmp_lt_u32 s18, 12
	s_cbranch_scc1 .Lp1a_plain
	s_branch .Lp1a_slow
; __device__ __forceinline__ unsigned cvt_pk_bf16(float lo, float hi) { unsigned r; asm volatile("v_cvt_pk_bf16_f32 %0, %1, %2" : "=v"(r) : "v"(lo), "v"(hi)); return r; }
;     __device__ __forceinline__ void operator()(const f32x4 (&acc)[2][2][4][2], const Unit& u, int wr, int wc, int fr, int fq) const {
;         const int row0 = u.pm * BM + wr * 64 + fr, col0 = u.pn * BM + wc * 32 + 8 * fq;
; #pragma unroll
;         for (int ai = 0; ai < 2; ++ai)
; #pragma unroll
;             for (int m = 0; m < 4; ++m) {
;                 const int row = row0 + ai * HALF + m * 16;
; #pragma unroll
;                 for (int bj = 0; bj < 2; ++bj) {
;                     const int col = col0 + bj * HALF;
;                     float v[8];
; #pragma unroll
;                     for (int j = 0; j < 4; ++j) { v[j] = acc[ai][bj][m][0][j]; v[4 + j] = acc[ai][bj][m][1][j]; }
;     ...
;                     u32x4 w; w.x = cvt_pk_bf16(v[0], v[1]); w.y = cvt_pk_bf16(v[2], v[3]); w.z = cvt_pk_bf16(v[4], v[5]); w.w = cvt_pk_bf16(v[6], v[7]);
;                     *(u32x4*)op = w;
.Lp1a_kcheck:
	s_cmp_ge_u32 s8, 0x80
	s_cbranch_scc1 .Lp1a_slow
	s_and_b32 s20, s8, 7
	s_cmp_ge_u32 s20, 6
	s_cbranch_scc1 .Lp1a_slow
.Lp1a_plain:
	v_lshl_add_u32 v150, s8, 8, v137
	v_lshl_or_b32 v148, s18, 8, v175
	v_mul_u32_u24_e32 v150, 0x4800, v150
	v_lshl_add_u32 v150, v148, 1, v150
	v_cvt_pk_bf16_f32 v180, v124, v125
	v_cvt_pk_bf16_f32 v181, v126, v127
	v_cvt_pk_bf16_f32 v182, v120, v121
	v_cvt_pk_bf16_f32 v183, v122, v123
	global_store_dwordx4 v150, v[180:183], s[12:13]
	v_cvt_pk_bf16_f32 v184, v116, v117
	v_cvt_pk_bf16_f32 v185, v118, v119
	v_cvt_pk_bf16_f32 v186, v112, v113
	v_cvt_pk_bf16_f32 v187, v114, v115
	global_store_dwordx4 v150, v[184:187], s[12:13] offset:256
	v_add_u32_e32 v196, 0x48000, v150
	v_cvt_pk_bf16_f32 v188, v108, v109
	v_cvt_pk_bf16_f32 v189, v110, v111
	v_cvt_pk_bf16_f32 v190, v104, v105
	v_cvt_pk_bf16_f32 v191, v106, v107
	global_store_dwordx4 v196, v[188:191], s[12:13]
	v_cvt_pk_bf16_f32 v192, v100, v101
	v_cvt_pk_bf16_f32 v193, v102, v103
	v_cvt_pk_bf16_f32 v194, v96, v97
	v_cvt_pk_bf16_f32 v195, v98, v99
	global_store_dwordx4 v196, v[192:195], s[12:13] offset:256
	v_add_u32_e32 v197, 0x90000, v150
	v_cvt_pk_bf16_f32 v180, v92, v93
	v_cvt_pk_bf16_f32 v181, v94, v95
	v_cvt_pk_bf16_f32 v182, v88, v89
	v_cvt_pk_bf16_f32 v183, v90, v91
	global_store_dwordx4 v197, v[180:183], s[12:13]
	v_cvt_pk_bf16_f32 v184, v84, v85
	v_cvt_pk_bf16_f32 v185, v86, v87
	v_cvt_pk_bf16_f32 v186, v80, v81
	v_cvt_pk_bf16_f32 v187, v82, v83
	global_store_dwordx4 v197, v[184:187], s[12:13] offset:256
	v_add_u32_e32 v198, 0xd8000, v150
	v_cvt_pk_bf16_f32 v188, v76, v77
	v_cvt_pk_bf16_f32 v189, v78, v79
	v_cvt_pk_bf16_f32 v190, v72, v73
	v_cvt_pk_bf16_f32 v191, v74, v75
	global_store_dwordx4 v198, v[188:191], s[12:13]
	v_cvt_pk_bf16_f32 v192, v68, v69
	v_cvt_pk_bf16_f32 v193, v70, v71
	v_cvt_pk_bf16_f32 v194, v64, v65
	v_cvt_pk_bf16_f32 v195, v66, v67
	global_store_dwordx4 v198, v[192:195], s[12:13] offset:256
	v_add_u32_e32 v199, 0x240000, v150
	v_cvt_pk_bf16_f32 v180, v60, v61
	v_cvt_pk_bf16_f32 v181, v62, v63
	v_cvt_pk_bf16_f32 v182, v56, v57
	v_cvt_pk_bf16_f32 v183, v58, v59
	global_store_dwordx4 v199, v[180:183], s[12:13]
	v_cvt_pk_bf16_f32 v184, v52, v53
	v_cvt_pk_bf16_f32 v185, v54, v55
	v_cvt_pk_bf16_f32 v186, v48, v49
	v_cvt_pk_bf16_f32 v187, v50, v51
	global_store_dwordx4 v199, v[184:187], s[12:13] offset:256
	v_add_u32_e32 v200, 0x288000, v150
	v_cvt_pk_bf16_f32 v188, v44, v45
	v_cvt_pk_bf16_f32 v189, v46, v47
	v_cvt_pk_bf16_f32 v190, v40, v41
	v_cvt_pk_bf16_f32 v191, v42, v43
	global_store_dwordx4 v200, v[188:191], s[12:13]
	v_cvt_pk_bf16_f32 v192, v36, v37
	v_cvt_pk_bf16_f32 v193, v38, v39
	v_cvt_pk_bf16_f32 v194, v32, v33
	v_cvt_pk_bf16_f32 v195, v34, v35
	global_store_dwordx4 v200, v[192:195], s[12:13] offset:256
	v_add_u32_e32 v201, 0x2d0000, v150
	v_cvt_pk_bf16_f32 v180, v28, v29
	v_cvt_pk_bf16_f32 v181, v30, v31
	v_cvt_pk_bf16_f32 v182, v24, v25
	v_cvt_pk_bf16_f32 v183, v26, v27
	global_store_dwordx4 v201, v[180:183], s[12:13]
	v_cvt_pk_bf16_f32 v184, v20, v21
	v_cvt_pk_bf16_f32 v185, v22, v23
	v_cvt_pk_bf16_f32 v186, v16, v17
	v_cvt_pk_bf16_f32 v187, v18, v19
	global_store_dwordx4 v201, v[184:187], s[12:13] offset:256
	v_add_u32_e32 v202, 0x318000, v150
	v_cvt_pk_bf16_f32 v188, v12, v13
	v_cvt_pk_bf16_f32 v189, v14, v15
	v_cvt_pk_bf16_f32 v190, v8, v9
	v_cvt_pk_bf16_f32 v191, v10, v11
	global_store_dwordx4 v202, v[188:191], s[12:13]
	v_cvt_pk_bf16_f32 v192, v4, v5
	v_cvt_pk_bf16_f32 v193, v6, v7
	v_cvt_pk_bf16_f32 v194, v0, v1
	v_cvt_pk_bf16_f32 v195, v2, v3
	global_store_dwordx4 v202, v[192:195], s[12:13] offset:256
	s_branch .LBB0_450

; #define PG8_STAGE(bufoff, gbase, voff) do { _Pragma("unroll") for (int _i = 0; _i < 2; ++_i) \
;         __builtin_amdgcn_global_load_lds((const unsigned*)((const char*)(gbase) + (voff)[_i]), (PG8_LAS unsigned*)(lds + (bufoff) + ldsw + _i * 8192), 16, 0, 0); } while (0)
; #define PG8_WAIT_V(n) asm volatile("s_waitcnt vmcnt(" #n ")" ::: "memory")
; #define PG8_BAR __builtin_amdgcn_s_barrier()
; template <class Epi, class Sched, bool ALIGN_EPI = false, bool SP2 = false>
; __device__ __forceinline__ void gemm_phase(PG8_LAS unsigned char* lds, const Gemm g, const Sched& S, const Epi& E) {
;     ...
;     const char* cA = (const char*)g.A + (size_t)cur.pm * tstepA + (size_t)cur.kz * kzb; const char* cB = (const char*)g.Bt + (size_t)cur.pn * tstepB + (size_t)cur.kz * kzb;
;     S.a_ready(cur);
;     if constexpr (SP2) {
;         PG8_STAGE(PG8_SB(0, 0), cB, voffB); PG8_STAGE(PG8_SB(0, 1), cB + hstepB, voffB); PG8_STAGE(PG8_SA(0, 0), cA, voffA); PG8_STAGE(PG8_SA(0, 1), cA + hstepA, voffA);
;         if (wr == 1) PG8_BAR;
;         PG8_WAIT_V(2); PG8_BAR;
;         PG8_STAGE(PG8_SB(1, 0), cB + kstep, voffB); PG8_STAGE(PG8_SA(1, 0), cA + kstep, voffA); PG8_STAGE(PG8_SB(1, 1), cB + hstepB + kstep, voffB);
;         PG8_WAIT_V(6); PG8_BAR;
.LBB0_491:
	s_add_u32 s76, s26, 0x12800000
	s_addc_u32 s77, s27, 0
	s_add_u32 s18, s26, 0x14c20000
	s_mov_b64 s[20:21], 0x80
	s_addc_u32 s19, s27, 0
	s_lshl_b32 s5, s5, 5
	s_add_i32 m0, s69, 0x18000
	v_lshl_add_u64 v[6:7], v[6:7], 0, s[20:21]
	s_lshl_b32 s7, s4, 13
	s_and_b32 s5, s5, 0x60
	s_waitcnt vmcnt(2)
	s_barrier
	global_load_lds_dwordx4 v[6:7], off
	v_lshl_add_u64 v[4:5], v[4:5], 0, s[20:21]
	s_add_i32 m0, s69, 0x1a000
	s_add_i32 s78, s69, 0x8000
	s_add_i32 s79, s69, 0xa000
	global_load_lds_dwordx4 v[4:5], off
	v_lshl_add_u64 v[2:3], v[2:3], 0, s[20:21]
	s_mov_b32 m0, s78
	s_add_u32 s28, s60, 0x80080
	global_load_lds_dwordx4 v[2:3], off
	v_lshl_add_u64 v[0:1], v[0:1], 0, s[20:21]
	s_mov_b32 m0, s79
	s_addc_u32 s29, s61, 0
	global_load_lds_dwordx4 v[0:1], off
	s_add_i32 m0, s69, 0x1c000
	v_lshl_add_u64 v[0:1], s[28:29], 0, v[130:131]
	global_load_lds_dwordx4 v[0:1], off
	v_lshl_add_u64 v[0:1], s[28:29], 0, v[134:135]
	s_add_i32 m0, s69, 0x1e000
	v_lshlrev_b32_e32 v2, 12, v169
	global_load_lds_dwordx4 v[0:1], off
	v_lshlrev_b32_e32 v1, 2, v171
	v_lshl_or_b32 v0, v171, 6, v172
	v_and_b32_e32 v1, 32, v1
	v_bitop3_b32 v0, v0, s7, v1 bitop3:0xde
	v_lshlrev_b32_e32 v1, 9, v162
	v_and_b32_e32 v1, 0x70000, v1
	v_or3_b32 v1, v163, v1, v2
	v_add_u32_e32 v138, v1, v168
	v_lshlrev_b32_e32 v1, 5, v170
	s_waitcnt vmcnt(0)
	s_cmpk_lt_u32 s22, 0x100
	v_and_b32_e32 v1, 0xf0000, v1
	v_lshl_or_b32 v153, s5, 7, v173
	s_cselect_b64 s[22:23], -1, 0
	v_or3_b32 v1, v163, v1, v2
	s_add_i32 s81, 0, 0x10000
	s_add_i32 s82, 0, 0x14000
	v_lshl_or_b32 v152, s4, 6, v171
	s_ashr_i32 s80, s35, 31
	v_or_b32_e32 v154, s5, v136
	v_mov_b32_e32 v139, v137
	v_add_u32_e32 v140, v1, v168
	v_mov_b32_e32 v141, v137
	v_mov_b64_e32 v[142:143], 0x210
	v_mov_b64_e32 v[144:145], 0x20f
	v_add_u32_e32 v155, s81, v153
	v_add_u32_e32 v156, s82, v153
	v_add_u32_e32 v157, 0, v0
	s_mov_b32 s83, 0x10800
	s_barrier
	s_branch .LBB0_494

; template <class Epi, class Sched, bool ALIGN_EPI = false, bool SP2 = false>
; __device__ __forceinline__ void gemm_phase(PG8_LAS unsigned char* lds, const Gemm g, const Sched& S, const Epi& E) {
;     ...
;         const bool has_next = S.next(ui + 1, nxt);
;         const char* nA = has_next ? (const char*)g.A + (size_t)nxt.pm * tstepA + (size_t)nxt.kz * kzb : cA; const char* nB = has_next ? (const char*)g.Bt + (size_t)nxt.pn * tstepB + (size_t)nxt.kz * kzb : cB;
;     ...
; #pragma unroll
;         for (int a = 0; a < 2; ++a)
; #pragma unroll
;             for (int b = 0; b < 2; ++b)
; #pragma unroll
;                 for (int m = 0; m < 4; ++m)
; #pragma unroll
;                     for (int n = 0; n < 2; ++n) acc[a][b][m][n] = (f32x4){0.f, 0.f, 0.f, 0.f};
;         cur = nxt; cA = nA; cB = nB; ++ui;
.LBB0_496:
	s_ashr_i32 s43, s42, 31
	s_lshl_b64 s[28:29], s[42:43], 20
	s_add_u32 s46, s64, s28
	s_addc_u32 s47, s65, s29
	s_and_b64 s[28:29], s[4:5], exec
	s_cselect_b32 s7, s47, s55
	s_cselect_b32 s28, s46, s54
	s_ashr_i32 s41, s40, 31
	s_lshl_b64 s[30:31], s[40:41], 20
	v_readlane_b32 s48, v240, 26
	v_readlane_b32 s49, v240, 27
	s_add_u32 s48, s48, s30
	s_addc_u32 s49, s49, s31
	s_and_b64 s[30:31], s[4:5], exec
	s_cselect_b32 s29, s49, s61
	s_cselect_b32 s30, s48, s60
	s_add_u32 s54, s54, 0x80080
	s_addc_u32 s55, s55, 0
	s_add_u32 s31, s60, 0x100
	v_mov_b64_e32 v[0:1], 0
	s_addc_u32 s33, s61, 0
	s_mov_b32 s34, -2
	v_mov_b64_e32 v[2:3], 0
	v_mov_b64_e32 v[4:5], 0
	v_mov_b64_e32 v[6:7], 0
	v_mov_b64_e32 v[16:17], 0
	v_mov_b64_e32 v[18:19], 0
	v_mov_b64_e32 v[20:21], 0
	v_mov_b64_e32 v[22:23], 0
	v_mov_b64_e32 v[32:33], 0
	v_mov_b64_e32 v[34:35], 0
	v_mov_b64_e32 v[36:37], 0
	v_mov_b64_e32 v[38:39], 0
	v_mov_b64_e32 v[48:49], 0
	v_mov_b64_e32 v[50:51], 0
	v_mov_b64_e32 v[52:53], 0
	v_mov_b64_e32 v[54:55], 0
	v_mov_b64_e32 v[8:9], 0
	v_mov_b64_e32 v[10:11], 0
	v_mov_b64_e32 v[12:13], 0
	v_mov_b64_e32 v[14:15], 0
	v_mov_b64_e32 v[24:25], 0
	v_mov_b64_e32 v[26:27], 0
	v_mov_b64_e32 v[28:29], 0
	v_mov_b64_e32 v[30:31], 0
	v_mov_b64_e32 v[40:41], 0
	v_mov_b64_e32 v[42:43], 0
	v_mov_b64_e32 v[44:45], 0
	v_mov_b64_e32 v[46:47], 0
	v_mov_b64_e32 v[56:57], 0
	v_mov_b64_e32 v[58:59], 0
	v_mov_b64_e32 v[60:61], 0
	v_mov_b64_e32 v[62:63], 0
	v_mov_b64_e32 v[64:65], 0
	v_mov_b64_e32 v[66:67], 0
	v_mov_b64_e32 v[68:69], 0
	v_mov_b64_e32 v[70:71], 0
	v_mov_b64_e32 v[80:81], 0
	v_mov_b64_e32 v[82:83], 0
	v_mov_b64_e32 v[84:85], 0
	v_mov_b64_e32 v[86:87], 0
	v_mov_b64_e32 v[96:97], 0
	v_mov_b64_e32 v[98:99], 0
	v_mov_b64_e32 v[100:101], 0
	v_mov_b64_e32 v[102:103], 0
	v_mov_b64_e32 v[112:113], 0
	v_mov_b64_e32 v[114:115], 0
	v_mov_b64_e32 v[116:117], 0
	v_mov_b64_e32 v[118:119], 0
	v_mov_b64_e32 v[72:73], 0
	v_mov_b64_e32 v[74:75], 0
	v_mov_b64_e32 v[76:77], 0
	v_mov_b64_e32 v[78:79], 0
	v_mov_b64_e32 v[88:89], 0
	v_mov_b64_e32 v[90:91], 0
	v_mov_b64_e32 v[92:93], 0
	v_mov_b64_e32 v[94:95], 0
	v_mov_b64_e32 v[104:105], 0
	v_mov_b64_e32 v[106:107], 0
	v_mov_b64_e32 v[108:109], 0
	v_mov_b64_e32 v[110:111], 0
	v_mov_b64_e32 v[120:121], 0
	v_mov_b64_e32 v[122:123], 0
	v_mov_b64_e32 v[124:125], 0
	v_mov_b64_e32 v[126:127], 0
	s_branch .LBB0_497
.Lrx1_A:
	s_waitcnt vmcnt(24)
	s_branch .Lrx1_A_back

; #define PG8_STAGE(bufoff, gbase, voff) do { _Pragma("unroll") for (int _i = 0; _i < 2; ++_i) \
;         __builtin_amdgcn_global_load_lds((const unsigned*)((const char*)(gbase) + (voff)[_i]), (PG8_LAS unsigned*)(lds + (bufoff) + ldsw + _i * 8192), 16, 0, 0); } while (0)
; #define PG8_LDA(dst, b, h) do { _Pragma("unroll") for (int m = 0; m < 4; ++m) _Pragma("unroll") for (int k = 0; k < 2; ++k) dst[m][k] = *(const PG8_LAS bf16x8*)(lds + PG8_SA(b, h) + aoff + m * 2048 + k * 1024); } while (0)
; #define PG8_LDB(dst, b, h) do { _Pragma("unroll") for (int n = 0; n < 2; ++n) _Pragma("unroll") for (int k = 0; k < 2; ++k) dst[n][k] = *(const PG8_LAS bf16x8*)(lds + PG8_SB(b, h) + boff + n * 2048 + k * 1024); } while (0)
; #define PG8_MMA(ai, bj, At, Bt) do { __builtin_amdgcn_s_setprio(1); _Pragma("unroll") for (int m = 0; m < 4; ++m) _Pragma("unroll") for (int n = 0; n < 2; ++n) _Pragma("unroll") for (int k = 0; k < 2; ++k) \
;         acc[ai][bj][m][n] = __builtin_amdgcn_mfma_f32_16x16x32_bf16(Bt[n][k], At[m][k], acc[ai][bj][m][n], 0, 0, 0); __builtin_amdgcn_s_setprio(0); } while (0)
; #define PG8_WAIT_V(n) asm volatile("s_waitcnt vmcnt(" #n ")" ::: "memory")
; #define PG8_WAIT_L(n) asm volatile("s_waitcnt lgkmcnt(" #n ")" ::: "memory")
; #define PG8_BAR __builtin_amdgcn_s_barrier()
; #define PG8_SCHED __builtin_amdgcn_sched_barrier(0)
; template <class Epi, class Sched, bool ALIGN_EPI = false, bool SP2 = false>
; __device__ __forceinline__ void gemm_phase(PG8_LAS unsigned char* lds, const Gemm g, const Sched& S, const Epi& E) {
;     ...
;             PG8_LDB(B0, 0, 0); PG8_LDB(B1, 0, 1); PG8_SCHED; PG8_LDA(At, 0, 0); PG8_STAGE(PG8_SA(1, 1), a1 + hstepA, voffA);
;             PG8_WAIT_V(8); PG8_WAIT_L(0); PG8_BAR; PG8_MMA(0, 0, At, B0); PG8_MMA(0, 1, At, B1); PG8_BAR; PG8_SCHED;
;             PG8_LDA(At, 0, 1); PG8_STAGE(PG8_SB(0, 0), b2, voffB); PG8_STAGE(PG8_SB(0, 1), b2 + hstepB, voffB); PG8_STAGE(PG8_SA(0, 0), a2, voffA);
.LBB0_497:
	ds_read_b128 v[146:149], v155
	ds_read_b128 v[158:161], v155 offset:1024
	ds_read_b128 v[168:171], v155 offset:2048
	ds_read_b128 v[172:175], v155 offset:3072
	ds_read_b128 v[176:179], v156
	ds_read_b128 v[180:183], v156 offset:1024
	ds_read_b128 v[184:187], v156 offset:2048
	ds_read_b128 v[188:191], v156 offset:3072
	s_add_u32 s41, s54, 0xfff80080
	s_addc_u32 s43, s55, -1
	s_cmp_eq_u32 s34, 28
	s_cselect_b32 s63, s7, s43
	s_cselect_b32 s62, s28, s41
	s_cselect_b32 s61, s29, s33
	s_cselect_b32 s60, s30, s31
	s_add_i32 m0, s69, 0xc000
	ds_read_b128 v[192:195], v157
	ds_read_b128 v[196:199], v157 offset:1024
	ds_read_b128 v[200:203], v157 offset:2048
	ds_read_b128 v[204:207], v157 offset:3072
	ds_read_b128 v[208:211], v157 offset:4096
	ds_read_b128 v[212:215], v157 offset:5120
	ds_read_b128 v[216:219], v157 offset:6144
	ds_read_b128 v[220:223], v157 offset:7168
	global_load_lds_dwordx4 v138, s[54:55]
	s_add_i32 m0, s69, 0xe000
	s_nop 0
	global_load_lds_dwordx4 v140, s[54:55]
	s_cmp_eq_u32 s34, -2
	s_cbranch_scc1 .Lrx1_A
	s_waitcnt vmcnt(8)
.Lrx1_A_back:
	s_waitcnt lgkmcnt(0)
	s_barrier
	s_setprio 0
	s_waitcnt lgkmcnt(0)
	v_mfma_f32_16x16x32_bf16 v[124:127], v[146:149], v[192:195], v[124:127]
	v_mfma_f32_16x16x32_bf16 v[120:123], v[168:171], v[192:195], v[120:123]
	v_mfma_f32_16x16x32_bf16 v[108:111], v[146:149], v[200:203], v[108:111]
	v_mfma_f32_16x16x32_bf16 v[104:107], v[168:171], v[200:203], v[104:107]
	v_mfma_f32_16x16x32_bf16 v[92:95], v[146:149], v[208:211], v[92:95]
	v_mfma_f32_16x16x32_bf16 v[88:91], v[168:171], v[208:211], v[88:91]
	v_mfma_f32_16x16x32_bf16 v[76:79], v[146:149], v[216:219], v[76:79]
	v_mfma_f32_16x16x32_bf16 v[72:75], v[168:171], v[216:219], v[72:75]
	v_mfma_f32_16x16x32_bf16 v[124:127], v[158:161], v[196:199], v[124:127]
	v_mfma_f32_16x16x32_bf16 v[120:123], v[172:175], v[196:199], v[120:123]
	v_mfma_f32_16x16x32_bf16 v[108:111], v[158:161], v[204:207], v[108:111]
	v_mfma_f32_16x16x32_bf16 v[104:107], v[172:175], v[204:207], v[104:107]
	v_mfma_f32_16x16x32_bf16 v[92:95], v[158:161], v[212:215], v[92:95]
	v_mfma_f32_16x16x32_bf16 v[88:91], v[172:175], v[212:215], v[88:91]
	v_mfma_f32_16x16x32_bf16 v[76:79], v[158:161], v[220:223], v[76:79]
	v_mfma_f32_16x16x32_bf16 v[72:75], v[172:175], v[220:223], v[72:75]
	v_mfma_f32_16x16x32_bf16 v[116:119], v[176:179], v[192:195], v[116:119]
	v_mfma_f32_16x16x32_bf16 v[112:115], v[184:187], v[192:195], v[112:115]
	v_mfma_f32_16x16x32_bf16 v[100:103], v[176:179], v[200:203], v[100:103]
	v_mfma_f32_16x16x32_bf16 v[96:99], v[184:187], v[200:203], v[96:99]
	v_mfma_f32_16x16x32_bf16 v[84:87], v[176:179], v[208:211], v[84:87]
	v_mfma_f32_16x16x32_bf16 v[80:83], v[184:187], v[208:211], v[80:83]
	v_mfma_f32_16x16x32_bf16 v[68:71], v[176:179], v[216:219], v[68:71]
	v_mfma_f32_16x16x32_bf16 v[64:67], v[184:187], v[216:219], v[64:67]
	v_mfma_f32_16x16x32_bf16 v[116:119], v[180:183], v[196:199], v[116:119]
	v_mfma_f32_16x16x32_bf16 v[112:115], v[188:191], v[196:199], v[112:115]
	v_mfma_f32_16x16x32_bf16 v[100:103], v[180:183], v[204:207], v[100:103]
	v_mfma_f32_16x16x32_bf16 v[96:99], v[188:191], v[204:207], v[96:99]
	v_mfma_f32_16x16x32_bf16 v[84:87], v[180:183], v[212:215], v[84:87]
	v_mfma_f32_16x16x32_bf16 v[80:83], v[188:191], v[212:215], v[80:83]
	v_mfma_f32_16x16x32_bf16 v[68:71], v[180:183], v[220:223], v[68:71]
	v_mfma_f32_16x16x32_bf16 v[64:67], v[188:191], v[220:223], v[64:67]
	s_setprio 1
	s_barrier
	s_add_i32 s41, s81, s68
	v_lshl_add_u64 v[150:151], s[60:61], 0, v[130:131]
	s_mov_b32 m0, s41
	ds_read_b128 v[192:195], v157 offset:16384
	ds_read_b128 v[196:199], v157 offset:17408
	ds_read_b128 v[200:203], v157 offset:18432
	ds_read_b128 v[204:207], v157 offset:19456
	ds_read_b128 v[208:211], v157 offset:20480
	ds_read_b128 v[212:215], v157 offset:21504
	ds_read_b128 v[216:219], v157 offset:22528
	ds_read_b128 v[220:223], v157 offset:23552
	global_load_lds_dwordx4 v130, s[60:61]
	s_add_i32 m0, s41, 0x2000
	s_add_u32 s84, s60, 0x80000
	v_lshl_add_u64 v[224:225], s[60:61], 0, v[134:135]
	s_addc_u32 s85, s61, 0
	s_add_i32 s41, s82, s68
	global_load_lds_dwordx4 v134, s[60:61]
	s_mov_b32 m0, s41
	v_lshl_add_u64 v[228:229], s[62:63], 0, v[132:133]
	global_load_lds_dwordx4 v130, s[84:85]
	s_add_i32 m0, s41, 0x2000
	s_nop 0
	global_load_lds_dwordx4 v134, s[84:85]
	v_lshl_add_u64 v[226:227], s[62:63], 0, v[128:129]
	s_mov_b32 m0, s69
	s_nop 0
	global_load_lds_dwordx4 v128, s[62:63]
	s_mov_b32 m0, s70
	s_nop 0
	global_load_lds_dwordx4 v132, s[62:63]
	s_cmp_eq_u32 s34, -2
	s_cbranch_scc1 .Lrx1_B
	s_waitcnt vmcnt(8)
; #define PG8_STAGE(bufoff, gbase, voff) do { _Pragma("unroll") for (int _i = 0; _i < 2; ++_i) \
;         __builtin_amdgcn_global_load_lds((const unsigned*)((const char*)(gbase) + (voff)[_i]), (PG8_LAS unsigned*)(lds + (bufoff) + ldsw + _i * 8192), 16, 0, 0); } while (0)
; #define PG8_LDA(dst, b, h) do { _Pragma("unroll") for (int m = 0; m < 4; ++m) _Pragma("unroll") for (int k = 0; k < 2; ++k) dst[m][k] = *(const PG8_LAS bf16x8*)(lds + PG8_SA(b, h) + aoff + m * 2048 + k * 1024); } while (0)
; #define PG8_LDB(dst, b, h) do { _Pragma("unroll") for (int n = 0; n < 2; ++n) _Pragma("unroll") for (int k = 0; k < 2; ++k) dst[n][k] = *(const PG8_LAS bf16x8*)(lds + PG8_SB(b, h) + boff + n * 2048 + k * 1024); } while (0)
; #define PG8_MMA(ai, bj, At, Bt) do { __builtin_amdgcn_s_setprio(1); _Pragma("unroll") for (int m = 0; m < 4; ++m) _Pragma("unroll") for (int n = 0; n < 2; ++n) _Pragma("unroll") for (int k = 0; k < 2; ++k) \
;         acc[ai][bj][m][n] = __builtin_amdgcn_mfma_f32_16x16x32_bf16(Bt[n][k], At[m][k], acc[ai][bj][m][n], 0, 0, 0); __builtin_amdgcn_s_setprio(0); } while (0)
; #define PG8_WAIT_V(n) asm volatile("s_waitcnt vmcnt(" #n ")" ::: "memory")
; #define PG8_WAIT_L(n) asm volatile("s_waitcnt lgkmcnt(" #n ")" ::: "memory")
; #define PG8_BAR __builtin_amdgcn_s_barrier()
; #define PG8_SCHED __builtin_amdgcn_sched_barrier(0)
; template <class Epi, class Sched, bool ALIGN_EPI = false, bool SP2 = false>
; __device__ __forceinline__ void gemm_phase(PG8_LAS unsigned char* lds, const Gemm g, const Sched& S, const Epi& E) {
;     ...
;             PG8_WAIT_V(8); PG8_WAIT_L(0); PG8_BAR; PG8_MMA(1, 0, At, B0); PG8_MMA(1, 1, At, B1); PG8_BAR; PG8_SCHED;
;             PG8_LDB(B0, 1, 0); PG8_LDB(B1, 1, 1); PG8_SCHED; PG8_LDA(At, 1, 0); PG8_STAGE(PG8_SA(0, 1), a2 + hstepA, voffA);
;             PG8_WAIT_V(8); PG8_WAIT_L(0); PG8_BAR; PG8_MMA(0, 0, At, B0); PG8_MMA(0, 1, At, B1); PG8_BAR; PG8_SCHED;
.Lrx1_B_back:
	s_waitcnt lgkmcnt(0)
	s_barrier
	s_setprio 0
	s_waitcnt lgkmcnt(0)
	v_mfma_f32_16x16x32_bf16 v[60:63], v[146:149], v[192:195], v[60:63]
	v_mfma_f32_16x16x32_bf16 v[56:59], v[168:171], v[192:195], v[56:59]
	v_mfma_f32_16x16x32_bf16 v[44:47], v[146:149], v[200:203], v[44:47]
	v_mfma_f32_16x16x32_bf16 v[40:43], v[168:171], v[200:203], v[40:43]
	v_mfma_f32_16x16x32_bf16 v[28:31], v[146:149], v[208:211], v[28:31]
	v_mfma_f32_16x16x32_bf16 v[24:27], v[168:171], v[208:211], v[24:27]
	v_mfma_f32_16x16x32_bf16 v[12:15], v[146:149], v[216:219], v[12:15]
	v_mfma_f32_16x16x32_bf16 v[8:11], v[168:171], v[216:219], v[8:11]
	v_mfma_f32_16x16x32_bf16 v[60:63], v[158:161], v[196:199], v[60:63]
	v_mfma_f32_16x16x32_bf16 v[56:59], v[172:175], v[196:199], v[56:59]
	v_mfma_f32_16x16x32_bf16 v[44:47], v[158:161], v[204:207], v[44:47]
	v_mfma_f32_16x16x32_bf16 v[40:43], v[172:175], v[204:207], v[40:43]
	v_mfma_f32_16x16x32_bf16 v[28:31], v[158:161], v[212:215], v[28:31]
	v_mfma_f32_16x16x32_bf16 v[24:27], v[172:175], v[212:215], v[24:27]
	v_mfma_f32_16x16x32_bf16 v[12:15], v[158:161], v[220:223], v[12:15]
	v_mfma_f32_16x16x32_bf16 v[8:11], v[172:175], v[220:223], v[8:11]
	v_mfma_f32_16x16x32_bf16 v[52:55], v[176:179], v[192:195], v[52:55]
	v_mfma_f32_16x16x32_bf16 v[48:51], v[184:187], v[192:195], v[48:51]
	v_mfma_f32_16x16x32_bf16 v[36:39], v[176:179], v[200:203], v[36:39]
	v_mfma_f32_16x16x32_bf16 v[32:35], v[184:187], v[200:203], v[32:35]
	v_mfma_f32_16x16x32_bf16 v[20:23], v[176:179], v[208:211], v[20:23]
	v_mfma_f32_16x16x32_bf16 v[16:19], v[184:187], v[208:211], v[16:19]
	v_mfma_f32_16x16x32_bf16 v[4:7], v[176:179], v[216:219], v[4:7]
	v_mfma_f32_16x16x32_bf16 v[0:3], v[184:187], v[216:219], v[0:3]
	v_mfma_f32_16x16x32_bf16 v[52:55], v[180:183], v[196:199], v[52:55]
	v_mfma_f32_16x16x32_bf16 v[48:51], v[188:191], v[196:199], v[48:51]
	v_mfma_f32_16x16x32_bf16 v[36:39], v[180:183], v[204:207], v[36:39]
	v_mfma_f32_16x16x32_bf16 v[32:35], v[188:191], v[204:207], v[32:35]
	v_mfma_f32_16x16x32_bf16 v[20:23], v[180:183], v[212:215], v[20:23]
	v_mfma_f32_16x16x32_bf16 v[16:19], v[188:191], v[212:215], v[16:19]
	v_mfma_f32_16x16x32_bf16 v[4:7], v[180:183], v[220:223], v[4:7]
	v_mfma_f32_16x16x32_bf16 v[0:3], v[188:191], v[220:223], v[0:3]
	s_setprio 1
	s_barrier
	s_add_i32 s41, 0, 0x18000
	v_add_u32_e32 v136, s41, v153
	s_add_i32 s43, 0, 0x1c000
	ds_read_b128 v[146:149], v136
	ds_read_b128 v[158:161], v136 offset:1024
	ds_read_b128 v[168:171], v136 offset:2048
	ds_read_b128 v[172:175], v136 offset:3072
	v_add_u32_e32 v136, s43, v153
	ds_read_b128 v[176:179], v136
	ds_read_b128 v[180:183], v136 offset:1024
	ds_read_b128 v[184:187], v136 offset:2048
	ds_read_b128 v[188:191], v136 offset:3072
	s_add_u32 s62, s62, 0x80000
	s_addc_u32 s63, s63, 0
	s_mov_b32 m0, s71
	ds_read_b128 v[192:195], v157 offset:32768
	ds_read_b128 v[196:199], v157 offset:33792
	ds_read_b128 v[200:203], v157 offset:34816
	ds_read_b128 v[204:207], v157 offset:35840
	ds_read_b128 v[208:211], v157 offset:36864
	ds_read_b128 v[212:215], v157 offset:37888
	ds_read_b128 v[216:219], v157 offset:38912
	ds_read_b128 v[220:223], v157 offset:39936
	global_load_lds_dwordx4 v128, s[62:63]
	s_mov_b32 m0, s72
	s_nop 0
	global_load_lds_dwordx4 v132, s[62:63]
	s_waitcnt vmcnt(8)
	s_waitcnt lgkmcnt(0)
	s_barrier
	s_setprio 0
	s_waitcnt lgkmcnt(0)
	v_mfma_f32_16x16x32_bf16 v[124:127], v[146:149], v[192:195], v[124:127]
	v_mfma_f32_16x16x32_bf16 v[120:123], v[168:171], v[192:195], v[120:123]
	v_mfma_f32_16x16x32_bf16 v[108:111], v[146:149], v[200:203], v[108:111]
	v_mfma_f32_16x16x32_bf16 v[104:107], v[168:171], v[200:203], v[104:107]
	v_mfma_f32_16x16x32_bf16 v[92:95], v[146:149], v[208:211], v[92:95]
	v_mfma_f32_16x16x32_bf16 v[88:91], v[168:171], v[208:211], v[88:91]
	v_mfma_f32_16x16x32_bf16 v[76:79], v[146:149], v[216:219], v[76:79]
	v_mfma_f32_16x16x32_bf16 v[72:75], v[168:171], v[216:219], v[72:75]
	v_mfma_f32_16x16x32_bf16 v[124:127], v[158:161], v[196:199], v[124:127]
	v_mfma_f32_16x16x32_bf16 v[120:123], v[172:175], v[196:199], v[120:123]
	v_mfma_f32_16x16x32_bf16 v[108:111], v[158:161], v[204:207], v[108:111]
	v_mfma_f32_16x16x32_bf16 v[104:107], v[172:175], v[204:207], v[104:107]
	v_mfma_f32_16x16x32_bf16 v[92:95], v[158:161], v[212:215], v[92:95]
	v_mfma_f32_16x16x32_bf16 v[88:91], v[172:175], v[212:215], v[88:91]
	v_mfma_f32_16x16x32_bf16 v[76:79], v[158:161], v[220:223], v[76:79]
	v_mfma_f32_16x16x32_bf16 v[72:75], v[172:175], v[220:223], v[72:75]
	v_mfma_f32_16x16x32_bf16 v[116:119], v[176:179], v[192:195], v[116:119]
	v_mfma_f32_16x16x32_bf16 v[112:115], v[184:187], v[192:195], v[112:115]
	v_mfma_f32_16x16x32_bf16 v[100:103], v[176:179], v[200:203], v[100:103]
	v_mfma_f32_16x16x32_bf16 v[96:99], v[184:187], v[200:203], v[96:99]
	v_mfma_f32_16x16x32_bf16 v[84:87], v[176:179], v[208:211], v[84:87]
	v_mfma_f32_16x16x32_bf16 v[80:83], v[184:187], v[208:211], v[80:83]
	v_mfma_f32_16x16x32_bf16 v[68:71], v[176:179], v[216:219], v[68:71]
	v_mfma_f32_16x16x32_bf16 v[64:67], v[184:187], v[216:219], v[64:67]
	v_mfma_f32_16x16x32_bf16 v[116:119], v[180:183], v[196:199], v[116:119]
	v_mfma_f32_16x16x32_bf16 v[112:115], v[188:191], v[196:199], v[112:115]
	v_mfma_f32_16x16x32_bf16 v[100:103], v[180:183], v[204:207], v[100:103]
	v_mfma_f32_16x16x32_bf16 v[96:99], v[188:191], v[204:207], v[96:99]
	v_mfma_f32_16x16x32_bf16 v[84:87], v[180:183], v[212:215], v[84:87]
	v_mfma_f32_16x16x32_bf16 v[80:83], v[188:191], v[212:215], v[80:83]
	v_mfma_f32_16x16x32_bf16 v[68:71], v[180:183], v[220:223], v[68:71]
	v_mfma_f32_16x16x32_bf16 v[64:67], v[188:191], v[220:223], v[64:67]
	s_setprio 1
	s_barrier
; #define PG8_STAGE(bufoff, gbase, voff) do { _Pragma("unroll") for (int _i = 0; _i < 2; ++_i) \
;         __builtin_amdgcn_global_load_lds((const unsigned*)((const char*)(gbase) + (voff)[_i]), (PG8_LAS unsigned*)(lds + (bufoff) + ldsw + _i * 8192), 16, 0, 0); } while (0)
; #define PG8_LDA(dst, b, h) do { _Pragma("unroll") for (int m = 0; m < 4; ++m) _Pragma("unroll") for (int k = 0; k < 2; ++k) dst[m][k] = *(const PG8_LAS bf16x8*)(lds + PG8_SA(b, h) + aoff + m * 2048 + k * 1024); } while (0)
; #define PG8_MMA(ai, bj, At, Bt) do { __builtin_amdgcn_s_setprio(1); _Pragma("unroll") for (int m = 0; m < 4; ++m) _Pragma("unroll") for (int n = 0; n < 2; ++n) _Pragma("unroll") for (int k = 0; k < 2; ++k) \
;         acc[ai][bj][m][n] = __builtin_amdgcn_mfma_f32_16x16x32_bf16(Bt[n][k], At[m][k], acc[ai][bj][m][n], 0, 0, 0); __builtin_amdgcn_s_setprio(0); } while (0)
; #define PG8_WAIT_V(n) asm volatile("s_waitcnt vmcnt(" #n ")" ::: "memory")
; #define PG8_WAIT_L(n) asm volatile("s_waitcnt lgkmcnt(" #n ")" ::: "memory")
; #define PG8_BAR __builtin_amdgcn_s_barrier()
; #define PG8_SCHED __builtin_amdgcn_sched_barrier(0)
; template <class Epi, class Sched, bool ALIGN_EPI = false, bool SP2 = false>
; __device__ __forceinline__ void gemm_phase(PG8_LAS unsigned char* lds, const Gemm g, const Sched& S, const Epi& E) {
;     ...
;             PG8_LDA(At, 1, 1); PG8_STAGE(PG8_SB(1, 0), b3, voffB); PG8_STAGE(PG8_SB(1, 1), b3 + hstepB, voffB); PG8_STAGE(PG8_SA(1, 0), a3, voffA);
;             PG8_WAIT_V(8); PG8_WAIT_L(0); PG8_BAR; PG8_MMA(1, 0, At, B0); PG8_MMA(1, 1, At, B1); PG8_BAR; PG8_SCHED;
	s_add_i32 s41, s41, s68
	v_lshl_add_u64 v[150:151], v[150:151], 0, s[20:21]
	s_mov_b32 m0, s41
	ds_read_b128 v[192:195], v157 offset:49152
	ds_read_b128 v[196:199], v157 offset:50176
	ds_read_b128 v[200:203], v157 offset:51200
	ds_read_b128 v[204:207], v157 offset:52224
	ds_read_b128 v[208:211], v157 offset:53248
	ds_read_b128 v[212:215], v157 offset:54272
	ds_read_b128 v[216:219], v157 offset:55296
	ds_read_b128 v[220:223], v157 offset:56320
	global_load_lds_dwordx4 v[150:151], off
	s_add_i32 m0, s41, 0x2000
	s_add_u32 s60, s60, 0x80080
	v_lshl_add_u64 v[150:151], v[224:225], 0, s[20:21]
	s_addc_u32 s61, s61, 0
	s_add_i32 s41, s43, s68
	global_load_lds_dwordx4 v[150:151], off
	s_mov_b32 m0, s41
	s_nop 0
	global_load_lds_dwordx4 v130, s[60:61]
	s_add_i32 m0, s41, 0x2000
	s_nop 0
	global_load_lds_dwordx4 v134, s[60:61]
	v_lshl_add_u64 v[150:151], v[226:227], 0, s[20:21]
	s_mov_b32 m0, s78
	s_nop 0
	global_load_lds_dwordx4 v[150:151], off
	v_lshl_add_u64 v[150:151], v[228:229], 0, s[20:21]
	s_mov_b32 m0, s79
	s_nop 0
	global_load_lds_dwordx4 v[150:151], off
	s_waitcnt vmcnt(8)
	s_waitcnt lgkmcnt(0)
	s_barrier
	s_setprio 0
	s_waitcnt lgkmcnt(0)
	v_mfma_f32_16x16x32_bf16 v[60:63], v[146:149], v[192:195], v[60:63]
	v_mfma_f32_16x16x32_bf16 v[56:59], v[168:171], v[192:195], v[56:59]
	v_mfma_f32_16x16x32_bf16 v[44:47], v[146:149], v[200:203], v[44:47]
	v_mfma_f32_16x16x32_bf16 v[40:43], v[168:171], v[200:203], v[40:43]
	v_mfma_f32_16x16x32_bf16 v[28:31], v[146:149], v[208:211], v[28:31]
	v_mfma_f32_16x16x32_bf16 v[24:27], v[168:171], v[208:211], v[24:27]
	v_mfma_f32_16x16x32_bf16 v[12:15], v[146:149], v[216:219], v[12:15]
	v_mfma_f32_16x16x32_bf16 v[8:11], v[168:171], v[216:219], v[8:11]
	v_mfma_f32_16x16x32_bf16 v[60:63], v[158:161], v[196:199], v[60:63]
	v_mfma_f32_16x16x32_bf16 v[56:59], v[172:175], v[196:199], v[56:59]
	v_mfma_f32_16x16x32_bf16 v[44:47], v[158:161], v[204:207], v[44:47]
	v_mfma_f32_16x16x32_bf16 v[40:43], v[172:175], v[204:207], v[40:43]
	v_mfma_f32_16x16x32_bf16 v[28:31], v[158:161], v[212:215], v[28:31]
	v_mfma_f32_16x16x32_bf16 v[24:27], v[172:175], v[212:215], v[24:27]
	v_mfma_f32_16x16x32_bf16 v[12:15], v[158:161], v[220:223], v[12:15]
	v_mfma_f32_16x16x32_bf16 v[8:11], v[172:175], v[220:223], v[8:11]
	v_mfma_f32_16x16x32_bf16 v[52:55], v[176:179], v[192:195], v[52:55]
	v_mfma_f32_16x16x32_bf16 v[48:51], v[184:187], v[192:195], v[48:51]
	v_mfma_f32_16x16x32_bf16 v[36:39], v[176:179], v[200:203], v[36:39]
	v_mfma_f32_16x16x32_bf16 v[32:35], v[184:187], v[200:203], v[32:35]
	v_mfma_f32_16x16x32_bf16 v[20:23], v[176:179], v[208:211], v[20:23]
	v_mfma_f32_16x16x32_bf16 v[16:19], v[184:187], v[208:211], v[16:19]
	v_mfma_f32_16x16x32_bf16 v[4:7], v[176:179], v[216:219], v[4:7]
	v_mfma_f32_16x16x32_bf16 v[0:3], v[184:187], v[216:219], v[0:3]
	v_mfma_f32_16x16x32_bf16 v[52:55], v[180:183], v[196:199], v[52:55]
	v_mfma_f32_16x16x32_bf16 v[48:51], v[188:191], v[196:199], v[48:51]
	v_mfma_f32_16x16x32_bf16 v[36:39], v[180:183], v[204:207], v[36:39]
	v_mfma_f32_16x16x32_bf16 v[32:35], v[188:191], v[204:207], v[32:35]
	v_mfma_f32_16x16x32_bf16 v[20:23], v[180:183], v[212:215], v[20:23]
	v_mfma_f32_16x16x32_bf16 v[16:19], v[188:191], v[212:215], v[16:19]
	v_mfma_f32_16x16x32_bf16 v[4:7], v[180:183], v[220:223], v[4:7]
	v_mfma_f32_16x16x32_bf16 v[0:3], v[188:191], v[220:223], v[0:3]
	s_setprio 1
	s_barrier
	s_add_i32 s34, s34, 2
	s_add_u32 s54, s54, 0x100
	s_addc_u32 s55, s55, 0
	s_add_u32 s31, s31, 0x100
	s_addc_u32 s33, s33, 0
	s_cmp_gt_u32 s34, 29
	s_cbranch_scc0 .LBB0_497
	s_and_b64 vcc, exec, s[22:23]
	s_cbranch_vccz .LBB0_500
	s_barrier

; #define PG8_STAGE(bufoff, gbase, voff) do { _Pragma("unroll") for (int _i = 0; _i < 2; ++_i) \
;         __builtin_amdgcn_global_load_lds((const unsigned*)((const char*)(gbase) + (voff)[_i]), (PG8_LAS unsigned*)(lds + (bufoff) + ldsw + _i * 8192), 16, 0, 0); } while (0)
; #define PG8_WAIT_V(n) asm volatile("s_waitcnt vmcnt(" #n ")" ::: "memory")
; #define PG8_BAR __builtin_amdgcn_s_barrier()
; template <class Epi, class Sched, bool ALIGN_EPI = false, bool SP2 = false>
; __device__ __forceinline__ void gemm_phase(PG8_LAS unsigned char* lds, const Gemm g, const Sched& S, const Epi& E) {
;     ...
;     const char* cA = (const char*)g.A + (size_t)cur.pm * tstepA + (size_t)cur.kz * kzb; const char* cB = (const char*)g.Bt + (size_t)cur.pn * tstepB + (size_t)cur.kz * kzb;
;     S.a_ready(cur);
;     if constexpr (SP2) {
;         PG8_STAGE(PG8_SB(0, 0), cB, voffB); PG8_STAGE(PG8_SB(0, 1), cB + hstepB, voffB); PG8_STAGE(PG8_SA(0, 0), cA, voffA); PG8_STAGE(PG8_SA(0, 1), cA + hstepA, voffA);
;         if (wr == 1) PG8_BAR;
;         PG8_WAIT_V(2); PG8_BAR;
;         PG8_STAGE(PG8_SB(1, 0), cB + kstep, voffB); PG8_STAGE(PG8_SA(1, 0), cA + kstep, voffA); PG8_STAGE(PG8_SB(1, 1), cB + hstepB + kstep, voffB);
;         PG8_WAIT_V(6); PG8_BAR;
.LBB0_821:
	v_readlane_b32 s8, v240, 3
	v_readlane_b32 s9, v240, 4
	v_readlane_b32 s10, v240, 5
	v_readlane_b32 s11, v240, 6
	s_add_u32 s8, s8, 0x15803800
	s_addc_u32 s9, s9, 0
	s_lshl_b32 s5, s5, 5
	s_mov_b64 s[10:11], 0x80
	s_and_b32 s5, s5, 0x60
	s_add_i32 m0, s33, 0x18000
	v_lshl_add_u64 v[6:7], v[6:7], 0, s[10:11]
	s_lshl_b32 s18, s4, 13
	s_lshl_b32 s19, s5, 7
	s_waitcnt vmcnt(2)
	s_barrier
	global_load_lds_dwordx4 v[6:7], off
	v_lshl_add_u64 v[4:5], v[4:5], 0, s[10:11]
	s_add_i32 m0, s33, 0x1a000
	s_add_i32 s47, s33, 0x8000
	s_add_i32 s48, s33, 0xa000
	global_load_lds_dwordx4 v[4:5], off
	v_lshl_add_u64 v[0:1], v[0:1], 0, s[10:11]
	s_mov_b32 m0, s47
	s_add_u32 s16, s40, 0x40080
	global_load_lds_dwordx4 v[0:1], off
	v_lshl_add_u64 v[0:1], v[2:3], 0, s[10:11]
	s_mov_b32 m0, s48
	s_addc_u32 s17, s41, 0
	global_load_lds_dwordx4 v[0:1], off
	s_add_i32 m0, s33, 0x1c000
	v_lshl_add_u64 v[0:1], s[16:17], 0, v[132:133]
	global_load_lds_dwordx4 v[0:1], off
	v_lshl_add_u64 v[0:1], s[16:17], 0, v[128:129]
	s_add_i32 m0, s33, 0x1e000
	s_sext_i32_i8 s54, s0
	global_load_lds_dwordx4 v[0:1], off
	v_and_b32_e32 v0, 15, v162
	v_lshlrev_b32_e32 v1, 1, v8
	v_lshlrev_b32_e32 v2, 2, v162
	v_lshlrev_b32_e32 v3, 6, v162
	s_movk_i32 s0, 0x3c0
	v_lshl_or_b32 v150, s4, 6, v0
	v_lshl_or_b32 v0, v0, 6, v1
	v_and_b32_e32 v2, 32, v2
	v_and_or_b32 v1, v3, s0, v1
	s_waitcnt vmcnt(0)
	s_cmpk_lt_u32 s1, 0x100
	v_bitop3_b32 v0, v0, s18, v2 bitop3:0xde
	v_bitop3_b32 v151, s19, v1, v2 bitop3:0xf6
	s_cselect_b64 s[16:17], -1, 0
	s_add_i32 s49, 0, 0x10000
	s_add_i32 s50, 0, 0x14000
	v_or_b32_e32 v152, s5, v8
	v_add3_u32 v136, v12, v9, v10
	v_mov_b32_e32 v137, v133
	v_add3_u32 v138, v11, v9, v10
	v_mov_b32_e32 v139, v133
	v_mov_b64_e32 v[140:141], 0x420
	v_mov_b64_e32 v[142:143], 0x41f
	v_add_u32_e32 v153, s49, v151
	v_add_u32_e32 v154, s50, v151
	v_add_u32_e32 v155, 0, v0
	s_mov_b32 s51, 0xc1f00000
	v_mov_b32_e32 v156, 0x41f00000
	s_barrier
	s_branch .LBB0_824

; template <class Epi, class Sched, bool ALIGN_EPI = false, bool SP2 = false>
; __device__ __forceinline__ void gemm_phase(PG8_LAS unsigned char* lds, const Gemm g, const Sched& S, const Epi& E) {
;     ...
;         const bool has_next = S.next(ui + 1, nxt);
;         const char* nA = has_next ? (const char*)g.A + (size_t)nxt.pm * tstepA + (size_t)nxt.kz * kzb : cA; const char* nB = has_next ? (const char*)g.Bt + (size_t)nxt.pn * tstepB + (size_t)nxt.kz * kzb : cB;
;     ...
; #pragma unroll
;         for (int a = 0; a < 2; ++a)
; #pragma unroll
;             for (int b = 0; b < 2; ++b)
; #pragma unroll
;                 for (int m = 0; m < 4; ++m)
; #pragma unroll
;                     for (int n = 0; n < 2; ++n) acc[a][b][m][n] = (f32x4){0.f, 0.f, 0.f, 0.f};
;         cur = nxt; cA = nA; cB = nB; ++ui;
.LBB0_828:
	s_ashr_i32 s19, s18, 31
	s_lshl_b64 s[22:23], s[18:19], 19
	v_readlane_b32 s56, v240, 14
	v_readlane_b32 s57, v240, 15
	s_add_u32 s22, s56, s22
	s_addc_u32 s23, s57, s23
	s_and_b64 s[0:1], s[0:1], exec
	s_cselect_b32 s19, s23, s41
	s_cselect_b32 s55, s22, s40
	s_add_u32 s0, s42, 0x240080
	s_addc_u32 s1, s43, 0
	s_add_u32 s56, s40, 0x100
	v_mov_b64_e32 v[0:1], 0
	s_addc_u32 s57, s41, 0
	s_mov_b32 s58, -2
	v_mov_b64_e32 v[2:3], 0
	v_mov_b64_e32 v[4:5], 0
	v_mov_b64_e32 v[6:7], 0
	v_mov_b64_e32 v[16:17], 0
	v_mov_b64_e32 v[18:19], 0
	v_mov_b64_e32 v[20:21], 0
	v_mov_b64_e32 v[22:23], 0
	v_mov_b64_e32 v[32:33], 0
	v_mov_b64_e32 v[34:35], 0
	v_mov_b64_e32 v[36:37], 0
	v_mov_b64_e32 v[38:39], 0
	v_mov_b64_e32 v[48:49], 0
	v_mov_b64_e32 v[50:51], 0
	v_mov_b64_e32 v[52:53], 0
	v_mov_b64_e32 v[54:55], 0
	v_mov_b64_e32 v[8:9], 0
	v_mov_b64_e32 v[10:11], 0
	v_mov_b64_e32 v[12:13], 0
	v_mov_b64_e32 v[14:15], 0
	v_mov_b64_e32 v[24:25], 0
	v_mov_b64_e32 v[26:27], 0
	v_mov_b64_e32 v[28:29], 0
	v_mov_b64_e32 v[30:31], 0
	v_mov_b64_e32 v[40:41], 0
	v_mov_b64_e32 v[42:43], 0
	v_mov_b64_e32 v[44:45], 0
	v_mov_b64_e32 v[46:47], 0
	v_mov_b64_e32 v[56:57], 0
	v_mov_b64_e32 v[58:59], 0
	v_mov_b64_e32 v[60:61], 0
	v_mov_b64_e32 v[62:63], 0
	v_mov_b64_e32 v[64:65], 0
	v_mov_b64_e32 v[66:67], 0
	v_mov_b64_e32 v[68:69], 0
	v_mov_b64_e32 v[70:71], 0
	v_mov_b64_e32 v[80:81], 0
	v_mov_b64_e32 v[82:83], 0
	v_mov_b64_e32 v[84:85], 0
	v_mov_b64_e32 v[86:87], 0
	v_mov_b64_e32 v[96:97], 0
	v_mov_b64_e32 v[98:99], 0
	v_mov_b64_e32 v[100:101], 0
	v_mov_b64_e32 v[102:103], 0
	v_mov_b64_e32 v[112:113], 0
	v_mov_b64_e32 v[114:115], 0
	v_mov_b64_e32 v[116:117], 0
	v_mov_b64_e32 v[118:119], 0
	v_mov_b64_e32 v[72:73], 0
	v_mov_b64_e32 v[74:75], 0
	v_mov_b64_e32 v[76:77], 0
	v_mov_b64_e32 v[78:79], 0
	v_mov_b64_e32 v[88:89], 0
	v_mov_b64_e32 v[90:91], 0
	v_mov_b64_e32 v[92:93], 0
	v_mov_b64_e32 v[94:95], 0
	v_mov_b64_e32 v[104:105], 0
	v_mov_b64_e32 v[106:107], 0
	v_mov_b64_e32 v[108:109], 0
	v_mov_b64_e32 v[110:111], 0
	v_mov_b64_e32 v[120:121], 0
	v_mov_b64_e32 v[122:123], 0
	v_mov_b64_e32 v[124:125], 0
	v_mov_b64_e32 v[126:127], 0
	s_branch .LBB0_829

; #define PG8_STAGE(bufoff, gbase, voff) do { _Pragma("unroll") for (int _i = 0; _i < 2; ++_i) \
;         __builtin_amdgcn_global_load_lds((const unsigned*)((const char*)(gbase) + (voff)[_i]), (PG8_LAS unsigned*)(lds + (bufoff) + ldsw + _i * 8192), 16, 0, 0); } while (0)
; #define PG8_LDA(dst, b, h) do { _Pragma("unroll") for (int m = 0; m < 4; ++m) _Pragma("unroll") for (int k = 0; k < 2; ++k) dst[m][k] = *(const PG8_LAS bf16x8*)(lds + PG8_SA(b, h) + aoff + m * 2048 + k * 1024); } while (0)
; #define PG8_LDB(dst, b, h) do { _Pragma("unroll") for (int n = 0; n < 2; ++n) _Pragma("unroll") for (int k = 0; k < 2; ++k) dst[n][k] = *(const PG8_LAS bf16x8*)(lds + PG8_SB(b, h) + boff + n * 2048 + k * 1024); } while (0)
; #define PG8_MMA(ai, bj, At, Bt) do { __builtin_amdgcn_s_setprio(1); _Pragma("unroll") for (int m = 0; m < 4; ++m) _Pragma("unroll") for (int n = 0; n < 2; ++n) _Pragma("unroll") for (int k = 0; k < 2; ++k) \
;         acc[ai][bj][m][n] = __builtin_amdgcn_mfma_f32_16x16x32_bf16(Bt[n][k], At[m][k], acc[ai][bj][m][n], 0, 0, 0); __builtin_amdgcn_s_setprio(0); } while (0)
; #define PG8_WAIT_V(n) asm volatile("s_waitcnt vmcnt(" #n ")" ::: "memory")
; #define PG8_WAIT_L(n) asm volatile("s_waitcnt lgkmcnt(" #n ")" ::: "memory")
; #define PG8_BAR __builtin_amdgcn_s_barrier()
; #define PG8_SCHED __builtin_amdgcn_sched_barrier(0)
; template <class Epi, class Sched, bool ALIGN_EPI = false, bool SP2 = false>
; __device__ __forceinline__ void gemm_phase(PG8_LAS unsigned char* lds, const Gemm g, const Sched& S, const Epi& E) {
;     ...
;             PG8_LDB(B0, 0, 0); PG8_LDB(B1, 0, 1); PG8_SCHED; PG8_LDA(At, 0, 0); PG8_STAGE(PG8_SA(1, 1), a1 + hstepA, voffA);
;             PG8_WAIT_V(8); PG8_WAIT_L(0); PG8_BAR; PG8_MMA(0, 0, At, B0); PG8_MMA(0, 1, At, B1); PG8_BAR; PG8_SCHED;
;             PG8_LDA(At, 0, 1); PG8_STAGE(PG8_SB(0, 0), b2, voffB); PG8_STAGE(PG8_SB(0, 1), b2 + hstepB, voffB); PG8_STAGE(PG8_SA(0, 0), a2, voffA);
.LBB0_829:
	ds_read_b128 v[144:147], v153
	ds_read_b128 v[158:161], v153 offset:1024
	ds_read_b128 v[166:169], v153 offset:2048
	ds_read_b128 v[170:173], v153 offset:3072
	ds_read_b128 v[174:177], v154
	ds_read_b128 v[178:181], v154 offset:1024
	ds_read_b128 v[182:185], v154 offset:2048
	ds_read_b128 v[186:189], v154 offset:3072
	s_add_u32 s40, s0, 0xffdc0080
	s_addc_u32 s41, s1, -1
	s_cmp_eq_u32 s58, 12
	s_cselect_b32 s43, s21, s41
	s_cselect_b32 s42, s20, s40
	s_cselect_b32 s41, s19, s57
	s_cselect_b32 s40, s55, s56
	s_add_i32 m0, s33, 0xc000
	ds_read_b128 v[190:193], v155
	ds_read_b128 v[194:197], v155 offset:1024
	ds_read_b128 v[198:201], v155 offset:2048
	ds_read_b128 v[202:205], v155 offset:3072
	ds_read_b128 v[206:209], v155 offset:4096
	ds_read_b128 v[210:213], v155 offset:5120
	ds_read_b128 v[214:217], v155 offset:6144
	ds_read_b128 v[218:221], v155 offset:7168
	global_load_lds_dwordx4 v136, s[0:1]
	s_add_i32 m0, s33, 0xe000
	s_nop 0
	global_load_lds_dwordx4 v138, s[0:1]
	s_cmp_eq_u32 s58, -2
	s_cbranch_scc1 .Lrx2_A
	s_waitcnt vmcnt(8)
.Lrx2_A_back:
	s_waitcnt lgkmcnt(0)
	s_barrier
	s_setprio 0
	s_waitcnt lgkmcnt(0)
	v_mfma_f32_16x16x32_bf16 v[124:127], v[144:147], v[190:193], v[124:127]
	v_mfma_f32_16x16x32_bf16 v[120:123], v[166:169], v[190:193], v[120:123]
	v_mfma_f32_16x16x32_bf16 v[108:111], v[144:147], v[198:201], v[108:111]
	v_mfma_f32_16x16x32_bf16 v[104:107], v[166:169], v[198:201], v[104:107]
	v_mfma_f32_16x16x32_bf16 v[92:95], v[144:147], v[206:209], v[92:95]
	v_mfma_f32_16x16x32_bf16 v[88:91], v[166:169], v[206:209], v[88:91]
	v_mfma_f32_16x16x32_bf16 v[76:79], v[144:147], v[214:217], v[76:79]
	v_mfma_f32_16x16x32_bf16 v[72:75], v[166:169], v[214:217], v[72:75]
	v_mfma_f32_16x16x32_bf16 v[124:127], v[158:161], v[194:197], v[124:127]
	v_mfma_f32_16x16x32_bf16 v[120:123], v[170:173], v[194:197], v[120:123]
	v_mfma_f32_16x16x32_bf16 v[108:111], v[158:161], v[202:205], v[108:111]
	v_mfma_f32_16x16x32_bf16 v[104:107], v[170:173], v[202:205], v[104:107]
	v_mfma_f32_16x16x32_bf16 v[92:95], v[158:161], v[210:213], v[92:95]
	v_mfma_f32_16x16x32_bf16 v[88:91], v[170:173], v[210:213], v[88:91]
	v_mfma_f32_16x16x32_bf16 v[76:79], v[158:161], v[218:221], v[76:79]
	v_mfma_f32_16x16x32_bf16 v[72:75], v[170:173], v[218:221], v[72:75]
	v_mfma_f32_16x16x32_bf16 v[116:119], v[174:177], v[190:193], v[116:119]
	v_mfma_f32_16x16x32_bf16 v[112:115], v[182:185], v[190:193], v[112:115]
	v_mfma_f32_16x16x32_bf16 v[100:103], v[174:177], v[198:201], v[100:103]
	v_mfma_f32_16x16x32_bf16 v[96:99], v[182:185], v[198:201], v[96:99]
	v_mfma_f32_16x16x32_bf16 v[84:87], v[174:177], v[206:209], v[84:87]
	v_mfma_f32_16x16x32_bf16 v[80:83], v[182:185], v[206:209], v[80:83]
	v_mfma_f32_16x16x32_bf16 v[68:71], v[174:177], v[214:217], v[68:71]
	v_mfma_f32_16x16x32_bf16 v[64:67], v[182:185], v[214:217], v[64:67]
	v_mfma_f32_16x16x32_bf16 v[116:119], v[178:181], v[194:197], v[116:119]
	v_mfma_f32_16x16x32_bf16 v[112:115], v[186:189], v[194:197], v[112:115]
	v_mfma_f32_16x16x32_bf16 v[100:103], v[178:181], v[202:205], v[100:103]
	v_mfma_f32_16x16x32_bf16 v[96:99], v[186:189], v[202:205], v[96:99]
	v_mfma_f32_16x16x32_bf16 v[84:87], v[178:181], v[210:213], v[84:87]
	v_mfma_f32_16x16x32_bf16 v[80:83], v[186:189], v[210:213], v[80:83]
	v_mfma_f32_16x16x32_bf16 v[68:71], v[178:181], v[218:221], v[68:71]
	v_mfma_f32_16x16x32_bf16 v[64:67], v[186:189], v[218:221], v[64:67]
	s_setprio 1
	s_barrier
	s_add_i32 s59, s49, s30
	v_lshl_add_u64 v[148:149], s[40:41], 0, v[132:133]
	s_mov_b32 m0, s59
	ds_read_b128 v[190:193], v155 offset:16384
	ds_read_b128 v[194:197], v155 offset:17408
	ds_read_b128 v[198:201], v155 offset:18432
	ds_read_b128 v[202:205], v155 offset:19456
	ds_read_b128 v[206:209], v155 offset:20480
	ds_read_b128 v[210:213], v155 offset:21504
	ds_read_b128 v[214:217], v155 offset:22528
	ds_read_b128 v[218:221], v155 offset:23552
	global_load_lds_dwordx4 v132, s[40:41]
	s_add_i32 m0, s59, 0x2000
	s_add_u32 s60, s40, 0x40000
	v_lshl_add_u64 v[222:223], s[40:41], 0, v[128:129]
	s_addc_u32 s61, s41, 0
	s_add_i32 s59, s50, s30
	global_load_lds_dwordx4 v128, s[40:41]
	s_mov_b32 m0, s59
	v_lshl_add_u64 v[226:227], s[42:43], 0, v[130:131]
	global_load_lds_dwordx4 v132, s[60:61]
	s_add_i32 m0, s59, 0x2000
	s_nop 0
	global_load_lds_dwordx4 v128, s[60:61]
	v_lshl_add_u64 v[224:225], s[42:43], 0, v[134:135]
	s_mov_b32 m0, s33
	s_nop 0
	global_load_lds_dwordx4 v134, s[42:43]
	s_mov_b32 m0, s34
	s_nop 0
	global_load_lds_dwordx4 v130, s[42:43]
	s_cmp_eq_u32 s58, -2
	s_cbranch_scc1 .Lrx2_B
	s_waitcnt vmcnt(8)
; #define PG8_STAGE(bufoff, gbase, voff) do { _Pragma("unroll") for (int _i = 0; _i < 2; ++_i) \
;         __builtin_amdgcn_global_load_lds((const unsigned*)((const char*)(gbase) + (voff)[_i]), (PG8_LAS unsigned*)(lds + (bufoff) + ldsw + _i * 8192), 16, 0, 0); } while (0)
; #define PG8_LDA(dst, b, h) do { _Pragma("unroll") for (int m = 0; m < 4; ++m) _Pragma("unroll") for (int k = 0; k < 2; ++k) dst[m][k] = *(const PG8_LAS bf16x8*)(lds + PG8_SA(b, h) + aoff + m * 2048 + k * 1024); } while (0)
; #define PG8_LDB(dst, b, h) do { _Pragma("unroll") for (int n = 0; n < 2; ++n) _Pragma("unroll") for (int k = 0; k < 2; ++k) dst[n][k] = *(const PG8_LAS bf16x8*)(lds + PG8_SB(b, h) + boff + n * 2048 + k * 1024); } while (0)
; #define PG8_MMA(ai, bj, At, Bt) do { __builtin_amdgcn_s_setprio(1); _Pragma("unroll") for (int m = 0; m < 4; ++m) _Pragma("unroll") for (int n = 0; n < 2; ++n) _Pragma("unroll") for (int k = 0; k < 2; ++k) \
;         acc[ai][bj][m][n] = __builtin_amdgcn_mfma_f32_16x16x32_bf16(Bt[n][k], At[m][k], acc[ai][bj][m][n], 0, 0, 0); __builtin_amdgcn_s_setprio(0); } while (0)
; #define PG8_WAIT_V(n) asm volatile("s_waitcnt vmcnt(" #n ")" ::: "memory")
; #define PG8_WAIT_L(n) asm volatile("s_waitcnt lgkmcnt(" #n ")" ::: "memory")
; #define PG8_BAR __builtin_amdgcn_s_barrier()
; #define PG8_SCHED __builtin_amdgcn_sched_barrier(0)
; template <class Epi, class Sched, bool ALIGN_EPI = false, bool SP2 = false>
; __device__ __forceinline__ void gemm_phase(PG8_LAS unsigned char* lds, const Gemm g, const Sched& S, const Epi& E) {
;     ...
;             PG8_WAIT_V(8); PG8_WAIT_L(0); PG8_BAR; PG8_MMA(1, 0, At, B0); PG8_MMA(1, 1, At, B1); PG8_BAR; PG8_SCHED;
;             PG8_LDB(B0, 1, 0); PG8_LDB(B1, 1, 1); PG8_SCHED; PG8_LDA(At, 1, 0); PG8_STAGE(PG8_SA(0, 1), a2 + hstepA, voffA);
;             PG8_WAIT_V(8); PG8_WAIT_L(0); PG8_BAR; PG8_MMA(0, 0, At, B0); PG8_MMA(0, 1, At, B1); PG8_BAR; PG8_SCHED;
.Lrx2_B_back:
	s_waitcnt lgkmcnt(0)
	s_barrier
	s_setprio 0
	s_waitcnt lgkmcnt(0)
	v_mfma_f32_16x16x32_bf16 v[60:63], v[144:147], v[190:193], v[60:63]
	v_mfma_f32_16x16x32_bf16 v[56:59], v[166:169], v[190:193], v[56:59]
	v_mfma_f32_16x16x32_bf16 v[44:47], v[144:147], v[198:201], v[44:47]
	v_mfma_f32_16x16x32_bf16 v[40:43], v[166:169], v[198:201], v[40:43]
	v_mfma_f32_16x16x32_bf16 v[28:31], v[144:147], v[206:209], v[28:31]
	v_mfma_f32_16x16x32_bf16 v[24:27], v[166:169], v[206:209], v[24:27]
	v_mfma_f32_16x16x32_bf16 v[12:15], v[144:147], v[214:217], v[12:15]
	v_mfma_f32_16x16x32_bf16 v[8:11], v[166:169], v[214:217], v[8:11]
	v_mfma_f32_16x16x32_bf16 v[60:63], v[158:161], v[194:197], v[60:63]
	v_mfma_f32_16x16x32_bf16 v[56:59], v[170:173], v[194:197], v[56:59]
	v_mfma_f32_16x16x32_bf16 v[44:47], v[158:161], v[202:205], v[44:47]
	v_mfma_f32_16x16x32_bf16 v[40:43], v[170:173], v[202:205], v[40:43]
	v_mfma_f32_16x16x32_bf16 v[28:31], v[158:161], v[210:213], v[28:31]
	v_mfma_f32_16x16x32_bf16 v[24:27], v[170:173], v[210:213], v[24:27]
	v_mfma_f32_16x16x32_bf16 v[12:15], v[158:161], v[218:221], v[12:15]
	v_mfma_f32_16x16x32_bf16 v[8:11], v[170:173], v[218:221], v[8:11]
	v_mfma_f32_16x16x32_bf16 v[52:55], v[174:177], v[190:193], v[52:55]
	v_mfma_f32_16x16x32_bf16 v[48:51], v[182:185], v[190:193], v[48:51]
	v_mfma_f32_16x16x32_bf16 v[36:39], v[174:177], v[198:201], v[36:39]
	v_mfma_f32_16x16x32_bf16 v[32:35], v[182:185], v[198:201], v[32:35]
	v_mfma_f32_16x16x32_bf16 v[20:23], v[174:177], v[206:209], v[20:23]
	v_mfma_f32_16x16x32_bf16 v[16:19], v[182:185], v[206:209], v[16:19]
	v_mfma_f32_16x16x32_bf16 v[4:7], v[174:177], v[214:217], v[4:7]
	v_mfma_f32_16x16x32_bf16 v[0:3], v[182:185], v[214:217], v[0:3]
	v_mfma_f32_16x16x32_bf16 v[52:55], v[178:181], v[194:197], v[52:55]
	v_mfma_f32_16x16x32_bf16 v[48:51], v[186:189], v[194:197], v[48:51]
	v_mfma_f32_16x16x32_bf16 v[36:39], v[178:181], v[202:205], v[36:39]
	v_mfma_f32_16x16x32_bf16 v[32:35], v[186:189], v[202:205], v[32:35]
	v_mfma_f32_16x16x32_bf16 v[20:23], v[178:181], v[210:213], v[20:23]
	v_mfma_f32_16x16x32_bf16 v[16:19], v[186:189], v[210:213], v[16:19]
	v_mfma_f32_16x16x32_bf16 v[4:7], v[178:181], v[218:221], v[4:7]
	v_mfma_f32_16x16x32_bf16 v[0:3], v[186:189], v[218:221], v[0:3]
	s_setprio 1
	s_barrier
	s_add_i32 s59, 0, 0x18000
	v_add_u32_e32 v157, s59, v151
	s_add_i32 s60, 0, 0x1c000
	ds_read_b128 v[144:147], v157
	ds_read_b128 v[158:161], v157 offset:1024
	ds_read_b128 v[166:169], v157 offset:2048
	ds_read_b128 v[170:173], v157 offset:3072
	v_add_u32_e32 v157, s60, v151
	ds_read_b128 v[174:177], v157
	ds_read_b128 v[178:181], v157 offset:1024
	ds_read_b128 v[182:185], v157 offset:2048
	ds_read_b128 v[186:189], v157 offset:3072
	s_add_u32 s42, s42, 0x240000
	s_addc_u32 s43, s43, 0
	s_mov_b32 m0, s35
	ds_read_b128 v[190:193], v155 offset:32768
	ds_read_b128 v[194:197], v155 offset:33792
	ds_read_b128 v[198:201], v155 offset:34816
	ds_read_b128 v[202:205], v155 offset:35840
	ds_read_b128 v[206:209], v155 offset:36864
	ds_read_b128 v[210:213], v155 offset:37888
	ds_read_b128 v[214:217], v155 offset:38912
	ds_read_b128 v[218:221], v155 offset:39936
	global_load_lds_dwordx4 v134, s[42:43]
	s_mov_b32 m0, s44
	s_nop 0
	global_load_lds_dwordx4 v130, s[42:43]
	s_waitcnt vmcnt(8)
	s_waitcnt lgkmcnt(0)
	s_barrier
	s_setprio 0
	s_waitcnt lgkmcnt(0)
	v_mfma_f32_16x16x32_bf16 v[124:127], v[144:147], v[190:193], v[124:127]
	v_mfma_f32_16x16x32_bf16 v[120:123], v[166:169], v[190:193], v[120:123]
	v_mfma_f32_16x16x32_bf16 v[108:111], v[144:147], v[198:201], v[108:111]
	v_mfma_f32_16x16x32_bf16 v[104:107], v[166:169], v[198:201], v[104:107]
	v_mfma_f32_16x16x32_bf16 v[92:95], v[144:147], v[206:209], v[92:95]
	v_mfma_f32_16x16x32_bf16 v[88:91], v[166:169], v[206:209], v[88:91]
	v_mfma_f32_16x16x32_bf16 v[76:79], v[144:147], v[214:217], v[76:79]
	v_mfma_f32_16x16x32_bf16 v[72:75], v[166:169], v[214:217], v[72:75]
	v_mfma_f32_16x16x32_bf16 v[124:127], v[158:161], v[194:197], v[124:127]
	v_mfma_f32_16x16x32_bf16 v[120:123], v[170:173], v[194:197], v[120:123]
	v_mfma_f32_16x16x32_bf16 v[108:111], v[158:161], v[202:205], v[108:111]
	v_mfma_f32_16x16x32_bf16 v[104:107], v[170:173], v[202:205], v[104:107]
	v_mfma_f32_16x16x32_bf16 v[92:95], v[158:161], v[210:213], v[92:95]
	v_mfma_f32_16x16x32_bf16 v[88:91], v[170:173], v[210:213], v[88:91]
	v_mfma_f32_16x16x32_bf16 v[76:79], v[158:161], v[218:221], v[76:79]
	v_mfma_f32_16x16x32_bf16 v[72:75], v[170:173], v[218:221], v[72:75]
	v_mfma_f32_16x16x32_bf16 v[116:119], v[174:177], v[190:193], v[116:119]
	v_mfma_f32_16x16x32_bf16 v[112:115], v[182:185], v[190:193], v[112:115]
	v_mfma_f32_16x16x32_bf16 v[100:103], v[174:177], v[198:201], v[100:103]
	v_mfma_f32_16x16x32_bf16 v[96:99], v[182:185], v[198:201], v[96:99]
	v_mfma_f32_16x16x32_bf16 v[84:87], v[174:177], v[206:209], v[84:87]
	v_mfma_f32_16x16x32_bf16 v[80:83], v[182:185], v[206:209], v[80:83]
	v_mfma_f32_16x16x32_bf16 v[68:71], v[174:177], v[214:217], v[68:71]
	v_mfma_f32_16x16x32_bf16 v[64:67], v[182:185], v[214:217], v[64:67]
	v_mfma_f32_16x16x32_bf16 v[116:119], v[178:181], v[194:197], v[116:119]
	v_mfma_f32_16x16x32_bf16 v[112:115], v[186:189], v[194:197], v[112:115]
	v_mfma_f32_16x16x32_bf16 v[100:103], v[178:181], v[202:205], v[100:103]
	v_mfma_f32_16x16x32_bf16 v[96:99], v[186:189], v[202:205], v[96:99]
	v_mfma_f32_16x16x32_bf16 v[84:87], v[178:181], v[210:213], v[84:87]
	v_mfma_f32_16x16x32_bf16 v[80:83], v[186:189], v[210:213], v[80:83]
	v_mfma_f32_16x16x32_bf16 v[68:71], v[178:181], v[218:221], v[68:71]
	v_mfma_f32_16x16x32_bf16 v[64:67], v[186:189], v[218:221], v[64:67]
	s_setprio 1
	s_barrier
; #define PG8_STAGE(bufoff, gbase, voff) do { _Pragma("unroll") for (int _i = 0; _i < 2; ++_i) \
;         __builtin_amdgcn_global_load_lds((const unsigned*)((const char*)(gbase) + (voff)[_i]), (PG8_LAS unsigned*)(lds + (bufoff) + ldsw + _i * 8192), 16, 0, 0); } while (0)
; #define PG8_LDA(dst, b, h) do { _Pragma("unroll") for (int m = 0; m < 4; ++m) _Pragma("unroll") for (int k = 0; k < 2; ++k) dst[m][k] = *(const PG8_LAS bf16x8*)(lds + PG8_SA(b, h) + aoff + m * 2048 + k * 1024); } while (0)
; #define PG8_MMA(ai, bj, At, Bt) do { __builtin_amdgcn_s_setprio(1); _Pragma("unroll") for (int m = 0; m < 4; ++m) _Pragma("unroll") for (int n = 0; n < 2; ++n) _Pragma("unroll") for (int k = 0; k < 2; ++k) \
;         acc[ai][bj][m][n] = __builtin_amdgcn_mfma_f32_16x16x32_bf16(Bt[n][k], At[m][k], acc[ai][bj][m][n], 0, 0, 0); __builtin_amdgcn_s_setprio(0); } while (0)
; #define PG8_WAIT_V(n) asm volatile("s_waitcnt vmcnt(" #n ")" ::: "memory")
; #define PG8_WAIT_L(n) asm volatile("s_waitcnt lgkmcnt(" #n ")" ::: "memory")
; #define PG8_BAR __builtin_amdgcn_s_barrier()
; #define PG8_SCHED __builtin_amdgcn_sched_barrier(0)
; template <class Epi, class Sched, bool ALIGN_EPI = false, bool SP2 = false>
; __device__ __forceinline__ void gemm_phase(PG8_LAS unsigned char* lds, const Gemm g, const Sched& S, const Epi& E) {
;     ...
;             PG8_LDA(At, 1, 1); PG8_STAGE(PG8_SB(1, 0), b3, voffB); PG8_STAGE(PG8_SB(1, 1), b3 + hstepB, voffB); PG8_STAGE(PG8_SA(1, 0), a3, voffA);
;             PG8_WAIT_V(8); PG8_WAIT_L(0); PG8_BAR; PG8_MMA(1, 0, At, B0); PG8_MMA(1, 1, At, B1); PG8_BAR; PG8_SCHED;
	s_add_i32 s42, s59, s30
	v_lshl_add_u64 v[148:149], v[148:149], 0, s[10:11]
	s_mov_b32 m0, s42
	ds_read_b128 v[190:193], v155 offset:49152
	ds_read_b128 v[194:197], v155 offset:50176
	ds_read_b128 v[198:201], v155 offset:51200
	ds_read_b128 v[202:205], v155 offset:52224
	ds_read_b128 v[206:209], v155 offset:53248
	ds_read_b128 v[210:213], v155 offset:54272
	ds_read_b128 v[214:217], v155 offset:55296
	ds_read_b128 v[218:221], v155 offset:56320
	global_load_lds_dwordx4 v[148:149], off
	s_add_i32 m0, s42, 0x2000
	s_add_u32 s40, s40, 0x40080
	v_lshl_add_u64 v[148:149], v[222:223], 0, s[10:11]
	s_addc_u32 s41, s41, 0
	s_add_i32 s42, s60, s30
	global_load_lds_dwordx4 v[148:149], off
	s_mov_b32 m0, s42
	s_nop 0
	global_load_lds_dwordx4 v132, s[40:41]
	s_add_i32 m0, s42, 0x2000
	s_nop 0
	global_load_lds_dwordx4 v128, s[40:41]
	v_lshl_add_u64 v[148:149], v[224:225], 0, s[10:11]
	s_mov_b32 m0, s47
	s_nop 0
	global_load_lds_dwordx4 v[148:149], off
	v_lshl_add_u64 v[148:149], v[226:227], 0, s[10:11]
	s_mov_b32 m0, s48
	s_nop 0
	global_load_lds_dwordx4 v[148:149], off
	s_waitcnt vmcnt(8)
	s_waitcnt lgkmcnt(0)
	s_barrier
	s_setprio 0
	s_waitcnt lgkmcnt(0)
	v_mfma_f32_16x16x32_bf16 v[60:63], v[144:147], v[190:193], v[60:63]
	v_mfma_f32_16x16x32_bf16 v[56:59], v[166:169], v[190:193], v[56:59]
	v_mfma_f32_16x16x32_bf16 v[44:47], v[144:147], v[198:201], v[44:47]
	v_mfma_f32_16x16x32_bf16 v[40:43], v[166:169], v[198:201], v[40:43]
	v_mfma_f32_16x16x32_bf16 v[28:31], v[144:147], v[206:209], v[28:31]
	v_mfma_f32_16x16x32_bf16 v[24:27], v[166:169], v[206:209], v[24:27]
	v_mfma_f32_16x16x32_bf16 v[12:15], v[144:147], v[214:217], v[12:15]
	v_mfma_f32_16x16x32_bf16 v[8:11], v[166:169], v[214:217], v[8:11]
	v_mfma_f32_16x16x32_bf16 v[60:63], v[158:161], v[194:197], v[60:63]
	v_mfma_f32_16x16x32_bf16 v[56:59], v[170:173], v[194:197], v[56:59]
	v_mfma_f32_16x16x32_bf16 v[44:47], v[158:161], v[202:205], v[44:47]
	v_mfma_f32_16x16x32_bf16 v[40:43], v[170:173], v[202:205], v[40:43]
	v_mfma_f32_16x16x32_bf16 v[28:31], v[158:161], v[210:213], v[28:31]
	v_mfma_f32_16x16x32_bf16 v[24:27], v[170:173], v[210:213], v[24:27]
	v_mfma_f32_16x16x32_bf16 v[12:15], v[158:161], v[218:221], v[12:15]
	v_mfma_f32_16x16x32_bf16 v[8:11], v[170:173], v[218:221], v[8:11]
	v_mfma_f32_16x16x32_bf16 v[52:55], v[174:177], v[190:193], v[52:55]
	v_mfma_f32_16x16x32_bf16 v[48:51], v[182:185], v[190:193], v[48:51]
	v_mfma_f32_16x16x32_bf16 v[36:39], v[174:177], v[198:201], v[36:39]
	v_mfma_f32_16x16x32_bf16 v[32:35], v[182:185], v[198:201], v[32:35]
	v_mfma_f32_16x16x32_bf16 v[20:23], v[174:177], v[206:209], v[20:23]
	v_mfma_f32_16x16x32_bf16 v[16:19], v[182:185], v[206:209], v[16:19]
	v_mfma_f32_16x16x32_bf16 v[4:7], v[174:177], v[214:217], v[4:7]
	v_mfma_f32_16x16x32_bf16 v[0:3], v[182:185], v[214:217], v[0:3]
	v_mfma_f32_16x16x32_bf16 v[52:55], v[178:181], v[194:197], v[52:55]
	v_mfma_f32_16x16x32_bf16 v[48:51], v[186:189], v[194:197], v[48:51]
	v_mfma_f32_16x16x32_bf16 v[36:39], v[178:181], v[202:205], v[36:39]
	v_mfma_f32_16x16x32_bf16 v[32:35], v[186:189], v[202:205], v[32:35]
	v_mfma_f32_16x16x32_bf16 v[20:23], v[178:181], v[210:213], v[20:23]
	v_mfma_f32_16x16x32_bf16 v[16:19], v[186:189], v[210:213], v[16:19]
	v_mfma_f32_16x16x32_bf16 v[4:7], v[178:181], v[218:221], v[4:7]
	v_mfma_f32_16x16x32_bf16 v[0:3], v[186:189], v[218:221], v[0:3]
	s_setprio 1
	s_barrier
	s_add_i32 s58, s58, 2
	s_add_u32 s0, s0, 0x100
	s_addc_u32 s1, s1, 0
	s_add_u32 s56, s56, 0x100
	s_addc_u32 s57, s57, 0
	s_cmp_gt_u32 s58, 13
	s_cbranch_scc0 .LBB0_829
	s_and_b64 vcc, exec, s[16:17]
	s_cbranch_vccz .LBB0_832
	s_barrier

; #define PG8_STAGE(bufoff, gbase, voff) do { _Pragma("unroll") for (int _i = 0; _i < 2; ++_i) \
;         __builtin_amdgcn_global_load_lds((const unsigned*)((const char*)(gbase) + (voff)[_i]), (PG8_LAS unsigned*)(lds + (bufoff) + ldsw + _i * 8192), 16, 0, 0); } while (0)
; #define PG8_WAIT_V(n) asm volatile("s_waitcnt vmcnt(" #n ")" ::: "memory")
; #define PG8_BAR __builtin_amdgcn_s_barrier()
; template <class Epi, class Sched, bool ALIGN_EPI = false, bool SP2 = false>
; __device__ __forceinline__ void gemm_phase(PG8_LAS unsigned char* lds, const Gemm g, const Sched& S, const Epi& E) {
;     ...
;     const char* cA = (const char*)g.A + (size_t)cur.pm * tstepA + (size_t)cur.kz * kzb; const char* cB = (const char*)g.Bt + (size_t)cur.pn * tstepB + (size_t)cur.kz * kzb;
;     S.a_ready(cur);
;     if constexpr (SP2) {
;         PG8_STAGE(PG8_SB(0, 0), cB, voffB); PG8_STAGE(PG8_SB(0, 1), cB + hstepB, voffB); PG8_STAGE(PG8_SA(0, 0), cA, voffA); PG8_STAGE(PG8_SA(0, 1), cA + hstepA, voffA);
;         if (wr == 1) PG8_BAR;
;         PG8_WAIT_V(2); PG8_BAR;
;         PG8_STAGE(PG8_SB(1, 0), cB + kstep, voffB); PG8_STAGE(PG8_SA(1, 0), cA + kstep, voffA); PG8_STAGE(PG8_SB(1, 1), cB + hstepB + kstep, voffB);
;         PG8_WAIT_V(6); PG8_BAR;
.LBB0_840:
	v_readlane_b32 s16, v240, 3
	v_readlane_b32 s17, v240, 4
	s_add_u32 s10, s16, 0x15802800
	s_addc_u32 s11, s17, 0
	s_lshl_b32 s5, s5, 5
	s_mov_b64 s[16:17], 0x80
	s_and_b32 s5, s5, 0x60
	s_add_i32 m0, s46, 0x18000
	v_lshl_add_u64 v[6:7], v[6:7], 0, s[16:17]
	v_readlane_b32 s18, v240, 5
	s_lshl_b32 s20, s4, 13
	s_lshl_b32 s21, s5, 7
	s_waitcnt vmcnt(2)
	s_barrier
	global_load_lds_dwordx4 v[6:7], off
	v_lshl_add_u64 v[4:5], v[4:5], 0, s[16:17]
	s_add_i32 m0, s46, 0x1a000
	s_waitcnt lgkmcnt(0)
	s_add_i32 s52, s46, 0x8000
	s_add_i32 s53, s46, 0xa000
	v_readlane_b32 s19, v240, 6
	global_load_lds_dwordx4 v[4:5], off
	v_lshl_add_u64 v[0:1], v[0:1], 0, s[16:17]
	s_mov_b32 m0, s52
	s_add_u32 s18, s42, 0x40080
	global_load_lds_dwordx4 v[0:1], off
	v_lshl_add_u64 v[0:1], v[2:3], 0, s[16:17]
	s_mov_b32 m0, s53
	s_addc_u32 s19, s43, 0
	global_load_lds_dwordx4 v[0:1], off
	s_add_i32 m0, s46, 0x1c000
	v_lshl_add_u64 v[0:1], s[18:19], 0, v[132:133]
	global_load_lds_dwordx4 v[0:1], off
	v_lshl_add_u64 v[0:1], s[18:19], 0, v[128:129]
	s_add_i32 m0, s46, 0x1e000
	s_sext_i32_i8 s29, s0
	global_load_lds_dwordx4 v[0:1], off
	v_and_b32_e32 v0, 15, v162
	v_lshlrev_b32_e32 v1, 1, v8
	v_lshlrev_b32_e32 v2, 2, v162
	v_lshlrev_b32_e32 v3, 6, v162
	s_movk_i32 s0, 0x3c0
	v_lshl_or_b32 v152, s4, 6, v0
	v_lshl_or_b32 v0, v0, 6, v1
	v_and_b32_e32 v2, 32, v2
	v_and_or_b32 v1, v3, s0, v1
	s_waitcnt vmcnt(0)
	s_cmpk_lt_u32 s1, 0x100
	v_bitop3_b32 v0, v0, s20, v2 bitop3:0xde
	v_bitop3_b32 v153, s21, v1, v2 bitop3:0xf6
	s_cselect_b64 s[18:19], -1, 0
	s_add_i32 s54, 0, 0x10000
	s_add_i32 s55, 0, 0x14000
	v_or_b32_e32 v154, s5, v8
	v_add3_u32 v136, v12, v9, v10
	v_mov_b32_e32 v137, v133
	v_add3_u32 v138, v11, v9, v10
	v_mov_b32_e32 v139, v133
	v_mov_b64_e32 v[140:141], 0x420
	v_mov_b64_e32 v[142:143], 0x41f
	v_add_u32_e32 v155, s54, v153
	v_add_u32_e32 v156, s55, v153
	v_add_u32_e32 v157, 0, v0
	s_mov_b32 s56, 0xc1f00000
	v_mov_b32_e32 v158, 0x41f00000
	s_barrier
	s_branch .LBB0_843

; template <class Epi, class Sched, bool ALIGN_EPI = false, bool SP2 = false>
; __device__ __forceinline__ void gemm_phase(PG8_LAS unsigned char* lds, const Gemm g, const Sched& S, const Epi& E) {
;     ...
;         const bool has_next = S.next(ui + 1, nxt);
;         const char* nA = has_next ? (const char*)g.A + (size_t)nxt.pm * tstepA + (size_t)nxt.kz * kzb : cA; const char* nB = has_next ? (const char*)g.Bt + (size_t)nxt.pn * tstepB + (size_t)nxt.kz * kzb : cB;
;     ...
; #pragma unroll
;         for (int a = 0; a < 2; ++a)
; #pragma unroll
;             for (int b = 0; b < 2; ++b)
; #pragma unroll
;                 for (int m = 0; m < 4; ++m)
; #pragma unroll
;                     for (int n = 0; n < 2; ++n) acc[a][b][m][n] = (f32x4){0.f, 0.f, 0.f, 0.f};
;         cur = nxt; cA = nA; cB = nB; ++ui;
.LBB0_847:
	s_ashr_i32 s21, s20, 31
	s_lshl_b64 s[30:31], s[20:21], 19
	v_readlane_b32 s40, v240, 12
	v_readlane_b32 s41, v240, 13
	s_add_u32 s40, s40, s30
	s_addc_u32 s41, s41, s31
	s_and_b64 s[0:1], s[0:1], exec
	s_cselect_b32 s21, s41, s43
	s_cselect_b32 s30, s40, s42
	s_add_u32 s0, s44, 0x240080
	s_addc_u32 s1, s45, 0
	s_add_u32 s31, s42, 0x100
	v_mov_b64_e32 v[0:1], 0
	s_addc_u32 s34, s43, 0
	s_mov_b32 s58, -2
	v_mov_b64_e32 v[2:3], 0
	v_mov_b64_e32 v[4:5], 0
	v_mov_b64_e32 v[6:7], 0
	v_mov_b64_e32 v[16:17], 0
	v_mov_b64_e32 v[18:19], 0
	v_mov_b64_e32 v[20:21], 0
	v_mov_b64_e32 v[22:23], 0
	v_mov_b64_e32 v[32:33], 0
	v_mov_b64_e32 v[34:35], 0
	v_mov_b64_e32 v[36:37], 0
	v_mov_b64_e32 v[38:39], 0
	v_mov_b64_e32 v[48:49], 0
	v_mov_b64_e32 v[50:51], 0
	v_mov_b64_e32 v[52:53], 0
	v_mov_b64_e32 v[54:55], 0
	v_mov_b64_e32 v[8:9], 0
	v_mov_b64_e32 v[10:11], 0
	v_mov_b64_e32 v[12:13], 0
	v_mov_b64_e32 v[14:15], 0
	v_mov_b64_e32 v[24:25], 0
	v_mov_b64_e32 v[26:27], 0
	v_mov_b64_e32 v[28:29], 0
	v_mov_b64_e32 v[30:31], 0
	v_mov_b64_e32 v[40:41], 0
	v_mov_b64_e32 v[42:43], 0
	v_mov_b64_e32 v[44:45], 0
	v_mov_b64_e32 v[46:47], 0
	v_mov_b64_e32 v[56:57], 0
	v_mov_b64_e32 v[58:59], 0
	v_mov_b64_e32 v[60:61], 0
	v_mov_b64_e32 v[62:63], 0
	v_mov_b64_e32 v[64:65], 0
	v_mov_b64_e32 v[66:67], 0
	v_mov_b64_e32 v[68:69], 0
	v_mov_b64_e32 v[70:71], 0
	v_mov_b64_e32 v[80:81], 0
	v_mov_b64_e32 v[82:83], 0
	v_mov_b64_e32 v[84:85], 0
	v_mov_b64_e32 v[86:87], 0
	v_mov_b64_e32 v[96:97], 0
	v_mov_b64_e32 v[98:99], 0
	v_mov_b64_e32 v[100:101], 0
	v_mov_b64_e32 v[102:103], 0
	v_mov_b64_e32 v[112:113], 0
	v_mov_b64_e32 v[114:115], 0
	v_mov_b64_e32 v[116:117], 0
	v_mov_b64_e32 v[118:119], 0
	v_mov_b64_e32 v[72:73], 0
	v_mov_b64_e32 v[74:75], 0
	v_mov_b64_e32 v[76:77], 0
	v_mov_b64_e32 v[78:79], 0
	v_mov_b64_e32 v[88:89], 0
	v_mov_b64_e32 v[90:91], 0
	v_mov_b64_e32 v[92:93], 0
	v_mov_b64_e32 v[94:95], 0
	v_mov_b64_e32 v[104:105], 0
	v_mov_b64_e32 v[106:107], 0
	v_mov_b64_e32 v[108:109], 0
	v_mov_b64_e32 v[110:111], 0
	v_mov_b64_e32 v[120:121], 0
	v_mov_b64_e32 v[122:123], 0
	v_mov_b64_e32 v[124:125], 0
	v_mov_b64_e32 v[126:127], 0
	s_branch .LBB0_848

; #define PG8_STAGE(bufoff, gbase, voff) do { _Pragma("unroll") for (int _i = 0; _i < 2; ++_i) \
;         __builtin_amdgcn_global_load_lds((const unsigned*)((const char*)(gbase) + (voff)[_i]), (PG8_LAS unsigned*)(lds + (bufoff) + ldsw + _i * 8192), 16, 0, 0); } while (0)
; #define PG8_LDA(dst, b, h) do { _Pragma("unroll") for (int m = 0; m < 4; ++m) _Pragma("unroll") for (int k = 0; k < 2; ++k) dst[m][k] = *(const PG8_LAS bf16x8*)(lds + PG8_SA(b, h) + aoff + m * 2048 + k * 1024); } while (0)
; #define PG8_LDB(dst, b, h) do { _Pragma("unroll") for (int n = 0; n < 2; ++n) _Pragma("unroll") for (int k = 0; k < 2; ++k) dst[n][k] = *(const PG8_LAS bf16x8*)(lds + PG8_SB(b, h) + boff + n * 2048 + k * 1024); } while (0)
; #define PG8_MMA(ai, bj, At, Bt) do { __builtin_amdgcn_s_setprio(1); _Pragma("unroll") for (int m = 0; m < 4; ++m) _Pragma("unroll") for (int n = 0; n < 2; ++n) _Pragma("unroll") for (int k = 0; k < 2; ++k) \
;         acc[ai][bj][m][n] = __builtin_amdgcn_mfma_f32_16x16x32_bf16(Bt[n][k], At[m][k], acc[ai][bj][m][n], 0, 0, 0); __builtin_amdgcn_s_setprio(0); } while (0)
; #define PG8_WAIT_V(n) asm volatile("s_waitcnt vmcnt(" #n ")" ::: "memory")
; #define PG8_WAIT_L(n) asm volatile("s_waitcnt lgkmcnt(" #n ")" ::: "memory")
; #define PG8_BAR __builtin_amdgcn_s_barrier()
; #define PG8_SCHED __builtin_amdgcn_sched_barrier(0)
; template <class Epi, class Sched, bool ALIGN_EPI = false, bool SP2 = false>
; __device__ __forceinline__ void gemm_phase(PG8_LAS unsigned char* lds, const Gemm g, const Sched& S, const Epi& E) {
;     ...
;             PG8_LDB(B0, 0, 0); PG8_LDB(B1, 0, 1); PG8_SCHED; PG8_LDA(At, 0, 0); PG8_STAGE(PG8_SA(1, 1), a1 + hstepA, voffA);
;             PG8_WAIT_V(8); PG8_WAIT_L(0); PG8_BAR; PG8_MMA(0, 0, At, B0); PG8_MMA(0, 1, At, B1); PG8_BAR; PG8_SCHED;
;             PG8_LDA(At, 0, 1); PG8_STAGE(PG8_SB(0, 0), b2, voffB); PG8_STAGE(PG8_SB(0, 1), b2 + hstepB, voffB); PG8_STAGE(PG8_SA(0, 0), a2, voffA);
.LBB0_848:
	ds_read_b128 v[144:147], v155
	ds_read_b128 v[148:151], v155 offset:1024
	ds_read_b128 v[166:169], v155 offset:2048
	ds_read_b128 v[170:173], v155 offset:3072
	ds_read_b128 v[174:177], v156
	ds_read_b128 v[178:181], v156 offset:1024
	ds_read_b128 v[182:185], v156 offset:2048
	ds_read_b128 v[186:189], v156 offset:3072
	s_add_u32 s42, s0, 0xffdc0080
	s_addc_u32 s43, s1, -1
	s_cmp_eq_u32 s58, 12
	s_cselect_b32 s45, s23, s43
	s_cselect_b32 s44, s22, s42
	s_cselect_b32 s43, s21, s34
	s_cselect_b32 s42, s30, s31
	s_add_i32 m0, s46, 0xc000
	ds_read_b128 v[190:193], v157
	ds_read_b128 v[194:197], v157 offset:1024
	ds_read_b128 v[198:201], v157 offset:2048
	ds_read_b128 v[202:205], v157 offset:3072
	ds_read_b128 v[206:209], v157 offset:4096
	ds_read_b128 v[210:213], v157 offset:5120
	ds_read_b128 v[214:217], v157 offset:6144
	ds_read_b128 v[218:221], v157 offset:7168
	global_load_lds_dwordx4 v136, s[0:1]
	s_add_i32 m0, s46, 0xe000
	s_nop 0
	global_load_lds_dwordx4 v138, s[0:1]
	s_cmp_eq_u32 s58, -2
	s_cbranch_scc1 .Lrx3_A
	s_waitcnt vmcnt(8)
.Lrx3_A_back:
	s_waitcnt lgkmcnt(0)
	s_barrier
	s_setprio 0
	s_waitcnt lgkmcnt(0)
	v_mfma_f32_16x16x32_bf16 v[124:127], v[144:147], v[190:193], v[124:127]
	v_mfma_f32_16x16x32_bf16 v[120:123], v[166:169], v[190:193], v[120:123]
	v_mfma_f32_16x16x32_bf16 v[108:111], v[144:147], v[198:201], v[108:111]
	v_mfma_f32_16x16x32_bf16 v[104:107], v[166:169], v[198:201], v[104:107]
	v_mfma_f32_16x16x32_bf16 v[92:95], v[144:147], v[206:209], v[92:95]
	v_mfma_f32_16x16x32_bf16 v[88:91], v[166:169], v[206:209], v[88:91]
	v_mfma_f32_16x16x32_bf16 v[76:79], v[144:147], v[214:217], v[76:79]
	v_mfma_f32_16x16x32_bf16 v[72:75], v[166:169], v[214:217], v[72:75]
	v_mfma_f32_16x16x32_bf16 v[124:127], v[148:151], v[194:197], v[124:127]
	v_mfma_f32_16x16x32_bf16 v[120:123], v[170:173], v[194:197], v[120:123]
	v_mfma_f32_16x16x32_bf16 v[108:111], v[148:151], v[202:205], v[108:111]
	v_mfma_f32_16x16x32_bf16 v[104:107], v[170:173], v[202:205], v[104:107]
	v_mfma_f32_16x16x32_bf16 v[92:95], v[148:151], v[210:213], v[92:95]
	v_mfma_f32_16x16x32_bf16 v[88:91], v[170:173], v[210:213], v[88:91]
	v_mfma_f32_16x16x32_bf16 v[76:79], v[148:151], v[218:221], v[76:79]
	v_mfma_f32_16x16x32_bf16 v[72:75], v[170:173], v[218:221], v[72:75]
	v_mfma_f32_16x16x32_bf16 v[116:119], v[174:177], v[190:193], v[116:119]
	v_mfma_f32_16x16x32_bf16 v[112:115], v[182:185], v[190:193], v[112:115]
	v_mfma_f32_16x16x32_bf16 v[100:103], v[174:177], v[198:201], v[100:103]
	v_mfma_f32_16x16x32_bf16 v[96:99], v[182:185], v[198:201], v[96:99]
	v_mfma_f32_16x16x32_bf16 v[84:87], v[174:177], v[206:209], v[84:87]
	v_mfma_f32_16x16x32_bf16 v[80:83], v[182:185], v[206:209], v[80:83]
	v_mfma_f32_16x16x32_bf16 v[68:71], v[174:177], v[214:217], v[68:71]
	v_mfma_f32_16x16x32_bf16 v[64:67], v[182:185], v[214:217], v[64:67]
	v_mfma_f32_16x16x32_bf16 v[116:119], v[178:181], v[194:197], v[116:119]
	v_mfma_f32_16x16x32_bf16 v[112:115], v[186:189], v[194:197], v[112:115]
	v_mfma_f32_16x16x32_bf16 v[100:103], v[178:181], v[202:205], v[100:103]
	v_mfma_f32_16x16x32_bf16 v[96:99], v[186:189], v[202:205], v[96:99]
	v_mfma_f32_16x16x32_bf16 v[84:87], v[178:181], v[210:213], v[84:87]
	v_mfma_f32_16x16x32_bf16 v[80:83], v[186:189], v[210:213], v[80:83]
	v_mfma_f32_16x16x32_bf16 v[68:71], v[178:181], v[218:221], v[68:71]
	v_mfma_f32_16x16x32_bf16 v[64:67], v[186:189], v[218:221], v[64:67]
	s_setprio 1
	s_barrier
	s_add_i32 s59, s54, s33
	v_lshl_add_u64 v[160:161], s[42:43], 0, v[132:133]
	s_mov_b32 m0, s59
	ds_read_b128 v[190:193], v157 offset:16384
	ds_read_b128 v[194:197], v157 offset:17408
	ds_read_b128 v[198:201], v157 offset:18432
	ds_read_b128 v[202:205], v157 offset:19456
	ds_read_b128 v[206:209], v157 offset:20480
	ds_read_b128 v[210:213], v157 offset:21504
	ds_read_b128 v[214:217], v157 offset:22528
	ds_read_b128 v[218:221], v157 offset:23552
	global_load_lds_dwordx4 v132, s[42:43]
	s_add_i32 m0, s59, 0x2000
	s_add_u32 s60, s42, 0x40000
	v_lshl_add_u64 v[222:223], s[42:43], 0, v[128:129]
	s_addc_u32 s61, s43, 0
	s_add_i32 s59, s55, s33
	global_load_lds_dwordx4 v128, s[42:43]
	s_mov_b32 m0, s59
	v_lshl_add_u64 v[226:227], s[44:45], 0, v[130:131]
	global_load_lds_dwordx4 v132, s[60:61]
	s_add_i32 m0, s59, 0x2000
	s_nop 0
	global_load_lds_dwordx4 v128, s[60:61]
	v_lshl_add_u64 v[224:225], s[44:45], 0, v[134:135]
	s_mov_b32 m0, s46
	s_nop 0
	global_load_lds_dwordx4 v134, s[44:45]
	s_mov_b32 m0, s47
	s_nop 0
	global_load_lds_dwordx4 v130, s[44:45]
	s_cmp_eq_u32 s58, -2
	s_cbranch_scc1 .Lrx3_B
	s_waitcnt vmcnt(8)
; #define PG8_STAGE(bufoff, gbase, voff) do { _Pragma("unroll") for (int _i = 0; _i < 2; ++_i) \
;         __builtin_amdgcn_global_load_lds((const unsigned*)((const char*)(gbase) + (voff)[_i]), (PG8_LAS unsigned*)(lds + (bufoff) + ldsw + _i * 8192), 16, 0, 0); } while (0)
; #define PG8_LDA(dst, b, h) do { _Pragma("unroll") for (int m = 0; m < 4; ++m) _Pragma("unroll") for (int k = 0; k < 2; ++k) dst[m][k] = *(const PG8_LAS bf16x8*)(lds + PG8_SA(b, h) + aoff + m * 2048 + k * 1024); } while (0)
; #define PG8_LDB(dst, b, h) do { _Pragma("unroll") for (int n = 0; n < 2; ++n) _Pragma("unroll") for (int k = 0; k < 2; ++k) dst[n][k] = *(const PG8_LAS bf16x8*)(lds + PG8_SB(b, h) + boff + n * 2048 + k * 1024); } while (0)
; #define PG8_MMA(ai, bj, At, Bt) do { __builtin_amdgcn_s_setprio(1); _Pragma("unroll") for (int m = 0; m < 4; ++m) _Pragma("unroll") for (int n = 0; n < 2; ++n) _Pragma("unroll") for (int k = 0; k < 2; ++k) \
;         acc[ai][bj][m][n] = __builtin_amdgcn_mfma_f32_16x16x32_bf16(Bt[n][k], At[m][k], acc[ai][bj][m][n], 0, 0, 0); __builtin_amdgcn_s_setprio(0); } while (0)
; #define PG8_WAIT_V(n) asm volatile("s_waitcnt vmcnt(" #n ")" ::: "memory")
; #define PG8_WAIT_L(n) asm volatile("s_waitcnt lgkmcnt(" #n ")" ::: "memory")
; #define PG8_BAR __builtin_amdgcn_s_barrier()
; #define PG8_SCHED __builtin_amdgcn_sched_barrier(0)
; template <class Epi, class Sched, bool ALIGN_EPI = false, bool SP2 = false>
; __device__ __forceinline__ void gemm_phase(PG8_LAS unsigned char* lds, const Gemm g, const Sched& S, const Epi& E) {
;     ...
;             PG8_WAIT_V(8); PG8_WAIT_L(0); PG8_BAR; PG8_MMA(1, 0, At, B0); PG8_MMA(1, 1, At, B1); PG8_BAR; PG8_SCHED;
;             PG8_LDB(B0, 1, 0); PG8_LDB(B1, 1, 1); PG8_SCHED; PG8_LDA(At, 1, 0); PG8_STAGE(PG8_SA(0, 1), a2 + hstepA, voffA);
;             PG8_WAIT_V(8); PG8_WAIT_L(0); PG8_BAR; PG8_MMA(0, 0, At, B0); PG8_MMA(0, 1, At, B1); PG8_BAR; PG8_SCHED;
.Lrx3_B_back:
	s_waitcnt lgkmcnt(0)
	s_barrier
	s_setprio 0
	s_waitcnt lgkmcnt(0)
	v_mfma_f32_16x16x32_bf16 v[60:63], v[144:147], v[190:193], v[60:63]
	v_mfma_f32_16x16x32_bf16 v[56:59], v[166:169], v[190:193], v[56:59]
	v_mfma_f32_16x16x32_bf16 v[44:47], v[144:147], v[198:201], v[44:47]
	v_mfma_f32_16x16x32_bf16 v[40:43], v[166:169], v[198:201], v[40:43]
	v_mfma_f32_16x16x32_bf16 v[28:31], v[144:147], v[206:209], v[28:31]
	v_mfma_f32_16x16x32_bf16 v[24:27], v[166:169], v[206:209], v[24:27]
	v_mfma_f32_16x16x32_bf16 v[12:15], v[144:147], v[214:217], v[12:15]
	v_mfma_f32_16x16x32_bf16 v[8:11], v[166:169], v[214:217], v[8:11]
	v_mfma_f32_16x16x32_bf16 v[60:63], v[148:151], v[194:197], v[60:63]
	v_mfma_f32_16x16x32_bf16 v[56:59], v[170:173], v[194:197], v[56:59]
	v_mfma_f32_16x16x32_bf16 v[44:47], v[148:151], v[202:205], v[44:47]
	v_mfma_f32_16x16x32_bf16 v[40:43], v[170:173], v[202:205], v[40:43]
	v_mfma_f32_16x16x32_bf16 v[28:31], v[148:151], v[210:213], v[28:31]
	v_mfma_f32_16x16x32_bf16 v[24:27], v[170:173], v[210:213], v[24:27]
	v_mfma_f32_16x16x32_bf16 v[12:15], v[148:151], v[218:221], v[12:15]
	v_mfma_f32_16x16x32_bf16 v[8:11], v[170:173], v[218:221], v[8:11]
	v_mfma_f32_16x16x32_bf16 v[52:55], v[174:177], v[190:193], v[52:55]
	v_mfma_f32_16x16x32_bf16 v[48:51], v[182:185], v[190:193], v[48:51]
	v_mfma_f32_16x16x32_bf16 v[36:39], v[174:177], v[198:201], v[36:39]
	v_mfma_f32_16x16x32_bf16 v[32:35], v[182:185], v[198:201], v[32:35]
	v_mfma_f32_16x16x32_bf16 v[20:23], v[174:177], v[206:209], v[20:23]
	v_mfma_f32_16x16x32_bf16 v[16:19], v[182:185], v[206:209], v[16:19]
	v_mfma_f32_16x16x32_bf16 v[4:7], v[174:177], v[214:217], v[4:7]
	v_mfma_f32_16x16x32_bf16 v[0:3], v[182:185], v[214:217], v[0:3]
	v_mfma_f32_16x16x32_bf16 v[52:55], v[178:181], v[194:197], v[52:55]
	v_mfma_f32_16x16x32_bf16 v[48:51], v[186:189], v[194:197], v[48:51]
	v_mfma_f32_16x16x32_bf16 v[36:39], v[178:181], v[202:205], v[36:39]
	v_mfma_f32_16x16x32_bf16 v[32:35], v[186:189], v[202:205], v[32:35]
	v_mfma_f32_16x16x32_bf16 v[20:23], v[178:181], v[210:213], v[20:23]
	v_mfma_f32_16x16x32_bf16 v[16:19], v[186:189], v[210:213], v[16:19]
	v_mfma_f32_16x16x32_bf16 v[4:7], v[178:181], v[218:221], v[4:7]
	v_mfma_f32_16x16x32_bf16 v[0:3], v[186:189], v[218:221], v[0:3]
	s_setprio 1
	s_barrier
	s_add_i32 s59, 0, 0x18000
	v_add_u32_e32 v159, s59, v153
	s_add_i32 s60, 0, 0x1c000
	ds_read_b128 v[144:147], v159
	ds_read_b128 v[148:151], v159 offset:1024
	ds_read_b128 v[166:169], v159 offset:2048
	ds_read_b128 v[170:173], v159 offset:3072
	v_add_u32_e32 v159, s60, v153
	ds_read_b128 v[174:177], v159
	ds_read_b128 v[178:181], v159 offset:1024
	ds_read_b128 v[182:185], v159 offset:2048
	ds_read_b128 v[186:189], v159 offset:3072
	s_add_u32 s44, s44, 0x240000
	s_addc_u32 s45, s45, 0
	s_mov_b32 m0, s48
	ds_read_b128 v[190:193], v157 offset:32768
	ds_read_b128 v[194:197], v157 offset:33792
	ds_read_b128 v[198:201], v157 offset:34816
	ds_read_b128 v[202:205], v157 offset:35840
	ds_read_b128 v[206:209], v157 offset:36864
	ds_read_b128 v[210:213], v157 offset:37888
	ds_read_b128 v[214:217], v157 offset:38912
	ds_read_b128 v[218:221], v157 offset:39936
	global_load_lds_dwordx4 v134, s[44:45]
	s_mov_b32 m0, s49
	s_nop 0
	global_load_lds_dwordx4 v130, s[44:45]
	s_waitcnt vmcnt(8)
	s_waitcnt lgkmcnt(0)
	s_barrier
	s_setprio 0
	s_waitcnt lgkmcnt(0)
	v_mfma_f32_16x16x32_bf16 v[124:127], v[144:147], v[190:193], v[124:127]
	v_mfma_f32_16x16x32_bf16 v[120:123], v[166:169], v[190:193], v[120:123]
	v_mfma_f32_16x16x32_bf16 v[108:111], v[144:147], v[198:201], v[108:111]
	v_mfma_f32_16x16x32_bf16 v[104:107], v[166:169], v[198:201], v[104:107]
	v_mfma_f32_16x16x32_bf16 v[92:95], v[144:147], v[206:209], v[92:95]
	v_mfma_f32_16x16x32_bf16 v[88:91], v[166:169], v[206:209], v[88:91]
	v_mfma_f32_16x16x32_bf16 v[76:79], v[144:147], v[214:217], v[76:79]
	v_mfma_f32_16x16x32_bf16 v[72:75], v[166:169], v[214:217], v[72:75]
	v_mfma_f32_16x16x32_bf16 v[124:127], v[148:151], v[194:197], v[124:127]
	v_mfma_f32_16x16x32_bf16 v[120:123], v[170:173], v[194:197], v[120:123]
	v_mfma_f32_16x16x32_bf16 v[108:111], v[148:151], v[202:205], v[108:111]
	v_mfma_f32_16x16x32_bf16 v[104:107], v[170:173], v[202:205], v[104:107]
	v_mfma_f32_16x16x32_bf16 v[92:95], v[148:151], v[210:213], v[92:95]
	v_mfma_f32_16x16x32_bf16 v[88:91], v[170:173], v[210:213], v[88:91]
	v_mfma_f32_16x16x32_bf16 v[76:79], v[148:151], v[218:221], v[76:79]
	v_mfma_f32_16x16x32_bf16 v[72:75], v[170:173], v[218:221], v[72:75]
	v_mfma_f32_16x16x32_bf16 v[116:119], v[174:177], v[190:193], v[116:119]
	v_mfma_f32_16x16x32_bf16 v[112:115], v[182:185], v[190:193], v[112:115]
	v_mfma_f32_16x16x32_bf16 v[100:103], v[174:177], v[198:201], v[100:103]
	v_mfma_f32_16x16x32_bf16 v[96:99], v[182:185], v[198:201], v[96:99]
	v_mfma_f32_16x16x32_bf16 v[84:87], v[174:177], v[206:209], v[84:87]
	v_mfma_f32_16x16x32_bf16 v[80:83], v[182:185], v[206:209], v[80:83]
	v_mfma_f32_16x16x32_bf16 v[68:71], v[174:177], v[214:217], v[68:71]
	v_mfma_f32_16x16x32_bf16 v[64:67], v[182:185], v[214:217], v[64:67]
	v_mfma_f32_16x16x32_bf16 v[116:119], v[178:181], v[194:197], v[116:119]
	v_mfma_f32_16x16x32_bf16 v[112:115], v[186:189], v[194:197], v[112:115]
	v_mfma_f32_16x16x32_bf16 v[100:103], v[178:181], v[202:205], v[100:103]
	v_mfma_f32_16x16x32_bf16 v[96:99], v[186:189], v[202:205], v[96:99]
	v_mfma_f32_16x16x32_bf16 v[84:87], v[178:181], v[210:213], v[84:87]
	v_mfma_f32_16x16x32_bf16 v[80:83], v[186:189], v[210:213], v[80:83]
	v_mfma_f32_16x16x32_bf16 v[68:71], v[178:181], v[218:221], v[68:71]
	v_mfma_f32_16x16x32_bf16 v[64:67], v[186:189], v[218:221], v[64:67]
	s_setprio 1
	s_barrier
; #define PG8_STAGE(bufoff, gbase, voff) do { _Pragma("unroll") for (int _i = 0; _i < 2; ++_i) \
;         __builtin_amdgcn_global_load_lds((const unsigned*)((const char*)(gbase) + (voff)[_i]), (PG8_LAS unsigned*)(lds + (bufoff) + ldsw + _i * 8192), 16, 0, 0); } while (0)
; #define PG8_LDA(dst, b, h) do { _Pragma("unroll") for (int m = 0; m < 4; ++m) _Pragma("unroll") for (int k = 0; k < 2; ++k) dst[m][k] = *(const PG8_LAS bf16x8*)(lds + PG8_SA(b, h) + aoff + m * 2048 + k * 1024); } while (0)
; #define PG8_MMA(ai, bj, At, Bt) do { __builtin_amdgcn_s_setprio(1); _Pragma("unroll") for (int m = 0; m < 4; ++m) _Pragma("unroll") for (int n = 0; n < 2; ++n) _Pragma("unroll") for (int k = 0; k < 2; ++k) \
;         acc[ai][bj][m][n] = __builtin_amdgcn_mfma_f32_16x16x32_bf16(Bt[n][k], At[m][k], acc[ai][bj][m][n], 0, 0, 0); __builtin_amdgcn_s_setprio(0); } while (0)
; #define PG8_WAIT_V(n) asm volatile("s_waitcnt vmcnt(" #n ")" ::: "memory")
; #define PG8_WAIT_L(n) asm volatile("s_waitcnt lgkmcnt(" #n ")" ::: "memory")
; #define PG8_BAR __builtin_amdgcn_s_barrier()
; #define PG8_SCHED __builtin_amdgcn_sched_barrier(0)
; template <class Epi, class Sched, bool ALIGN_EPI = false, bool SP2 = false>
; __device__ __forceinline__ void gemm_phase(PG8_LAS unsigned char* lds, const Gemm g, const Sched& S, const Epi& E) {
;     ...
;             PG8_LDA(At, 1, 1); PG8_STAGE(PG8_SB(1, 0), b3, voffB); PG8_STAGE(PG8_SB(1, 1), b3 + hstepB, voffB); PG8_STAGE(PG8_SA(1, 0), a3, voffA);
;             PG8_WAIT_V(8); PG8_WAIT_L(0); PG8_BAR; PG8_MMA(1, 0, At, B0); PG8_MMA(1, 1, At, B1); PG8_BAR; PG8_SCHED;
	s_add_i32 s44, s59, s33
	v_lshl_add_u64 v[160:161], v[160:161], 0, s[16:17]
	s_mov_b32 m0, s44
	ds_read_b128 v[190:193], v157 offset:49152
	ds_read_b128 v[194:197], v157 offset:50176
	ds_read_b128 v[198:201], v157 offset:51200
	ds_read_b128 v[202:205], v157 offset:52224
	ds_read_b128 v[206:209], v157 offset:53248
	ds_read_b128 v[210:213], v157 offset:54272
	ds_read_b128 v[214:217], v157 offset:55296
	ds_read_b128 v[218:221], v157 offset:56320
	global_load_lds_dwordx4 v[160:161], off
	s_add_i32 m0, s44, 0x2000
	s_add_u32 s42, s42, 0x40080
	v_lshl_add_u64 v[160:161], v[222:223], 0, s[16:17]
	s_addc_u32 s43, s43, 0
	s_add_i32 s44, s60, s33
	global_load_lds_dwordx4 v[160:161], off
	s_mov_b32 m0, s44
	s_nop 0
	global_load_lds_dwordx4 v132, s[42:43]
	s_add_i32 m0, s44, 0x2000
	s_nop 0
	global_load_lds_dwordx4 v128, s[42:43]
	v_lshl_add_u64 v[160:161], v[224:225], 0, s[16:17]
	s_mov_b32 m0, s52
	s_nop 0
	global_load_lds_dwordx4 v[160:161], off
	v_lshl_add_u64 v[160:161], v[226:227], 0, s[16:17]
	s_mov_b32 m0, s53
	s_nop 0
	global_load_lds_dwordx4 v[160:161], off
	s_waitcnt vmcnt(8)
	s_waitcnt lgkmcnt(0)
	s_barrier
	s_setprio 0
	s_waitcnt lgkmcnt(0)
	v_mfma_f32_16x16x32_bf16 v[60:63], v[144:147], v[190:193], v[60:63]
	v_mfma_f32_16x16x32_bf16 v[56:59], v[166:169], v[190:193], v[56:59]
	v_mfma_f32_16x16x32_bf16 v[44:47], v[144:147], v[198:201], v[44:47]
	v_mfma_f32_16x16x32_bf16 v[40:43], v[166:169], v[198:201], v[40:43]
	v_mfma_f32_16x16x32_bf16 v[28:31], v[144:147], v[206:209], v[28:31]
	v_mfma_f32_16x16x32_bf16 v[24:27], v[166:169], v[206:209], v[24:27]
	v_mfma_f32_16x16x32_bf16 v[12:15], v[144:147], v[214:217], v[12:15]
	v_mfma_f32_16x16x32_bf16 v[8:11], v[166:169], v[214:217], v[8:11]
	v_mfma_f32_16x16x32_bf16 v[60:63], v[148:151], v[194:197], v[60:63]
	v_mfma_f32_16x16x32_bf16 v[56:59], v[170:173], v[194:197], v[56:59]
	v_mfma_f32_16x16x32_bf16 v[44:47], v[148:151], v[202:205], v[44:47]
	v_mfma_f32_16x16x32_bf16 v[40:43], v[170:173], v[202:205], v[40:43]
	v_mfma_f32_16x16x32_bf16 v[28:31], v[148:151], v[210:213], v[28:31]
	v_mfma_f32_16x16x32_bf16 v[24:27], v[170:173], v[210:213], v[24:27]
	v_mfma_f32_16x16x32_bf16 v[12:15], v[148:151], v[218:221], v[12:15]
	v_mfma_f32_16x16x32_bf16 v[8:11], v[170:173], v[218:221], v[8:11]
	v_mfma_f32_16x16x32_bf16 v[52:55], v[174:177], v[190:193], v[52:55]
	v_mfma_f32_16x16x32_bf16 v[48:51], v[182:185], v[190:193], v[48:51]
	v_mfma_f32_16x16x32_bf16 v[36:39], v[174:177], v[198:201], v[36:39]
	v_mfma_f32_16x16x32_bf16 v[32:35], v[182:185], v[198:201], v[32:35]
	v_mfma_f32_16x16x32_bf16 v[20:23], v[174:177], v[206:209], v[20:23]
	v_mfma_f32_16x16x32_bf16 v[16:19], v[182:185], v[206:209], v[16:19]
	v_mfma_f32_16x16x32_bf16 v[4:7], v[174:177], v[214:217], v[4:7]
	v_mfma_f32_16x16x32_bf16 v[0:3], v[182:185], v[214:217], v[0:3]
	v_mfma_f32_16x16x32_bf16 v[52:55], v[178:181], v[194:197], v[52:55]
	v_mfma_f32_16x16x32_bf16 v[48:51], v[186:189], v[194:197], v[48:51]
	v_mfma_f32_16x16x32_bf16 v[36:39], v[178:181], v[202:205], v[36:39]
	v_mfma_f32_16x16x32_bf16 v[32:35], v[186:189], v[202:205], v[32:35]
	v_mfma_f32_16x16x32_bf16 v[20:23], v[178:181], v[210:213], v[20:23]
	v_mfma_f32_16x16x32_bf16 v[16:19], v[186:189], v[210:213], v[16:19]
	v_mfma_f32_16x16x32_bf16 v[4:7], v[178:181], v[218:221], v[4:7]
	v_mfma_f32_16x16x32_bf16 v[0:3], v[186:189], v[218:221], v[0:3]
	s_setprio 1
	s_barrier
	s_add_i32 s58, s58, 2
	s_add_u32 s0, s0, 0x100
	s_addc_u32 s1, s1, 0
	s_add_u32 s31, s31, 0x100
	s_addc_u32 s34, s34, 0
	s_cmp_gt_u32 s58, 13
	s_cbranch_scc0 .LBB0_848
	s_and_b64 vcc, exec, s[18:19]
	s_cbranch_vccz .LBB0_851
	s_barrier

; #define PG8_STAGE(bufoff, gbase, voff) do { _Pragma("unroll") for (int _i = 0; _i < 2; ++_i) \
;         __builtin_amdgcn_global_load_lds((const unsigned*)((const char*)(gbase) + (voff)[_i]), (PG8_LAS unsigned*)(lds + (bufoff) + ldsw + _i * 8192), 16, 0, 0); } while (0)
; #define PG8_WAIT_V(n) asm volatile("s_waitcnt vmcnt(" #n ")" ::: "memory")
; #define PG8_BAR __builtin_amdgcn_s_barrier()
; template <class Epi, class Sched, bool ALIGN_EPI = false, bool SP2 = false>
; __device__ __forceinline__ void gemm_phase(PG8_LAS unsigned char* lds, const Gemm g, const Sched& S, const Epi& E) {
;     ...
;     const char* cA = (const char*)g.A + (size_t)cur.pm * tstepA + (size_t)cur.kz * kzb; const char* cB = (const char*)g.Bt + (size_t)cur.pn * tstepB + (size_t)cur.kz * kzb;
;     S.a_ready(cur);
;     if constexpr (SP2) {
;         PG8_STAGE(PG8_SB(0, 0), cB, voffB); PG8_STAGE(PG8_SB(0, 1), cB + hstepB, voffB); PG8_STAGE(PG8_SA(0, 0), cA, voffA); PG8_STAGE(PG8_SA(0, 1), cA + hstepA, voffA);
;         if (wr == 1) PG8_BAR;
;         PG8_WAIT_V(2); PG8_BAR;
;         PG8_STAGE(PG8_SB(1, 0), cB + kstep, voffB); PG8_STAGE(PG8_SA(1, 0), cA + kstep, voffA); PG8_STAGE(PG8_SB(1, 1), cB + hstepB + kstep, voffB);
;         PG8_WAIT_V(6); PG8_BAR;
.LBB0_917:
	s_lshl_b32 s16, s16, 5
	s_and_b32 s22, s16, 0x60
	s_mov_b64 s[16:17], 0x80
	s_add_i32 m0, s29, 0x18000
	v_lshl_add_u64 v[6:7], v[6:7], 0, s[16:17]
	s_lshl_b32 s19, s18, 13
	s_waitcnt vmcnt(2)
	s_barrier
	global_load_lds_dwordx4 v[6:7], off
	v_lshl_add_u64 v[2:3], v[2:3], 0, s[16:17]
	s_add_i32 m0, s29, 0x1a000
	s_add_i32 s35, s29, 0x8000
	s_add_i32 s51, s29, 0xa000
	global_load_lds_dwordx4 v[2:3], off
	v_lshl_add_u64 v[0:1], v[0:1], 0, s[16:17]
	s_mov_b32 m0, s35
	s_add_u32 s20, s54, 0x80080
	global_load_lds_dwordx4 v[0:1], off
	v_lshl_add_u64 v[0:1], v[4:5], 0, s[16:17]
	s_mov_b32 m0, s51
	s_addc_u32 s21, s55, 0
	global_load_lds_dwordx4 v[0:1], off
	s_add_i32 m0, s29, 0x1c000
	v_lshl_add_u64 v[0:1], s[20:21], 0, v[130:131]
	global_load_lds_dwordx4 v[0:1], off
	v_lshl_add_u64 v[0:1], s[20:21], 0, v[134:135]
	s_add_i32 m0, s29, 0x1e000
	v_lshlrev_b32_e32 v2, 12, v10
	global_load_lds_dwordx4 v[0:1], off
	v_lshlrev_b32_e32 v1, 2, v146
	v_lshl_or_b32 v0, v146, 6, v148
	v_and_b32_e32 v1, 32, v1
	v_bitop3_b32 v0, v0, s19, v1 bitop3:0xde
	v_lshlrev_b32_e32 v1, 9, v162
	v_and_b32_e32 v1, 0x70000, v1
	v_or3_b32 v1, v8, v1, v2
	v_add_u32_e32 v136, v1, v9
	v_lshlrev_b32_e32 v1, 5, v11
	s_waitcnt vmcnt(0)
	s_cmpk_lt_u32 s5, 0x100
	v_and_b32_e32 v1, 0xf0000, v1
	v_lshl_or_b32 v150, s18, 6, v146
	v_lshl_or_b32 v151, s22, 7, v149
	s_cselect_b64 s[18:19], -1, 0
	v_or3_b32 v1, v8, v1, v2
	s_add_i32 s58, 0, 0x10000
	s_add_i32 s59, 0, 0x14000
	s_sext_i32_i8 s64, s4
	v_or_b32_e32 v152, s22, v147
	v_mov_b32_e32 v137, v131
	v_add_u32_e32 v138, v1, v9
	v_mov_b32_e32 v139, v131
	v_mov_b64_e32 v[140:141], 0x400
	v_mov_b64_e32 v[142:143], 0x3ff
	v_add_u32_e32 v153, s58, v151
	v_add_u32_e32 v154, s59, v151
	v_add_u32_e32 v155, 0, v0
	s_mov_b32 s60, 0x80000
	s_mov_b64 s[20:21], 0x90000
	s_mov_b32 s61, 0x90000
	s_mov_b64 s[22:23], 0xa0000
	s_mov_b32 s62, 0xa0000
	s_mov_b64 s[40:41], 0xb0000
	s_mov_b32 s63, 0xb0000
	s_barrier
	s_branch .LBB0_920

; template <class Epi, class Sched, bool ALIGN_EPI = false, bool SP2 = false>
; __device__ __forceinline__ void gemm_phase(PG8_LAS unsigned char* lds, const Gemm g, const Sched& S, const Epi& E) {
;     ...
;         const bool has_next = S.next(ui + 1, nxt);
;         const char* nA = has_next ? (const char*)g.A + (size_t)nxt.pm * tstepA + (size_t)nxt.kz * kzb : cA; const char* nB = has_next ? (const char*)g.Bt + (size_t)nxt.pn * tstepB + (size_t)nxt.kz * kzb : cB;
;     ...
; #pragma unroll
;         for (int a = 0; a < 2; ++a)
; #pragma unroll
;             for (int b = 0; b < 2; ++b)
; #pragma unroll
;                 for (int m = 0; m < 4; ++m)
; #pragma unroll
;                     for (int n = 0; n < 2; ++n) acc[a][b][m][n] = (f32x4){0.f, 0.f, 0.f, 0.f};
;         cur = nxt; cA = nA; cB = nB; ++ui;
.LBB0_926:
	s_ashr_i32 s45, s44, 31
	s_lshl_b64 s[46:47], s[44:45], 20
	v_readlane_b32 s48, v240, 26
	v_readlane_b32 s49, v240, 27
	s_add_u32 s46, s48, s46
	s_addc_u32 s47, s49, s47
	s_and_b64 s[48:49], s[4:5], exec
	s_cselect_b32 s45, s47, s53
	s_cselect_b32 s65, s46, s52
	s_ashr_i32 s43, s42, 31
	s_lshl_b64 s[48:49], s[42:43], 20
	v_readlane_b32 s56, v240, 16
	v_readlane_b32 s57, v240, 17
	s_add_u32 s48, s56, s48
	s_addc_u32 s49, s57, s49
	s_and_b64 s[56:57], s[4:5], exec
	s_cselect_b32 s43, s49, s55
	s_cselect_b32 s68, s48, s54
	s_add_u32 s52, s52, 0x80080
	s_addc_u32 s53, s53, 0
	s_add_u32 s69, s54, 0x100
	v_mov_b64_e32 v[0:1], 0
	s_addc_u32 s70, s55, 0
	s_mov_b32 s71, -2
	v_mov_b64_e32 v[2:3], 0
	v_mov_b64_e32 v[4:5], 0
	v_mov_b64_e32 v[6:7], 0
	v_mov_b64_e32 v[8:9], 0
	v_mov_b64_e32 v[10:11], 0
	v_mov_b64_e32 v[16:17], 0
	v_mov_b64_e32 v[18:19], 0
	v_mov_b64_e32 v[24:25], 0
	v_mov_b64_e32 v[26:27], 0
	v_mov_b64_e32 v[32:33], 0
	v_mov_b64_e32 v[34:35], 0
	v_mov_b64_e32 v[40:41], 0
	v_mov_b64_e32 v[42:43], 0
	v_mov_b64_e32 v[48:49], 0
	v_mov_b64_e32 v[50:51], 0
	v_mov_b64_e32 v[12:13], 0
	v_mov_b64_e32 v[14:15], 0
	v_mov_b64_e32 v[20:21], 0
	v_mov_b64_e32 v[22:23], 0
	v_mov_b64_e32 v[28:29], 0
	v_mov_b64_e32 v[30:31], 0
	v_mov_b64_e32 v[36:37], 0
	v_mov_b64_e32 v[38:39], 0
	v_mov_b64_e32 v[44:45], 0
	v_mov_b64_e32 v[46:47], 0
	v_mov_b64_e32 v[52:53], 0
	v_mov_b64_e32 v[54:55], 0
	v_mov_b64_e32 v[56:57], 0
	v_mov_b64_e32 v[58:59], 0
	v_mov_b64_e32 v[60:61], 0
	v_mov_b64_e32 v[62:63], 0
	v_mov_b64_e32 v[64:65], 0
	v_mov_b64_e32 v[66:67], 0
	v_mov_b64_e32 v[68:69], 0
	v_mov_b64_e32 v[70:71], 0
	v_mov_b64_e32 v[72:73], 0
	v_mov_b64_e32 v[74:75], 0
	v_mov_b64_e32 v[80:81], 0
	v_mov_b64_e32 v[82:83], 0
	v_mov_b64_e32 v[88:89], 0
	v_mov_b64_e32 v[90:91], 0
	v_mov_b64_e32 v[96:97], 0
	v_mov_b64_e32 v[98:99], 0
	v_mov_b64_e32 v[104:105], 0
	v_mov_b64_e32 v[106:107], 0
	v_mov_b64_e32 v[112:113], 0
	v_mov_b64_e32 v[114:115], 0
	v_mov_b64_e32 v[76:77], 0
	v_mov_b64_e32 v[78:79], 0
	v_mov_b64_e32 v[84:85], 0
	v_mov_b64_e32 v[86:87], 0
	v_mov_b64_e32 v[92:93], 0
	v_mov_b64_e32 v[94:95], 0
	v_mov_b64_e32 v[100:101], 0
	v_mov_b64_e32 v[102:103], 0
	v_mov_b64_e32 v[108:109], 0
	v_mov_b64_e32 v[110:111], 0
	v_mov_b64_e32 v[116:117], 0
	v_mov_b64_e32 v[118:119], 0
	v_mov_b64_e32 v[120:121], 0
	v_mov_b64_e32 v[122:123], 0
	v_mov_b64_e32 v[124:125], 0
	v_mov_b64_e32 v[126:127], 0
	s_branch .LBB0_927

; #define PG8_STAGE(bufoff, gbase, voff) do { _Pragma("unroll") for (int _i = 0; _i < 2; ++_i) \
;         __builtin_amdgcn_global_load_lds((const unsigned*)((const char*)(gbase) + (voff)[_i]), (PG8_LAS unsigned*)(lds + (bufoff) + ldsw + _i * 8192), 16, 0, 0); } while (0)
; #define PG8_LDA(dst, b, h) do { _Pragma("unroll") for (int m = 0; m < 4; ++m) _Pragma("unroll") for (int k = 0; k < 2; ++k) dst[m][k] = *(const PG8_LAS bf16x8*)(lds + PG8_SA(b, h) + aoff + m * 2048 + k * 1024); } while (0)
; #define PG8_LDB(dst, b, h) do { _Pragma("unroll") for (int n = 0; n < 2; ++n) _Pragma("unroll") for (int k = 0; k < 2; ++k) dst[n][k] = *(const PG8_LAS bf16x8*)(lds + PG8_SB(b, h) + boff + n * 2048 + k * 1024); } while (0)
; #define PG8_MMA(ai, bj, At, Bt) do { __builtin_amdgcn_s_setprio(1); _Pragma("unroll") for (int m = 0; m < 4; ++m) _Pragma("unroll") for (int n = 0; n < 2; ++n) _Pragma("unroll") for (int k = 0; k < 2; ++k) \
;         acc[ai][bj][m][n] = __builtin_amdgcn_mfma_f32_16x16x32_bf16(Bt[n][k], At[m][k], acc[ai][bj][m][n], 0, 0, 0); __builtin_amdgcn_s_setprio(0); } while (0)
; #define PG8_WAIT_V(n) asm volatile("s_waitcnt vmcnt(" #n ")" ::: "memory")
; #define PG8_WAIT_L(n) asm volatile("s_waitcnt lgkmcnt(" #n ")" ::: "memory")
; #define PG8_BAR __builtin_amdgcn_s_barrier()
; #define PG8_SCHED __builtin_amdgcn_sched_barrier(0)
; template <class Epi, class Sched, bool ALIGN_EPI = false, bool SP2 = false>
; __device__ __forceinline__ void gemm_phase(PG8_LAS unsigned char* lds, const Gemm g, const Sched& S, const Epi& E) {
;     ...
;             PG8_LDB(B0, 0, 0); PG8_LDB(B1, 0, 1); PG8_SCHED; PG8_LDA(At, 0, 0); PG8_STAGE(PG8_SA(1, 1), a1 + hstepA, voffA);
;             PG8_WAIT_V(8); PG8_WAIT_L(0); PG8_BAR; PG8_MMA(0, 0, At, B0); PG8_MMA(0, 1, At, B1); PG8_BAR; PG8_SCHED;
;             PG8_LDA(At, 0, 1); PG8_STAGE(PG8_SB(0, 0), b2, voffB); PG8_STAGE(PG8_SB(0, 1), b2 + hstepB, voffB); PG8_STAGE(PG8_SA(0, 0), a2, voffA);
.LBB0_927:
	ds_read_b128 v[156:159], v153
	ds_read_b128 v[166:169], v153 offset:1024
	ds_read_b128 v[170:173], v153 offset:2048
	ds_read_b128 v[174:177], v153 offset:3072
	ds_read_b128 v[178:181], v154
	ds_read_b128 v[182:185], v154 offset:1024
	ds_read_b128 v[186:189], v154 offset:2048
	ds_read_b128 v[190:193], v154 offset:3072
	s_add_u32 s54, s52, 0xfff80080
	s_addc_u32 s55, s53, -1
	s_cmp_eq_u32 s71, 28
	s_cselect_b32 s57, s45, s55
	s_cselect_b32 s56, s65, s54
	s_cselect_b32 s55, s43, s70
	s_cselect_b32 s54, s68, s69
	s_add_i32 m0, s29, 0xc000
	ds_read_b128 v[194:197], v155
	ds_read_b128 v[198:201], v155 offset:1024
	ds_read_b128 v[202:205], v155 offset:2048
	ds_read_b128 v[206:209], v155 offset:3072
	ds_read_b128 v[210:213], v155 offset:4096
	ds_read_b128 v[214:217], v155 offset:5120
	ds_read_b128 v[218:221], v155 offset:6144
	ds_read_b128 v[222:225], v155 offset:7168
	global_load_lds_dwordx4 v136, s[52:53]
	s_add_i32 m0, s29, 0xe000
	s_nop 0
	global_load_lds_dwordx4 v138, s[52:53]
	s_cmp_eq_u32 s71, -2
	s_cbranch_scc1 .Lrx4_A
	s_waitcnt vmcnt(8)
.Lrx4_A_back:
	s_waitcnt lgkmcnt(0)
	s_barrier
	s_setprio 0
	s_waitcnt lgkmcnt(0)
	v_mfma_f32_16x16x32_bf16 v[124:127], v[156:159], v[194:197], v[124:127]
	v_mfma_f32_16x16x32_bf16 v[120:123], v[170:173], v[194:197], v[120:123]
	v_mfma_f32_16x16x32_bf16 v[116:119], v[156:159], v[202:205], v[116:119]
	v_mfma_f32_16x16x32_bf16 v[108:111], v[170:173], v[202:205], v[108:111]
	v_mfma_f32_16x16x32_bf16 v[100:103], v[156:159], v[210:213], v[100:103]
	v_mfma_f32_16x16x32_bf16 v[92:95], v[170:173], v[210:213], v[92:95]
	v_mfma_f32_16x16x32_bf16 v[84:87], v[156:159], v[218:221], v[84:87]
	v_mfma_f32_16x16x32_bf16 v[76:79], v[170:173], v[218:221], v[76:79]
	v_mfma_f32_16x16x32_bf16 v[124:127], v[166:169], v[198:201], v[124:127]
	v_mfma_f32_16x16x32_bf16 v[120:123], v[174:177], v[198:201], v[120:123]
	v_mfma_f32_16x16x32_bf16 v[116:119], v[166:169], v[206:209], v[116:119]
	v_mfma_f32_16x16x32_bf16 v[108:111], v[174:177], v[206:209], v[108:111]
	v_mfma_f32_16x16x32_bf16 v[100:103], v[166:169], v[214:217], v[100:103]
	v_mfma_f32_16x16x32_bf16 v[92:95], v[174:177], v[214:217], v[92:95]
	v_mfma_f32_16x16x32_bf16 v[84:87], v[166:169], v[222:225], v[84:87]
	v_mfma_f32_16x16x32_bf16 v[76:79], v[174:177], v[222:225], v[76:79]
	v_mfma_f32_16x16x32_bf16 v[112:115], v[178:181], v[194:197], v[112:115]
	v_mfma_f32_16x16x32_bf16 v[104:107], v[186:189], v[194:197], v[104:107]
	v_mfma_f32_16x16x32_bf16 v[96:99], v[178:181], v[202:205], v[96:99]
	v_mfma_f32_16x16x32_bf16 v[88:91], v[186:189], v[202:205], v[88:91]
	v_mfma_f32_16x16x32_bf16 v[80:83], v[178:181], v[210:213], v[80:83]
	v_mfma_f32_16x16x32_bf16 v[72:75], v[186:189], v[210:213], v[72:75]
	v_mfma_f32_16x16x32_bf16 v[68:71], v[178:181], v[218:221], v[68:71]
	v_mfma_f32_16x16x32_bf16 v[64:67], v[186:189], v[218:221], v[64:67]
	v_mfma_f32_16x16x32_bf16 v[112:115], v[182:185], v[198:201], v[112:115]
	v_mfma_f32_16x16x32_bf16 v[104:107], v[190:193], v[198:201], v[104:107]
	v_mfma_f32_16x16x32_bf16 v[96:99], v[182:185], v[206:209], v[96:99]
	v_mfma_f32_16x16x32_bf16 v[88:91], v[190:193], v[206:209], v[88:91]
	v_mfma_f32_16x16x32_bf16 v[80:83], v[182:185], v[214:217], v[80:83]
	v_mfma_f32_16x16x32_bf16 v[72:75], v[190:193], v[214:217], v[72:75]
	v_mfma_f32_16x16x32_bf16 v[68:71], v[182:185], v[222:225], v[68:71]
	v_mfma_f32_16x16x32_bf16 v[64:67], v[190:193], v[222:225], v[64:67]
	s_setprio 1
	s_barrier
	s_add_i32 s72, s58, s28
	v_lshl_add_u64 v[144:145], s[54:55], 0, v[130:131]
	s_mov_b32 m0, s72
	ds_read_b128 v[194:197], v155 offset:16384
	ds_read_b128 v[198:201], v155 offset:17408
	ds_read_b128 v[202:205], v155 offset:18432
	ds_read_b128 v[206:209], v155 offset:19456
	ds_read_b128 v[210:213], v155 offset:20480
	ds_read_b128 v[214:217], v155 offset:21504
	ds_read_b128 v[218:221], v155 offset:22528
	ds_read_b128 v[222:225], v155 offset:23552
	global_load_lds_dwordx4 v130, s[54:55]
	s_add_i32 m0, s72, 0x2000
	s_add_u32 s72, s54, 0x80000
	v_lshl_add_u64 v[160:161], s[54:55], 0, v[134:135]
	s_addc_u32 s73, s55, 0
	s_add_i32 s74, s59, s28
	global_load_lds_dwordx4 v134, s[54:55]
	s_mov_b32 m0, s74
	v_lshl_add_u64 v[228:229], s[56:57], 0, v[132:133]
	global_load_lds_dwordx4 v130, s[72:73]
	s_add_i32 m0, s74, 0x2000
	s_nop 0
	global_load_lds_dwordx4 v134, s[72:73]
	v_lshl_add_u64 v[226:227], s[56:57], 0, v[128:129]
	s_mov_b32 m0, s29
	s_nop 0
	global_load_lds_dwordx4 v128, s[56:57]
	s_mov_b32 m0, s30
	s_nop 0
	global_load_lds_dwordx4 v132, s[56:57]
	s_cmp_eq_u32 s71, -2
	s_cbranch_scc1 .Lrx4_B
	s_waitcnt vmcnt(8)
; #define PG8_STAGE(bufoff, gbase, voff) do { _Pragma("unroll") for (int _i = 0; _i < 2; ++_i) \
;         __builtin_amdgcn_global_load_lds((const unsigned*)((const char*)(gbase) + (voff)[_i]), (PG8_LAS unsigned*)(lds + (bufoff) + ldsw + _i * 8192), 16, 0, 0); } while (0)
; #define PG8_LDA(dst, b, h) do { _Pragma("unroll") for (int m = 0; m < 4; ++m) _Pragma("unroll") for (int k = 0; k < 2; ++k) dst[m][k] = *(const PG8_LAS bf16x8*)(lds + PG8_SA(b, h) + aoff + m * 2048 + k * 1024); } while (0)
; #define PG8_LDB(dst, b, h) do { _Pragma("unroll") for (int n = 0; n < 2; ++n) _Pragma("unroll") for (int k = 0; k < 2; ++k) dst[n][k] = *(const PG8_LAS bf16x8*)(lds + PG8_SB(b, h) + boff + n * 2048 + k * 1024); } while (0)
; #define PG8_MMA(ai, bj, At, Bt) do { __builtin_amdgcn_s_setprio(1); _Pragma("unroll") for (int m = 0; m < 4; ++m) _Pragma("unroll") for (int n = 0; n < 2; ++n) _Pragma("unroll") for (int k = 0; k < 2; ++k) \
;         acc[ai][bj][m][n] = __builtin_amdgcn_mfma_f32_16x16x32_bf16(Bt[n][k], At[m][k], acc[ai][bj][m][n], 0, 0, 0); __builtin_amdgcn_s_setprio(0); } while (0)
; #define PG8_WAIT_V(n) asm volatile("s_waitcnt vmcnt(" #n ")" ::: "memory")
; #define PG8_WAIT_L(n) asm volatile("s_waitcnt lgkmcnt(" #n ")" ::: "memory")
; #define PG8_BAR __builtin_amdgcn_s_barrier()
; #define PG8_SCHED __builtin_amdgcn_sched_barrier(0)
; template <class Epi, class Sched, bool ALIGN_EPI = false, bool SP2 = false>
; __device__ __forceinline__ void gemm_phase(PG8_LAS unsigned char* lds, const Gemm g, const Sched& S, const Epi& E) {
;     ...
;             PG8_WAIT_V(8); PG8_WAIT_L(0); PG8_BAR; PG8_MMA(1, 0, At, B0); PG8_MMA(1, 1, At, B1); PG8_BAR; PG8_SCHED;
;             PG8_LDB(B0, 1, 0); PG8_LDB(B1, 1, 1); PG8_SCHED; PG8_LDA(At, 1, 0); PG8_STAGE(PG8_SA(0, 1), a2 + hstepA, voffA);
;             PG8_WAIT_V(8); PG8_WAIT_L(0); PG8_BAR; PG8_MMA(0, 0, At, B0); PG8_MMA(0, 1, At, B1); PG8_BAR; PG8_SCHED;
.Lrx4_B_back:
	s_waitcnt lgkmcnt(0)
	s_barrier
	s_setprio 0
	s_waitcnt lgkmcnt(0)
	v_mfma_f32_16x16x32_bf16 v[60:63], v[156:159], v[194:197], v[60:63]
	v_mfma_f32_16x16x32_bf16 v[56:59], v[170:173], v[194:197], v[56:59]
	v_mfma_f32_16x16x32_bf16 v[52:55], v[156:159], v[202:205], v[52:55]
	v_mfma_f32_16x16x32_bf16 v[44:47], v[170:173], v[202:205], v[44:47]
	v_mfma_f32_16x16x32_bf16 v[36:39], v[156:159], v[210:213], v[36:39]
	v_mfma_f32_16x16x32_bf16 v[28:31], v[170:173], v[210:213], v[28:31]
	v_mfma_f32_16x16x32_bf16 v[20:23], v[156:159], v[218:221], v[20:23]
	v_mfma_f32_16x16x32_bf16 v[12:15], v[170:173], v[218:221], v[12:15]
	v_mfma_f32_16x16x32_bf16 v[60:63], v[166:169], v[198:201], v[60:63]
	v_mfma_f32_16x16x32_bf16 v[56:59], v[174:177], v[198:201], v[56:59]
	v_mfma_f32_16x16x32_bf16 v[52:55], v[166:169], v[206:209], v[52:55]
	v_mfma_f32_16x16x32_bf16 v[44:47], v[174:177], v[206:209], v[44:47]
	v_mfma_f32_16x16x32_bf16 v[36:39], v[166:169], v[214:217], v[36:39]
	v_mfma_f32_16x16x32_bf16 v[28:31], v[174:177], v[214:217], v[28:31]
	v_mfma_f32_16x16x32_bf16 v[20:23], v[166:169], v[222:225], v[20:23]
	v_mfma_f32_16x16x32_bf16 v[12:15], v[174:177], v[222:225], v[12:15]
	v_mfma_f32_16x16x32_bf16 v[48:51], v[178:181], v[194:197], v[48:51]
	v_mfma_f32_16x16x32_bf16 v[40:43], v[186:189], v[194:197], v[40:43]
	v_mfma_f32_16x16x32_bf16 v[32:35], v[178:181], v[202:205], v[32:35]
	v_mfma_f32_16x16x32_bf16 v[24:27], v[186:189], v[202:205], v[24:27]
	v_mfma_f32_16x16x32_bf16 v[16:19], v[178:181], v[210:213], v[16:19]
	v_mfma_f32_16x16x32_bf16 v[8:11], v[186:189], v[210:213], v[8:11]
	v_mfma_f32_16x16x32_bf16 v[4:7], v[178:181], v[218:221], v[4:7]
	v_mfma_f32_16x16x32_bf16 v[0:3], v[186:189], v[218:221], v[0:3]
	v_mfma_f32_16x16x32_bf16 v[48:51], v[182:185], v[198:201], v[48:51]
	v_mfma_f32_16x16x32_bf16 v[40:43], v[190:193], v[198:201], v[40:43]
	v_mfma_f32_16x16x32_bf16 v[32:35], v[182:185], v[206:209], v[32:35]
	v_mfma_f32_16x16x32_bf16 v[24:27], v[190:193], v[206:209], v[24:27]
	v_mfma_f32_16x16x32_bf16 v[16:19], v[182:185], v[214:217], v[16:19]
	v_mfma_f32_16x16x32_bf16 v[8:11], v[190:193], v[214:217], v[8:11]
	v_mfma_f32_16x16x32_bf16 v[4:7], v[182:185], v[222:225], v[4:7]
	v_mfma_f32_16x16x32_bf16 v[0:3], v[190:193], v[222:225], v[0:3]
	s_setprio 1
	s_barrier
	s_add_i32 s72, 0, 0x18000
	v_add_u32_e32 v163, s72, v151
	s_add_i32 s73, 0, 0x1c000
	ds_read_b128 v[156:159], v163
	ds_read_b128 v[166:169], v163 offset:1024
	ds_read_b128 v[170:173], v163 offset:2048
	ds_read_b128 v[174:177], v163 offset:3072
	v_add_u32_e32 v163, s73, v151
	ds_read_b128 v[178:181], v163
	ds_read_b128 v[182:185], v163 offset:1024
	ds_read_b128 v[186:189], v163 offset:2048
	ds_read_b128 v[190:193], v163 offset:3072
	s_add_u32 s56, s56, 0x80000
	s_addc_u32 s57, s57, 0
	s_mov_b32 m0, s31
	ds_read_b128 v[194:197], v155 offset:32768
	ds_read_b128 v[198:201], v155 offset:33792
	ds_read_b128 v[202:205], v155 offset:34816
	ds_read_b128 v[206:209], v155 offset:35840
	ds_read_b128 v[210:213], v155 offset:36864
	ds_read_b128 v[214:217], v155 offset:37888
	ds_read_b128 v[218:221], v155 offset:38912
	ds_read_b128 v[222:225], v155 offset:39936
	global_load_lds_dwordx4 v128, s[56:57]
	s_mov_b32 m0, s33
	s_nop 0
	global_load_lds_dwordx4 v132, s[56:57]
	s_waitcnt vmcnt(8)
	s_waitcnt lgkmcnt(0)
	s_barrier
	s_setprio 0
	s_waitcnt lgkmcnt(0)
	v_mfma_f32_16x16x32_bf16 v[124:127], v[156:159], v[194:197], v[124:127]
	v_mfma_f32_16x16x32_bf16 v[120:123], v[170:173], v[194:197], v[120:123]
	v_mfma_f32_16x16x32_bf16 v[116:119], v[156:159], v[202:205], v[116:119]
	v_mfma_f32_16x16x32_bf16 v[108:111], v[170:173], v[202:205], v[108:111]
	v_mfma_f32_16x16x32_bf16 v[100:103], v[156:159], v[210:213], v[100:103]
	v_mfma_f32_16x16x32_bf16 v[92:95], v[170:173], v[210:213], v[92:95]
	v_mfma_f32_16x16x32_bf16 v[84:87], v[156:159], v[218:221], v[84:87]
	v_mfma_f32_16x16x32_bf16 v[76:79], v[170:173], v[218:221], v[76:79]
	v_mfma_f32_16x16x32_bf16 v[124:127], v[166:169], v[198:201], v[124:127]
	v_mfma_f32_16x16x32_bf16 v[120:123], v[174:177], v[198:201], v[120:123]
	v_mfma_f32_16x16x32_bf16 v[116:119], v[166:169], v[206:209], v[116:119]
	v_mfma_f32_16x16x32_bf16 v[108:111], v[174:177], v[206:209], v[108:111]
	v_mfma_f32_16x16x32_bf16 v[100:103], v[166:169], v[214:217], v[100:103]
	v_mfma_f32_16x16x32_bf16 v[92:95], v[174:177], v[214:217], v[92:95]
	v_mfma_f32_16x16x32_bf16 v[84:87], v[166:169], v[222:225], v[84:87]
	v_mfma_f32_16x16x32_bf16 v[76:79], v[174:177], v[222:225], v[76:79]
	v_mfma_f32_16x16x32_bf16 v[112:115], v[178:181], v[194:197], v[112:115]
	v_mfma_f32_16x16x32_bf16 v[104:107], v[186:189], v[194:197], v[104:107]
	v_mfma_f32_16x16x32_bf16 v[96:99], v[178:181], v[202:205], v[96:99]
	v_mfma_f32_16x16x32_bf16 v[88:91], v[186:189], v[202:205], v[88:91]
	v_mfma_f32_16x16x32_bf16 v[80:83], v[178:181], v[210:213], v[80:83]
	v_mfma_f32_16x16x32_bf16 v[72:75], v[186:189], v[210:213], v[72:75]
	v_mfma_f32_16x16x32_bf16 v[68:71], v[178:181], v[218:221], v[68:71]
	v_mfma_f32_16x16x32_bf16 v[64:67], v[186:189], v[218:221], v[64:67]
	v_mfma_f32_16x16x32_bf16 v[112:115], v[182:185], v[198:201], v[112:115]
	v_mfma_f32_16x16x32_bf16 v[104:107], v[190:193], v[198:201], v[104:107]
	v_mfma_f32_16x16x32_bf16 v[96:99], v[182:185], v[206:209], v[96:99]
	v_mfma_f32_16x16x32_bf16 v[88:91], v[190:193], v[206:209], v[88:91]
	v_mfma_f32_16x16x32_bf16 v[80:83], v[182:185], v[214:217], v[80:83]
	v_mfma_f32_16x16x32_bf16 v[72:75], v[190:193], v[214:217], v[72:75]
	v_mfma_f32_16x16x32_bf16 v[68:71], v[182:185], v[222:225], v[68:71]
	v_mfma_f32_16x16x32_bf16 v[64:67], v[190:193], v[222:225], v[64:67]
	s_setprio 1
	s_barrier
; #define PG8_STAGE(bufoff, gbase, voff) do { _Pragma("unroll") for (int _i = 0; _i < 2; ++_i) \
;         __builtin_amdgcn_global_load_lds((const unsigned*)((const char*)(gbase) + (voff)[_i]), (PG8_LAS unsigned*)(lds + (bufoff) + ldsw + _i * 8192), 16, 0, 0); } while (0)
; #define PG8_LDA(dst, b, h) do { _Pragma("unroll") for (int m = 0; m < 4; ++m) _Pragma("unroll") for (int k = 0; k < 2; ++k) dst[m][k] = *(const PG8_LAS bf16x8*)(lds + PG8_SA(b, h) + aoff + m * 2048 + k * 1024); } while (0)
; #define PG8_MMA(ai, bj, At, Bt) do { __builtin_amdgcn_s_setprio(1); _Pragma("unroll") for (int m = 0; m < 4; ++m) _Pragma("unroll") for (int n = 0; n < 2; ++n) _Pragma("unroll") for (int k = 0; k < 2; ++k) \
;         acc[ai][bj][m][n] = __builtin_amdgcn_mfma_f32_16x16x32_bf16(Bt[n][k], At[m][k], acc[ai][bj][m][n], 0, 0, 0); __builtin_amdgcn_s_setprio(0); } while (0)
; #define PG8_WAIT_V(n) asm volatile("s_waitcnt vmcnt(" #n ")" ::: "memory")
; #define PG8_WAIT_L(n) asm volatile("s_waitcnt lgkmcnt(" #n ")" ::: "memory")
; #define PG8_BAR __builtin_amdgcn_s_barrier()
; #define PG8_SCHED __builtin_amdgcn_sched_barrier(0)
; template <class Epi, class Sched, bool ALIGN_EPI = false, bool SP2 = false>
; __device__ __forceinline__ void gemm_phase(PG8_LAS unsigned char* lds, const Gemm g, const Sched& S, const Epi& E) {
;     ...
;             PG8_LDA(At, 1, 1); PG8_STAGE(PG8_SB(1, 0), b3, voffB); PG8_STAGE(PG8_SB(1, 1), b3 + hstepB, voffB); PG8_STAGE(PG8_SA(1, 0), a3, voffA);
;             PG8_WAIT_V(8); PG8_WAIT_L(0); PG8_BAR; PG8_MMA(1, 0, At, B0); PG8_MMA(1, 1, At, B1); PG8_BAR; PG8_SCHED;
	s_add_i32 s56, s72, s28
	v_lshl_add_u64 v[144:145], v[144:145], 0, s[16:17]
	s_mov_b32 m0, s56
	ds_read_b128 v[194:197], v155 offset:49152
	ds_read_b128 v[198:201], v155 offset:50176
	ds_read_b128 v[202:205], v155 offset:51200
	ds_read_b128 v[206:209], v155 offset:52224
	ds_read_b128 v[210:213], v155 offset:53248
	ds_read_b128 v[214:217], v155 offset:54272
	ds_read_b128 v[218:221], v155 offset:55296
	ds_read_b128 v[222:225], v155 offset:56320
	global_load_lds_dwordx4 v[144:145], off
	s_add_i32 m0, s56, 0x2000
	s_add_u32 s54, s54, 0x80080
	v_lshl_add_u64 v[144:145], v[160:161], 0, s[16:17]
	s_addc_u32 s55, s55, 0
	s_add_i32 s56, s73, s28
	global_load_lds_dwordx4 v[144:145], off
	s_mov_b32 m0, s56
	s_nop 0
	global_load_lds_dwordx4 v130, s[54:55]
	s_add_i32 m0, s56, 0x2000
	s_nop 0
	global_load_lds_dwordx4 v134, s[54:55]
	v_lshl_add_u64 v[144:145], v[226:227], 0, s[16:17]
	s_mov_b32 m0, s35
	s_nop 0
	global_load_lds_dwordx4 v[144:145], off
	v_lshl_add_u64 v[144:145], v[228:229], 0, s[16:17]
	s_mov_b32 m0, s51
	s_nop 0
	global_load_lds_dwordx4 v[144:145], off
	s_waitcnt vmcnt(8)
	s_waitcnt lgkmcnt(0)
	s_barrier
	s_setprio 0
	s_waitcnt lgkmcnt(0)
	v_mfma_f32_16x16x32_bf16 v[60:63], v[156:159], v[194:197], v[60:63]
	v_mfma_f32_16x16x32_bf16 v[56:59], v[170:173], v[194:197], v[56:59]
	v_mfma_f32_16x16x32_bf16 v[52:55], v[156:159], v[202:205], v[52:55]
	v_mfma_f32_16x16x32_bf16 v[44:47], v[170:173], v[202:205], v[44:47]
	v_mfma_f32_16x16x32_bf16 v[36:39], v[156:159], v[210:213], v[36:39]
	v_mfma_f32_16x16x32_bf16 v[28:31], v[170:173], v[210:213], v[28:31]
	v_mfma_f32_16x16x32_bf16 v[20:23], v[156:159], v[218:221], v[20:23]
	v_mfma_f32_16x16x32_bf16 v[12:15], v[170:173], v[218:221], v[12:15]
	v_mfma_f32_16x16x32_bf16 v[60:63], v[166:169], v[198:201], v[60:63]
	v_mfma_f32_16x16x32_bf16 v[56:59], v[174:177], v[198:201], v[56:59]
	v_mfma_f32_16x16x32_bf16 v[52:55], v[166:169], v[206:209], v[52:55]
	v_mfma_f32_16x16x32_bf16 v[44:47], v[174:177], v[206:209], v[44:47]
	v_mfma_f32_16x16x32_bf16 v[36:39], v[166:169], v[214:217], v[36:39]
	v_mfma_f32_16x16x32_bf16 v[28:31], v[174:177], v[214:217], v[28:31]
	v_mfma_f32_16x16x32_bf16 v[20:23], v[166:169], v[222:225], v[20:23]
	v_mfma_f32_16x16x32_bf16 v[12:15], v[174:177], v[222:225], v[12:15]
	v_mfma_f32_16x16x32_bf16 v[48:51], v[178:181], v[194:197], v[48:51]
	v_mfma_f32_16x16x32_bf16 v[40:43], v[186:189], v[194:197], v[40:43]
	v_mfma_f32_16x16x32_bf16 v[32:35], v[178:181], v[202:205], v[32:35]
	v_mfma_f32_16x16x32_bf16 v[24:27], v[186:189], v[202:205], v[24:27]
	v_mfma_f32_16x16x32_bf16 v[16:19], v[178:181], v[210:213], v[16:19]
	v_mfma_f32_16x16x32_bf16 v[8:11], v[186:189], v[210:213], v[8:11]
	v_mfma_f32_16x16x32_bf16 v[4:7], v[178:181], v[218:221], v[4:7]
	v_mfma_f32_16x16x32_bf16 v[0:3], v[186:189], v[218:221], v[0:3]
	v_mfma_f32_16x16x32_bf16 v[48:51], v[182:185], v[198:201], v[48:51]
	v_mfma_f32_16x16x32_bf16 v[40:43], v[190:193], v[198:201], v[40:43]
	v_mfma_f32_16x16x32_bf16 v[32:35], v[182:185], v[206:209], v[32:35]
	v_mfma_f32_16x16x32_bf16 v[24:27], v[190:193], v[206:209], v[24:27]
	v_mfma_f32_16x16x32_bf16 v[16:19], v[182:185], v[214:217], v[16:19]
	v_mfma_f32_16x16x32_bf16 v[8:11], v[190:193], v[214:217], v[8:11]
	v_mfma_f32_16x16x32_bf16 v[4:7], v[182:185], v[222:225], v[4:7]
	v_mfma_f32_16x16x32_bf16 v[0:3], v[190:193], v[222:225], v[0:3]
	s_setprio 1
	s_barrier
	s_add_i32 s71, s71, 2
	s_add_u32 s52, s52, 0x100
	s_addc_u32 s53, s53, 0
	s_add_u32 s69, s69, 0x100
	s_addc_u32 s70, s70, 0
	s_cmp_gt_u32 s71, 29
	s_cbranch_scc0 .LBB0_927
	s_and_b64 vcc, exec, s[18:19]
	s_cbranch_vccz .LBB0_930
	s_barrier

; #define PG8_STAGE(bufoff, gbase, voff) do { _Pragma("unroll") for (int _i = 0; _i < 2; ++_i) \
;         __builtin_amdgcn_global_load_lds((const unsigned*)((const char*)(gbase) + (voff)[_i]), (PG8_LAS unsigned*)(lds + (bufoff) + ldsw + _i * 8192), 16, 0, 0); } while (0)
; #define PG8_WAIT_V(n) asm volatile("s_waitcnt vmcnt(" #n ")" ::: "memory")
; #define PG8_BAR __builtin_amdgcn_s_barrier()
; template <class Epi, class Sched, bool ALIGN_EPI = false, bool SP2 = false>
; __device__ __forceinline__ void gemm_phase(PG8_LAS unsigned char* lds, const Gemm g, const Sched& S, const Epi& E) {
;     ...
;     const char* cA = (const char*)g.A + (size_t)cur.pm * tstepA + (size_t)cur.kz * kzb; const char* cB = (const char*)g.Bt + (size_t)cur.pn * tstepB + (size_t)cur.kz * kzb;
;     S.a_ready(cur);
;     if constexpr (SP2) {
;         PG8_STAGE(PG8_SB(0, 0), cB, voffB); PG8_STAGE(PG8_SB(0, 1), cB + hstepB, voffB); PG8_STAGE(PG8_SA(0, 0), cA, voffA); PG8_STAGE(PG8_SA(0, 1), cA + hstepA, voffA);
;         if (wr == 1) PG8_BAR;
;         PG8_WAIT_V(2); PG8_BAR;
;         PG8_STAGE(PG8_SB(1, 0), cB + kstep, voffB); PG8_STAGE(PG8_SA(1, 0), cA + kstep, voffA); PG8_STAGE(PG8_SB(1, 1), cB + hstepB + kstep, voffB);
;         PG8_WAIT_V(6); PG8_BAR;
.LBB0_1076:
	s_lshl_b32 s10, s10, 5
	s_and_b32 s20, s10, 0x60
	s_mov_b64 s[10:11], 0x80
	s_add_i32 m0, s30, 0x18000
	v_lshl_add_u64 v[6:7], v[6:7], 0, s[10:11]
	s_lshl_b32 s17, s16, 13
	s_lshl_b32 s21, s20, 7
	s_waitcnt vmcnt(2)
	s_barrier
	global_load_lds_dwordx4 v[6:7], off
	v_lshl_add_u64 v[4:5], v[4:5], 0, s[10:11]
	s_add_i32 m0, s30, 0x1a000
	s_add_i32 s47, s30, 0x8000
	s_waitcnt lgkmcnt(0)
	s_add_i32 s54, s30, 0xa000
	global_load_lds_dwordx4 v[4:5], off
	v_lshl_add_u64 v[0:1], v[0:1], 0, s[10:11]
	s_mov_b32 m0, s47
	s_add_u32 s18, s50, 0x80080
	global_load_lds_dwordx4 v[0:1], off
	v_lshl_add_u64 v[0:1], v[2:3], 0, s[10:11]
	s_mov_b32 m0, s54
	s_addc_u32 s19, s51, 0
	global_load_lds_dwordx4 v[0:1], off
	s_add_i32 m0, s30, 0x1c000
	v_lshl_add_u64 v[0:1], s[18:19], 0, v[132:133]
	global_load_lds_dwordx4 v[0:1], off
	v_lshl_add_u64 v[0:1], s[18:19], 0, v[128:129]
	s_add_i32 m0, s30, 0x1e000
	s_sext_i32_i16 s61, s4
	global_load_lds_dwordx4 v[0:1], off
	v_and_b32_e32 v0, 15, v162
	v_lshlrev_b32_e32 v1, 1, v11
	v_lshlrev_b32_e32 v2, 2, v162
	v_lshlrev_b32_e32 v3, 6, v162
	s_movk_i32 s4, 0x3c0
	v_lshl_or_b32 v144, s16, 6, v0
	v_lshl_or_b32 v0, v0, 6, v1
	v_and_b32_e32 v2, 32, v2
	v_and_or_b32 v1, v3, s4, v1
	v_bitop3_b32 v145, s21, v1, v2 bitop3:0xf6
	v_lshlrev_b32_e32 v1, 9, v162
	v_bitop3_b32 v0, v0, s17, v2 bitop3:0xde
	v_and_b32_e32 v1, 0x70000, v1
	v_lshlrev_b32_e32 v2, 12, v12
	v_or3_b32 v1, v9, v1, v2
	v_add_u32_e32 v136, v1, v10
	v_lshlrev_b32_e32 v1, 5, v8
	s_waitcnt vmcnt(0)
	s_cmpk_lt_u32 s5, 0x100
	v_and_b32_e32 v1, 0xf0000, v1
	s_cselect_b64 s[16:17], -1, 0
	v_or3_b32 v1, v9, v1, v2
	s_add_i32 s55, 0, 0x10000
	s_add_i32 s56, 0, 0x14000
	v_or_b32_e32 v146, s20, v11
	v_mov_b32_e32 v137, v133
	v_add_u32_e32 v138, v1, v10
	v_mov_b32_e32 v139, v133
	v_mov_b64_e32 v[140:141], 0x1080
	v_mov_b64_e32 v[142:143], 0x107f
	v_add_u32_e32 v147, s55, v145
	v_add_u32_e32 v148, s56, v145
	v_add_u32_e32 v149, 0, v0
	s_mov_b64 s[18:19], 0x200000
	s_mov_b32 s57, 0x200000
	s_mov_b64 s[20:21], 0x240000
	s_mov_b32 s58, 0x240000
	s_mov_b64 s[22:23], 0x280000
	s_mov_b32 s59, 0x280000
	s_mov_b64 s[36:37], 0x2c0000
	s_mov_b32 s60, 0x2c0000
	s_barrier
	s_branch .LBB0_1079

; template <class Epi, class Sched, bool ALIGN_EPI = false, bool SP2 = false>
; __device__ __forceinline__ void gemm_phase(PG8_LAS unsigned char* lds, const Gemm g, const Sched& S, const Epi& E) {
;     ...
;         const bool has_next = S.next(ui + 1, nxt);
;         const char* nA = has_next ? (const char*)g.A + (size_t)nxt.pm * tstepA + (size_t)nxt.kz * kzb : cA; const char* nB = has_next ? (const char*)g.Bt + (size_t)nxt.pn * tstepB + (size_t)nxt.kz * kzb : cB;
;     ...
; #pragma unroll
;         for (int a = 0; a < 2; ++a)
; #pragma unroll
;             for (int b = 0; b < 2; ++b)
; #pragma unroll
;                 for (int m = 0; m < 4; ++m)
; #pragma unroll
;                     for (int n = 0; n < 2; ++n) acc[a][b][m][n] = (f32x4){0.f, 0.f, 0.f, 0.f};
;         cur = nxt; cA = nA; cB = nB; ++ui;
.LBB0_1081:
	s_ashr_i32 s41, s40, 31
	s_lshl_b64 s[42:43], s[40:41], 20
	s_add_u32 s42, s26, s42
	s_addc_u32 s43, s27, s43
	s_and_b64 s[44:45], s[4:5], exec
	s_cselect_b32 s41, s43, s49
	s_cselect_b32 s62, s42, s48
	s_ashr_i32 s39, s38, 31
	s_lshl_b64 s[44:45], s[38:39], 20
	v_readlane_b32 s52, v240, 18
	v_readlane_b32 s53, v240, 19
	s_add_u32 s44, s52, s44
	s_addc_u32 s45, s53, s45
	s_and_b64 s[52:53], s[4:5], exec
	s_cselect_b32 s39, s45, s51
	s_cselect_b32 s63, s44, s50
	s_add_u32 s48, s48, 0x80080
	s_addc_u32 s49, s49, 0
	s_add_u32 s64, s50, 0x100
	v_mov_b64_e32 v[0:1], 0
	s_addc_u32 s65, s51, 0
	s_mov_b32 s66, -2
	v_mov_b64_e32 v[2:3], 0
	v_mov_b64_e32 v[4:5], 0
	v_mov_b64_e32 v[6:7], 0
	v_mov_b64_e32 v[12:13], 0
	v_mov_b64_e32 v[14:15], 0
	v_mov_b64_e32 v[20:21], 0
	v_mov_b64_e32 v[22:23], 0
	v_mov_b64_e32 v[28:29], 0
	v_mov_b64_e32 v[30:31], 0
	v_mov_b64_e32 v[36:37], 0
	v_mov_b64_e32 v[38:39], 0
	v_mov_b64_e32 v[44:45], 0
	v_mov_b64_e32 v[46:47], 0
	v_mov_b64_e32 v[52:53], 0
	v_mov_b64_e32 v[54:55], 0
	v_mov_b64_e32 v[8:9], 0
	v_mov_b64_e32 v[10:11], 0
	v_mov_b64_e32 v[16:17], 0
	v_mov_b64_e32 v[18:19], 0
	v_mov_b64_e32 v[24:25], 0
	v_mov_b64_e32 v[26:27], 0
	v_mov_b64_e32 v[32:33], 0
	v_mov_b64_e32 v[34:35], 0
	v_mov_b64_e32 v[40:41], 0
	v_mov_b64_e32 v[42:43], 0
	v_mov_b64_e32 v[48:49], 0
	v_mov_b64_e32 v[50:51], 0
	v_mov_b64_e32 v[56:57], 0
	v_mov_b64_e32 v[58:59], 0
	v_mov_b64_e32 v[60:61], 0
	v_mov_b64_e32 v[62:63], 0
	v_mov_b64_e32 v[64:65], 0
	v_mov_b64_e32 v[66:67], 0
	v_mov_b64_e32 v[68:69], 0
	v_mov_b64_e32 v[70:71], 0
	v_mov_b64_e32 v[76:77], 0
	v_mov_b64_e32 v[78:79], 0
	v_mov_b64_e32 v[84:85], 0
	v_mov_b64_e32 v[86:87], 0
	v_mov_b64_e32 v[92:93], 0
	v_mov_b64_e32 v[94:95], 0
	v_mov_b64_e32 v[100:101], 0
	v_mov_b64_e32 v[102:103], 0
	v_mov_b64_e32 v[108:109], 0
	v_mov_b64_e32 v[110:111], 0
	v_mov_b64_e32 v[116:117], 0
	v_mov_b64_e32 v[118:119], 0
	v_mov_b64_e32 v[72:73], 0
	v_mov_b64_e32 v[74:75], 0
	v_mov_b64_e32 v[80:81], 0
	v_mov_b64_e32 v[82:83], 0
	v_mov_b64_e32 v[88:89], 0
	v_mov_b64_e32 v[90:91], 0
	v_mov_b64_e32 v[96:97], 0
	v_mov_b64_e32 v[98:99], 0
	v_mov_b64_e32 v[104:105], 0
	v_mov_b64_e32 v[106:107], 0
	v_mov_b64_e32 v[112:113], 0
	v_mov_b64_e32 v[114:115], 0
	v_mov_b64_e32 v[120:121], 0
	v_mov_b64_e32 v[122:123], 0
	v_mov_b64_e32 v[124:125], 0
	v_mov_b64_e32 v[126:127], 0
	s_branch .LBB0_1082

; #define PG8_STAGE(bufoff, gbase, voff) do { _Pragma("unroll") for (int _i = 0; _i < 2; ++_i) \
;         __builtin_amdgcn_global_load_lds((const unsigned*)((const char*)(gbase) + (voff)[_i]), (PG8_LAS unsigned*)(lds + (bufoff) + ldsw + _i * 8192), 16, 0, 0); } while (0)
; #define PG8_LDA(dst, b, h) do { _Pragma("unroll") for (int m = 0; m < 4; ++m) _Pragma("unroll") for (int k = 0; k < 2; ++k) dst[m][k] = *(const PG8_LAS bf16x8*)(lds + PG8_SA(b, h) + aoff + m * 2048 + k * 1024); } while (0)
; #define PG8_LDB(dst, b, h) do { _Pragma("unroll") for (int n = 0; n < 2; ++n) _Pragma("unroll") for (int k = 0; k < 2; ++k) dst[n][k] = *(const PG8_LAS bf16x8*)(lds + PG8_SB(b, h) + boff + n * 2048 + k * 1024); } while (0)
; #define PG8_MMA(ai, bj, At, Bt) do { __builtin_amdgcn_s_setprio(1); _Pragma("unroll") for (int m = 0; m < 4; ++m) _Pragma("unroll") for (int n = 0; n < 2; ++n) _Pragma("unroll") for (int k = 0; k < 2; ++k) \
;         acc[ai][bj][m][n] = __builtin_amdgcn_mfma_f32_16x16x32_bf16(Bt[n][k], At[m][k], acc[ai][bj][m][n], 0, 0, 0); __builtin_amdgcn_s_setprio(0); } while (0)
; #define PG8_WAIT_V(n) asm volatile("s_waitcnt vmcnt(" #n ")" ::: "memory")
; #define PG8_WAIT_L(n) asm volatile("s_waitcnt lgkmcnt(" #n ")" ::: "memory")
; #define PG8_BAR __builtin_amdgcn_s_barrier()
; #define PG8_SCHED __builtin_amdgcn_sched_barrier(0)
; template <class Epi, class Sched, bool ALIGN_EPI = false, bool SP2 = false>
; __device__ __forceinline__ void gemm_phase(PG8_LAS unsigned char* lds, const Gemm g, const Sched& S, const Epi& E) {
;     ...
;             PG8_LDB(B0, 0, 0); PG8_LDB(B1, 0, 1); PG8_SCHED; PG8_LDA(At, 0, 0); PG8_STAGE(PG8_SA(1, 1), a1 + hstepA, voffA);
;             PG8_WAIT_V(8); PG8_WAIT_L(0); PG8_BAR; PG8_MMA(0, 0, At, B0); PG8_MMA(0, 1, At, B1); PG8_BAR; PG8_SCHED;
;             PG8_LDA(At, 0, 1); PG8_STAGE(PG8_SB(0, 0), b2, voffB); PG8_STAGE(PG8_SB(0, 1), b2 + hstepB, voffB); PG8_STAGE(PG8_SA(0, 0), a2, voffA);
.LBB0_1082:
	ds_read_b128 v[150:153], v147
	ds_read_b128 v[154:157], v147 offset:1024
	ds_read_b128 v[158:161], v147 offset:2048
	ds_read_b128 v[166:169], v147 offset:3072
	ds_read_b128 v[170:173], v148
	ds_read_b128 v[174:177], v148 offset:1024
	ds_read_b128 v[178:181], v148 offset:2048
	ds_read_b128 v[182:185], v148 offset:3072
	s_add_u32 s50, s48, 0xfff80080
	s_addc_u32 s51, s49, -1
	s_cmp_eq_u32 s66, 28
	s_cselect_b32 s53, s41, s51
	s_cselect_b32 s52, s62, s50
	s_cselect_b32 s51, s39, s65
	s_cselect_b32 s50, s63, s64
	s_add_i32 m0, s30, 0xc000
	ds_read_b128 v[186:189], v149
	ds_read_b128 v[190:193], v149 offset:1024
	ds_read_b128 v[194:197], v149 offset:2048
	ds_read_b128 v[198:201], v149 offset:3072
	ds_read_b128 v[202:205], v149 offset:4096
	ds_read_b128 v[206:209], v149 offset:5120
	ds_read_b128 v[210:213], v149 offset:6144
	ds_read_b128 v[214:217], v149 offset:7168
	global_load_lds_dwordx4 v136, s[48:49]
	s_add_i32 m0, s30, 0xe000
	s_nop 0
	global_load_lds_dwordx4 v138, s[48:49]
	s_cmp_eq_u32 s66, -2
	s_cbranch_scc1 .Lrx6_A
	s_waitcnt vmcnt(8)
.Lrx6_A_back:
	s_waitcnt lgkmcnt(0)
	s_barrier
	s_setprio 0
	s_waitcnt lgkmcnt(0)
	v_mfma_f32_16x16x32_bf16 v[124:127], v[150:153], v[186:189], v[124:127]
	v_mfma_f32_16x16x32_bf16 v[120:123], v[158:161], v[186:189], v[120:123]
	v_mfma_f32_16x16x32_bf16 v[112:115], v[150:153], v[194:197], v[112:115]
	v_mfma_f32_16x16x32_bf16 v[104:107], v[158:161], v[194:197], v[104:107]
	v_mfma_f32_16x16x32_bf16 v[96:99], v[150:153], v[202:205], v[96:99]
	v_mfma_f32_16x16x32_bf16 v[88:91], v[158:161], v[202:205], v[88:91]
	v_mfma_f32_16x16x32_bf16 v[80:83], v[150:153], v[210:213], v[80:83]
	v_mfma_f32_16x16x32_bf16 v[72:75], v[158:161], v[210:213], v[72:75]
	v_mfma_f32_16x16x32_bf16 v[124:127], v[154:157], v[190:193], v[124:127]
	v_mfma_f32_16x16x32_bf16 v[120:123], v[166:169], v[190:193], v[120:123]
	v_mfma_f32_16x16x32_bf16 v[112:115], v[154:157], v[198:201], v[112:115]
	v_mfma_f32_16x16x32_bf16 v[104:107], v[166:169], v[198:201], v[104:107]
	v_mfma_f32_16x16x32_bf16 v[96:99], v[154:157], v[206:209], v[96:99]
	v_mfma_f32_16x16x32_bf16 v[88:91], v[166:169], v[206:209], v[88:91]
	v_mfma_f32_16x16x32_bf16 v[80:83], v[154:157], v[214:217], v[80:83]
	v_mfma_f32_16x16x32_bf16 v[72:75], v[166:169], v[214:217], v[72:75]
	v_mfma_f32_16x16x32_bf16 v[116:119], v[170:173], v[186:189], v[116:119]
	v_mfma_f32_16x16x32_bf16 v[108:111], v[178:181], v[186:189], v[108:111]
	v_mfma_f32_16x16x32_bf16 v[100:103], v[170:173], v[194:197], v[100:103]
	v_mfma_f32_16x16x32_bf16 v[92:95], v[178:181], v[194:197], v[92:95]
	v_mfma_f32_16x16x32_bf16 v[84:87], v[170:173], v[202:205], v[84:87]
	v_mfma_f32_16x16x32_bf16 v[76:79], v[178:181], v[202:205], v[76:79]
	v_mfma_f32_16x16x32_bf16 v[68:71], v[170:173], v[210:213], v[68:71]
	v_mfma_f32_16x16x32_bf16 v[64:67], v[178:181], v[210:213], v[64:67]
	v_mfma_f32_16x16x32_bf16 v[116:119], v[174:177], v[190:193], v[116:119]
	v_mfma_f32_16x16x32_bf16 v[108:111], v[182:185], v[190:193], v[108:111]
	v_mfma_f32_16x16x32_bf16 v[100:103], v[174:177], v[198:201], v[100:103]
	v_mfma_f32_16x16x32_bf16 v[92:95], v[182:185], v[198:201], v[92:95]
	v_mfma_f32_16x16x32_bf16 v[84:87], v[174:177], v[206:209], v[84:87]
	v_mfma_f32_16x16x32_bf16 v[76:79], v[182:185], v[206:209], v[76:79]
	v_mfma_f32_16x16x32_bf16 v[68:71], v[174:177], v[214:217], v[68:71]
	v_mfma_f32_16x16x32_bf16 v[64:67], v[182:185], v[214:217], v[64:67]
	s_setprio 1
	s_barrier
	s_add_i32 s67, s55, s28
	v_lshl_add_u64 v[218:219], s[50:51], 0, v[132:133]
	s_mov_b32 m0, s67
	ds_read_b128 v[186:189], v149 offset:16384
	ds_read_b128 v[190:193], v149 offset:17408
	ds_read_b128 v[194:197], v149 offset:18432
	ds_read_b128 v[198:201], v149 offset:19456
	ds_read_b128 v[202:205], v149 offset:20480
	ds_read_b128 v[206:209], v149 offset:21504
	ds_read_b128 v[210:213], v149 offset:22528
	ds_read_b128 v[214:217], v149 offset:23552
	global_load_lds_dwordx4 v132, s[50:51]
	s_add_i32 m0, s67, 0x2000
	s_add_u32 s68, s50, 0x80000
	v_lshl_add_u64 v[220:221], s[50:51], 0, v[128:129]
	s_addc_u32 s69, s51, 0
	s_add_i32 s67, s56, s28
	global_load_lds_dwordx4 v128, s[50:51]
	s_mov_b32 m0, s67
	v_lshl_add_u64 v[224:225], s[52:53], 0, v[130:131]
	global_load_lds_dwordx4 v132, s[68:69]
	s_add_i32 m0, s67, 0x2000
	s_nop 0
	global_load_lds_dwordx4 v128, s[68:69]
	v_lshl_add_u64 v[222:223], s[52:53], 0, v[134:135]
	s_mov_b32 m0, s30
	s_nop 0
	global_load_lds_dwordx4 v134, s[52:53]
	s_mov_b32 m0, s31
	s_nop 0
	global_load_lds_dwordx4 v130, s[52:53]
	s_cmp_eq_u32 s66, -2
	s_cbranch_scc1 .Lrx6_B
	s_waitcnt vmcnt(8)
; #define PG8_STAGE(bufoff, gbase, voff) do { _Pragma("unroll") for (int _i = 0; _i < 2; ++_i) \
;         __builtin_amdgcn_global_load_lds((const unsigned*)((const char*)(gbase) + (voff)[_i]), (PG8_LAS unsigned*)(lds + (bufoff) + ldsw + _i * 8192), 16, 0, 0); } while (0)
; #define PG8_LDA(dst, b, h) do { _Pragma("unroll") for (int m = 0; m < 4; ++m) _Pragma("unroll") for (int k = 0; k < 2; ++k) dst[m][k] = *(const PG8_LAS bf16x8*)(lds + PG8_SA(b, h) + aoff + m * 2048 + k * 1024); } while (0)
; #define PG8_LDB(dst, b, h) do { _Pragma("unroll") for (int n = 0; n < 2; ++n) _Pragma("unroll") for (int k = 0; k < 2; ++k) dst[n][k] = *(const PG8_LAS bf16x8*)(lds + PG8_SB(b, h) + boff + n * 2048 + k * 1024); } while (0)
; #define PG8_MMA(ai, bj, At, Bt) do { __builtin_amdgcn_s_setprio(1); _Pragma("unroll") for (int m = 0; m < 4; ++m) _Pragma("unroll") for (int n = 0; n < 2; ++n) _Pragma("unroll") for (int k = 0; k < 2; ++k) \
;         acc[ai][bj][m][n] = __builtin_amdgcn_mfma_f32_16x16x32_bf16(Bt[n][k], At[m][k], acc[ai][bj][m][n], 0, 0, 0); __builtin_amdgcn_s_setprio(0); } while (0)
; #define PG8_WAIT_V(n) asm volatile("s_waitcnt vmcnt(" #n ")" ::: "memory")
; #define PG8_WAIT_L(n) asm volatile("s_waitcnt lgkmcnt(" #n ")" ::: "memory")
; #define PG8_BAR __builtin_amdgcn_s_barrier()
; #define PG8_SCHED __builtin_amdgcn_sched_barrier(0)
; template <class Epi, class Sched, bool ALIGN_EPI = false, bool SP2 = false>
; __device__ __forceinline__ void gemm_phase(PG8_LAS unsigned char* lds, const Gemm g, const Sched& S, const Epi& E) {
;     ...
;             PG8_WAIT_V(8); PG8_WAIT_L(0); PG8_BAR; PG8_MMA(1, 0, At, B0); PG8_MMA(1, 1, At, B1); PG8_BAR; PG8_SCHED;
;             PG8_LDB(B0, 1, 0); PG8_LDB(B1, 1, 1); PG8_SCHED; PG8_LDA(At, 1, 0); PG8_STAGE(PG8_SA(0, 1), a2 + hstepA, voffA);
;             PG8_WAIT_V(8); PG8_WAIT_L(0); PG8_BAR; PG8_MMA(0, 0, At, B0); PG8_MMA(0, 1, At, B1); PG8_BAR; PG8_SCHED;
.Lrx6_B_back:
	s_waitcnt lgkmcnt(0)
	s_barrier
	s_setprio 0
	s_waitcnt lgkmcnt(0)
	v_mfma_f32_16x16x32_bf16 v[60:63], v[150:153], v[186:189], v[60:63]
	v_mfma_f32_16x16x32_bf16 v[56:59], v[158:161], v[186:189], v[56:59]
	v_mfma_f32_16x16x32_bf16 v[48:51], v[150:153], v[194:197], v[48:51]
	v_mfma_f32_16x16x32_bf16 v[40:43], v[158:161], v[194:197], v[40:43]
	v_mfma_f32_16x16x32_bf16 v[32:35], v[150:153], v[202:205], v[32:35]
	v_mfma_f32_16x16x32_bf16 v[24:27], v[158:161], v[202:205], v[24:27]
	v_mfma_f32_16x16x32_bf16 v[16:19], v[150:153], v[210:213], v[16:19]
	v_mfma_f32_16x16x32_bf16 v[8:11], v[158:161], v[210:213], v[8:11]
	v_mfma_f32_16x16x32_bf16 v[60:63], v[154:157], v[190:193], v[60:63]
	v_mfma_f32_16x16x32_bf16 v[56:59], v[166:169], v[190:193], v[56:59]
	v_mfma_f32_16x16x32_bf16 v[48:51], v[154:157], v[198:201], v[48:51]
	v_mfma_f32_16x16x32_bf16 v[40:43], v[166:169], v[198:201], v[40:43]
	v_mfma_f32_16x16x32_bf16 v[32:35], v[154:157], v[206:209], v[32:35]
	v_mfma_f32_16x16x32_bf16 v[24:27], v[166:169], v[206:209], v[24:27]
	v_mfma_f32_16x16x32_bf16 v[16:19], v[154:157], v[214:217], v[16:19]
	v_mfma_f32_16x16x32_bf16 v[8:11], v[166:169], v[214:217], v[8:11]
	v_mfma_f32_16x16x32_bf16 v[52:55], v[170:173], v[186:189], v[52:55]
	v_mfma_f32_16x16x32_bf16 v[44:47], v[178:181], v[186:189], v[44:47]
	v_mfma_f32_16x16x32_bf16 v[36:39], v[170:173], v[194:197], v[36:39]
	v_mfma_f32_16x16x32_bf16 v[28:31], v[178:181], v[194:197], v[28:31]
	v_mfma_f32_16x16x32_bf16 v[20:23], v[170:173], v[202:205], v[20:23]
	v_mfma_f32_16x16x32_bf16 v[12:15], v[178:181], v[202:205], v[12:15]
	v_mfma_f32_16x16x32_bf16 v[4:7], v[170:173], v[210:213], v[4:7]
	v_mfma_f32_16x16x32_bf16 v[0:3], v[178:181], v[210:213], v[0:3]
	v_mfma_f32_16x16x32_bf16 v[52:55], v[174:177], v[190:193], v[52:55]
	v_mfma_f32_16x16x32_bf16 v[44:47], v[182:185], v[190:193], v[44:47]
	v_mfma_f32_16x16x32_bf16 v[36:39], v[174:177], v[198:201], v[36:39]
	v_mfma_f32_16x16x32_bf16 v[28:31], v[182:185], v[198:201], v[28:31]
	v_mfma_f32_16x16x32_bf16 v[20:23], v[174:177], v[206:209], v[20:23]
	v_mfma_f32_16x16x32_bf16 v[12:15], v[182:185], v[206:209], v[12:15]
	v_mfma_f32_16x16x32_bf16 v[4:7], v[174:177], v[214:217], v[4:7]
	v_mfma_f32_16x16x32_bf16 v[0:3], v[182:185], v[214:217], v[0:3]
	s_setprio 1
	s_barrier
	s_add_i32 s67, 0, 0x18000
	v_add_u32_e32 v163, s67, v145
	s_add_i32 s68, 0, 0x1c000
	ds_read_b128 v[150:153], v163
	ds_read_b128 v[154:157], v163 offset:1024
	ds_read_b128 v[158:161], v163 offset:2048
	ds_read_b128 v[166:169], v163 offset:3072
	v_add_u32_e32 v163, s68, v145
	ds_read_b128 v[170:173], v163
	ds_read_b128 v[174:177], v163 offset:1024
	ds_read_b128 v[178:181], v163 offset:2048
	ds_read_b128 v[182:185], v163 offset:3072
	s_add_u32 s52, s52, 0x80000
	s_addc_u32 s53, s53, 0
	s_mov_b32 m0, s33
	ds_read_b128 v[186:189], v149 offset:32768
	ds_read_b128 v[190:193], v149 offset:33792
	ds_read_b128 v[194:197], v149 offset:34816
	ds_read_b128 v[198:201], v149 offset:35840
	ds_read_b128 v[202:205], v149 offset:36864
	ds_read_b128 v[206:209], v149 offset:37888
	ds_read_b128 v[210:213], v149 offset:38912
	ds_read_b128 v[214:217], v149 offset:39936
	global_load_lds_dwordx4 v134, s[52:53]
	s_mov_b32 m0, s34
	s_nop 0
	global_load_lds_dwordx4 v130, s[52:53]
	s_waitcnt vmcnt(8)
	s_waitcnt lgkmcnt(0)
	s_barrier
	s_setprio 0
	s_waitcnt lgkmcnt(0)
	v_mfma_f32_16x16x32_bf16 v[124:127], v[150:153], v[186:189], v[124:127]
	v_mfma_f32_16x16x32_bf16 v[120:123], v[158:161], v[186:189], v[120:123]
	v_mfma_f32_16x16x32_bf16 v[112:115], v[150:153], v[194:197], v[112:115]
	v_mfma_f32_16x16x32_bf16 v[104:107], v[158:161], v[194:197], v[104:107]
	v_mfma_f32_16x16x32_bf16 v[96:99], v[150:153], v[202:205], v[96:99]
	v_mfma_f32_16x16x32_bf16 v[88:91], v[158:161], v[202:205], v[88:91]
	v_mfma_f32_16x16x32_bf16 v[80:83], v[150:153], v[210:213], v[80:83]
	v_mfma_f32_16x16x32_bf16 v[72:75], v[158:161], v[210:213], v[72:75]
	v_mfma_f32_16x16x32_bf16 v[124:127], v[154:157], v[190:193], v[124:127]
	v_mfma_f32_16x16x32_bf16 v[120:123], v[166:169], v[190:193], v[120:123]
	v_mfma_f32_16x16x32_bf16 v[112:115], v[154:157], v[198:201], v[112:115]
	v_mfma_f32_16x16x32_bf16 v[104:107], v[166:169], v[198:201], v[104:107]
	v_mfma_f32_16x16x32_bf16 v[96:99], v[154:157], v[206:209], v[96:99]
	v_mfma_f32_16x16x32_bf16 v[88:91], v[166:169], v[206:209], v[88:91]
	v_mfma_f32_16x16x32_bf16 v[80:83], v[154:157], v[214:217], v[80:83]
	v_mfma_f32_16x16x32_bf16 v[72:75], v[166:169], v[214:217], v[72:75]
	v_mfma_f32_16x16x32_bf16 v[116:119], v[170:173], v[186:189], v[116:119]
	v_mfma_f32_16x16x32_bf16 v[108:111], v[178:181], v[186:189], v[108:111]
	v_mfma_f32_16x16x32_bf16 v[100:103], v[170:173], v[194:197], v[100:103]
	v_mfma_f32_16x16x32_bf16 v[92:95], v[178:181], v[194:197], v[92:95]
	v_mfma_f32_16x16x32_bf16 v[84:87], v[170:173], v[202:205], v[84:87]
	v_mfma_f32_16x16x32_bf16 v[76:79], v[178:181], v[202:205], v[76:79]
	v_mfma_f32_16x16x32_bf16 v[68:71], v[170:173], v[210:213], v[68:71]
	v_mfma_f32_16x16x32_bf16 v[64:67], v[178:181], v[210:213], v[64:67]
	v_mfma_f32_16x16x32_bf16 v[116:119], v[174:177], v[190:193], v[116:119]
	v_mfma_f32_16x16x32_bf16 v[108:111], v[182:185], v[190:193], v[108:111]
	v_mfma_f32_16x16x32_bf16 v[100:103], v[174:177], v[198:201], v[100:103]
	v_mfma_f32_16x16x32_bf16 v[92:95], v[182:185], v[198:201], v[92:95]
	v_mfma_f32_16x16x32_bf16 v[84:87], v[174:177], v[206:209], v[84:87]
	v_mfma_f32_16x16x32_bf16 v[76:79], v[182:185], v[206:209], v[76:79]
	v_mfma_f32_16x16x32_bf16 v[68:71], v[174:177], v[214:217], v[68:71]
	v_mfma_f32_16x16x32_bf16 v[64:67], v[182:185], v[214:217], v[64:67]
	s_setprio 1
	s_barrier
; #define PG8_STAGE(bufoff, gbase, voff) do { _Pragma("unroll") for (int _i = 0; _i < 2; ++_i) \
;         __builtin_amdgcn_global_load_lds((const unsigned*)((const char*)(gbase) + (voff)[_i]), (PG8_LAS unsigned*)(lds + (bufoff) + ldsw + _i * 8192), 16, 0, 0); } while (0)
; #define PG8_LDA(dst, b, h) do { _Pragma("unroll") for (int m = 0; m < 4; ++m) _Pragma("unroll") for (int k = 0; k < 2; ++k) dst[m][k] = *(const PG8_LAS bf16x8*)(lds + PG8_SA(b, h) + aoff + m * 2048 + k * 1024); } while (0)
; #define PG8_MMA(ai, bj, At, Bt) do { __builtin_amdgcn_s_setprio(1); _Pragma("unroll") for (int m = 0; m < 4; ++m) _Pragma("unroll") for (int n = 0; n < 2; ++n) _Pragma("unroll") for (int k = 0; k < 2; ++k) \
;         acc[ai][bj][m][n] = __builtin_amdgcn_mfma_f32_16x16x32_bf16(Bt[n][k], At[m][k], acc[ai][bj][m][n], 0, 0, 0); __builtin_amdgcn_s_setprio(0); } while (0)
; #define PG8_WAIT_V(n) asm volatile("s_waitcnt vmcnt(" #n ")" ::: "memory")
; #define PG8_WAIT_L(n) asm volatile("s_waitcnt lgkmcnt(" #n ")" ::: "memory")
; #define PG8_BAR __builtin_amdgcn_s_barrier()
; #define PG8_SCHED __builtin_amdgcn_sched_barrier(0)
; template <class Epi, class Sched, bool ALIGN_EPI = false, bool SP2 = false>
; __device__ __forceinline__ void gemm_phase(PG8_LAS unsigned char* lds, const Gemm g, const Sched& S, const Epi& E) {
;     ...
;             PG8_LDA(At, 1, 1); PG8_STAGE(PG8_SB(1, 0), b3, voffB); PG8_STAGE(PG8_SB(1, 1), b3 + hstepB, voffB); PG8_STAGE(PG8_SA(1, 0), a3, voffA);
;             PG8_WAIT_V(8); PG8_WAIT_L(0); PG8_BAR; PG8_MMA(1, 0, At, B0); PG8_MMA(1, 1, At, B1); PG8_BAR; PG8_SCHED;
	s_add_i32 s52, s67, s28
	v_lshl_add_u64 v[218:219], v[218:219], 0, s[10:11]
	s_mov_b32 m0, s52
	ds_read_b128 v[186:189], v149 offset:49152
	ds_read_b128 v[190:193], v149 offset:50176
	ds_read_b128 v[194:197], v149 offset:51200
	ds_read_b128 v[198:201], v149 offset:52224
	ds_read_b128 v[202:205], v149 offset:53248
	ds_read_b128 v[206:209], v149 offset:54272
	ds_read_b128 v[210:213], v149 offset:55296
	ds_read_b128 v[214:217], v149 offset:56320
	global_load_lds_dwordx4 v[218:219], off
	s_add_i32 m0, s52, 0x2000
	s_add_u32 s50, s50, 0x80080
	v_lshl_add_u64 v[218:219], v[220:221], 0, s[10:11]
	s_addc_u32 s51, s51, 0
	s_add_i32 s52, s68, s28
	global_load_lds_dwordx4 v[218:219], off
	s_mov_b32 m0, s52
	s_nop 0
	global_load_lds_dwordx4 v132, s[50:51]
	s_add_i32 m0, s52, 0x2000
	s_nop 0
	global_load_lds_dwordx4 v128, s[50:51]
	v_lshl_add_u64 v[218:219], v[222:223], 0, s[10:11]
	s_mov_b32 m0, s47
	s_nop 0
	global_load_lds_dwordx4 v[218:219], off
	v_lshl_add_u64 v[218:219], v[224:225], 0, s[10:11]
	s_mov_b32 m0, s54
	s_nop 0
	global_load_lds_dwordx4 v[218:219], off
	s_waitcnt vmcnt(8)
	s_waitcnt lgkmcnt(0)
	s_barrier
	s_setprio 0
	s_waitcnt lgkmcnt(0)
	v_mfma_f32_16x16x32_bf16 v[60:63], v[150:153], v[186:189], v[60:63]
	v_mfma_f32_16x16x32_bf16 v[56:59], v[158:161], v[186:189], v[56:59]
	v_mfma_f32_16x16x32_bf16 v[48:51], v[150:153], v[194:197], v[48:51]
	v_mfma_f32_16x16x32_bf16 v[40:43], v[158:161], v[194:197], v[40:43]
	v_mfma_f32_16x16x32_bf16 v[32:35], v[150:153], v[202:205], v[32:35]
	v_mfma_f32_16x16x32_bf16 v[24:27], v[158:161], v[202:205], v[24:27]
	v_mfma_f32_16x16x32_bf16 v[16:19], v[150:153], v[210:213], v[16:19]
	v_mfma_f32_16x16x32_bf16 v[8:11], v[158:161], v[210:213], v[8:11]
	v_mfma_f32_16x16x32_bf16 v[60:63], v[154:157], v[190:193], v[60:63]
	v_mfma_f32_16x16x32_bf16 v[56:59], v[166:169], v[190:193], v[56:59]
	v_mfma_f32_16x16x32_bf16 v[48:51], v[154:157], v[198:201], v[48:51]
	v_mfma_f32_16x16x32_bf16 v[40:43], v[166:169], v[198:201], v[40:43]
	v_mfma_f32_16x16x32_bf16 v[32:35], v[154:157], v[206:209], v[32:35]
	v_mfma_f32_16x16x32_bf16 v[24:27], v[166:169], v[206:209], v[24:27]
	v_mfma_f32_16x16x32_bf16 v[16:19], v[154:157], v[214:217], v[16:19]
	v_mfma_f32_16x16x32_bf16 v[8:11], v[166:169], v[214:217], v[8:11]
	v_mfma_f32_16x16x32_bf16 v[52:55], v[170:173], v[186:189], v[52:55]
	v_mfma_f32_16x16x32_bf16 v[44:47], v[178:181], v[186:189], v[44:47]
	v_mfma_f32_16x16x32_bf16 v[36:39], v[170:173], v[194:197], v[36:39]
	v_mfma_f32_16x16x32_bf16 v[28:31], v[178:181], v[194:197], v[28:31]
	v_mfma_f32_16x16x32_bf16 v[20:23], v[170:173], v[202:205], v[20:23]
	v_mfma_f32_16x16x32_bf16 v[12:15], v[178:181], v[202:205], v[12:15]
	v_mfma_f32_16x16x32_bf16 v[4:7], v[170:173], v[210:213], v[4:7]
	v_mfma_f32_16x16x32_bf16 v[0:3], v[178:181], v[210:213], v[0:3]
	v_mfma_f32_16x16x32_bf16 v[52:55], v[174:177], v[190:193], v[52:55]
	v_mfma_f32_16x16x32_bf16 v[44:47], v[182:185], v[190:193], v[44:47]
	v_mfma_f32_16x16x32_bf16 v[36:39], v[174:177], v[198:201], v[36:39]
	v_mfma_f32_16x16x32_bf16 v[28:31], v[182:185], v[198:201], v[28:31]
	v_mfma_f32_16x16x32_bf16 v[20:23], v[174:177], v[206:209], v[20:23]
	v_mfma_f32_16x16x32_bf16 v[12:15], v[182:185], v[206:209], v[12:15]
	v_mfma_f32_16x16x32_bf16 v[4:7], v[174:177], v[214:217], v[4:7]
	v_mfma_f32_16x16x32_bf16 v[0:3], v[182:185], v[214:217], v[0:3]
	s_setprio 1
	s_barrier
	s_add_i32 s66, s66, 2
	s_add_u32 s48, s48, 0x100
	s_addc_u32 s49, s49, 0
	s_add_u32 s64, s64, 0x100
	s_addc_u32 s65, s65, 0
	s_cmp_gt_u32 s66, 29
	s_cbranch_scc0 .LBB0_1082
	s_and_b64 vcc, exec, s[16:17]
	s_cbranch_vccz .LBB0_1085
	s_barrier

; #define PG8_STAGE(bufoff, gbase, voff) do { _Pragma("unroll") for (int _i = 0; _i < 2; ++_i) \
;         __builtin_amdgcn_global_load_lds((const unsigned*)((const char*)(gbase) + (voff)[_i]), (PG8_LAS unsigned*)(lds + (bufoff) + ldsw + _i * 8192), 16, 0, 0); } while (0)
; #define PG8_WAIT_V(n) asm volatile("s_waitcnt vmcnt(" #n ")" ::: "memory")
; #define PG8_BAR __builtin_amdgcn_s_barrier()
; template <class Epi, class Sched, bool ALIGN_EPI = false, bool SP2 = false>
; __device__ __forceinline__ void gemm_phase(PG8_LAS unsigned char* lds, const Gemm g, const Sched& S, const Epi& E) {
;     ...
;     for (int i = 0; i < 2; ++i) { int R, C; stage_rc(tid * 16 + i * 8192, R, C); const int Rb = Epi::PERM ? ((R & ~31) + perm32(R & 31)) : R;
;         voffA[i] = (unsigned)(R * g.lda + C) * 2u; voffB[i] = (unsigned)(Rb * g.ldb + C) * 2u; }
;     const size_t kstep = (size_t)(BK * 2);
;     const size_t hstepA = (size_t)HALF * g.lda * 2, hstepB = (size_t)HALF * g.ldb * 2;
;     const size_t tstepA = 2 * hstepA, tstepB = 2 * hstepB;
;     const unsigned ldsw = (unsigned)wid * 1024u;
;     const int aoff = lds_byte(wr * 64 + fr, fq * 8), boff = lds_byte(wc * 32 + fr, fq * 8);
;     ...
;         PG8_STAGE(PG8_SB(0, 0), cB, voffB); PG8_STAGE(PG8_SB(0, 1), cB + hstepB, voffB); PG8_STAGE(PG8_SA(0, 0), cA, voffA); PG8_STAGE(PG8_SA(0, 1), cA + hstepA, voffA);
;         if (wr == 1) PG8_BAR;
;         PG8_WAIT_V(2); PG8_BAR;
;         PG8_STAGE(PG8_SB(1, 0), cB + kstep, voffB); PG8_STAGE(PG8_SA(1, 0), cA + kstep, voffA); PG8_STAGE(PG8_SB(1, 1), cB + hstepB + kstep, voffB);
;         PG8_WAIT_V(6); PG8_BAR;
.LBB0_1151:
	s_lshl_b32 s10, s10, 5
	s_and_b32 s20, s10, 0x60
	s_mov_b64 s[10:11], 0x80
	s_add_i32 m0, s29, 0x18000
	v_lshl_add_u64 v[6:7], v[6:7], 0, s[10:11]
	s_lshl_b32 s17, s16, 13
	s_waitcnt vmcnt(2)
	s_barrier
	global_load_lds_dwordx4 v[6:7], off
	v_lshl_add_u64 v[4:5], v[4:5], 0, s[10:11]
	s_add_i32 m0, s29, 0x1a000
	s_add_i32 s35, s29, 0x8000
	s_add_i32 s47, s29, 0xa000
	global_load_lds_dwordx4 v[4:5], off
	v_lshl_add_u64 v[0:1], v[0:1], 0, s[10:11]
	s_mov_b32 m0, s35
	s_add_u32 s18, s50, 0x200080
	global_load_lds_dwordx4 v[0:1], off
	v_lshl_add_u64 v[0:1], v[2:3], 0, s[10:11]
	s_mov_b32 m0, s47
	s_addc_u32 s19, s51, 0
	global_load_lds_dwordx4 v[0:1], off
	s_add_i32 m0, s29, 0x1c000
	v_lshl_add_u64 v[0:1], s[18:19], 0, v[130:131]
	global_load_lds_dwordx4 v[0:1], off
	v_lshl_add_u64 v[0:1], s[18:19], 0, v[134:135]
	s_add_i32 m0, s29, 0x1e000
	v_lshlrev_b32_e32 v2, 14, v148
	global_load_lds_dwordx4 v[0:1], off
	v_lshlrev_b32_e32 v1, 2, v149
	v_lshl_or_b32 v0, v149, 6, v152
	v_and_b32_e32 v1, 32, v1
	v_bitop3_b32 v0, v0, s17, v1 bitop3:0xde
	v_lshlrev_b32_e32 v1, 11, v162
	v_and_b32_e32 v1, 0x1c0000, v1
	v_or3_b32 v1, v146, v1, v2
	v_add_u32_e32 v136, v1, v147
	v_lshlrev_b32_e32 v1, 7, v151
	s_waitcnt vmcnt(0)
	s_cmpk_lt_u32 s5, 0x100
	v_and_b32_e32 v1, 0x3c0000, v1
	v_lshl_or_b32 v154, s16, 6, v149
	v_lshl_or_b32 v155, s20, 7, v153
	s_cselect_b64 s[16:17], -1, 0
	v_or3_b32 v1, v146, v1, v2
	s_waitcnt lgkmcnt(0)
	s_add_i32 s54, 0, 0x10000
	s_add_i32 s55, 0, 0x14000
	s_sext_i32_i8 s60, s4
	v_or_b32_e32 v156, s20, v150
	v_mov_b32_e32 v137, v131
	v_add_u32_e32 v138, v1, v147
	v_mov_b32_e32 v139, v131
	v_mov_b64_e32 v[140:141], 0x400
	v_mov_b64_e32 v[142:143], 0x3ff
	v_add_u32_e32 v157, s54, v155
	v_add_u32_e32 v158, s55, v155
	v_add_u32_e32 v159, 0, v0
	s_mov_b64 s[18:19], 0x80000
	s_mov_b32 s56, 0x80000
	s_mov_b64 s[20:21], 0x90000
	s_mov_b32 s57, 0x90000
	s_mov_b64 s[22:23], 0xa0000
	s_mov_b32 s58, 0xa0000
	s_mov_b64 s[36:37], 0xb0000
	s_mov_b32 s59, 0xb0000
	s_barrier
	s_branch .LBB0_1154

; template <class Epi, class Sched, bool ALIGN_EPI = false, bool SP2 = false>
; __device__ __forceinline__ void gemm_phase(PG8_LAS unsigned char* lds, const Gemm g, const Sched& S, const Epi& E) {
;     ...
;         const bool has_next = S.next(ui + 1, nxt);
;         const char* nA = has_next ? (const char*)g.A + (size_t)nxt.pm * tstepA + (size_t)nxt.kz * kzb : cA; const char* nB = has_next ? (const char*)g.Bt + (size_t)nxt.pn * tstepB + (size_t)nxt.kz * kzb : cB;
;         for (int t = 0; t < nt; t += 2) {
;             const bool last = (t == nt - 2);
;             const char* a1 = cA + (size_t)(t + 1) * kstep;
;             const char* a2 = last ? nA : cA + (size_t)(t + 2) * kstep; const char* b2 = last ? nB : cB + (size_t)(t + 2) * kstep;
;             const char* a3 = a2 + kstep; const char* b3 = b2 + kstep;
;     ...
; #pragma unroll
;         for (int a = 0; a < 2; ++a)
; #pragma unroll
;             for (int b = 0; b < 2; ++b)
; #pragma unroll
;                 for (int m = 0; m < 4; ++m)
; #pragma unroll
;                     for (int n = 0; n < 2; ++n) acc[a][b][m][n] = (f32x4){0.f, 0.f, 0.f, 0.f};
;         cur = nxt; cA = nA; cB = nB; ++ui;
.LBB0_1160:
	s_ashr_i32 s41, s40, 31
	s_lshl_b64 s[42:43], s[40:41], 22
	s_add_u32 s42, s12, s42
	s_addc_u32 s43, s13, s43
	s_and_b64 s[44:45], s[4:5], exec
	s_cselect_b32 s41, s43, s49
	s_cselect_b32 s61, s42, s48
	s_ashr_i32 s39, s38, 31
	s_lshl_b64 s[44:45], s[38:39], 22
	v_readlane_b32 s52, v240, 20
	v_readlane_b32 s53, v240, 21
	s_add_u32 s44, s52, s44
	s_addc_u32 s45, s53, s45
	s_and_b64 s[52:53], s[4:5], exec
	s_cselect_b32 s39, s45, s51
	s_cselect_b32 s62, s44, s50
	s_add_u32 s48, s48, 0x200080
	s_addc_u32 s49, s49, 0
	s_add_u32 s63, s50, 0x100
	v_mov_b64_e32 v[0:1], 0
	s_addc_u32 s64, s51, 0
	s_mov_b32 s65, -2
	v_mov_b64_e32 v[2:3], 0
	v_mov_b64_e32 v[4:5], 0
	v_mov_b64_e32 v[6:7], 0
	v_mov_b64_e32 v[8:9], 0
	v_mov_b64_e32 v[10:11], 0
	v_mov_b64_e32 v[16:17], 0
	v_mov_b64_e32 v[18:19], 0
	v_mov_b64_e32 v[24:25], 0
	v_mov_b64_e32 v[26:27], 0
	v_mov_b64_e32 v[32:33], 0
	v_mov_b64_e32 v[34:35], 0
	v_mov_b64_e32 v[40:41], 0
	v_mov_b64_e32 v[42:43], 0
	v_mov_b64_e32 v[48:49], 0
	v_mov_b64_e32 v[50:51], 0
	v_mov_b64_e32 v[12:13], 0
	v_mov_b64_e32 v[14:15], 0
	v_mov_b64_e32 v[20:21], 0
	v_mov_b64_e32 v[22:23], 0
	v_mov_b64_e32 v[28:29], 0
	v_mov_b64_e32 v[30:31], 0
	v_mov_b64_e32 v[36:37], 0
	v_mov_b64_e32 v[38:39], 0
	v_mov_b64_e32 v[44:45], 0
	v_mov_b64_e32 v[46:47], 0
	v_mov_b64_e32 v[52:53], 0
	v_mov_b64_e32 v[54:55], 0
	v_mov_b64_e32 v[56:57], 0
	v_mov_b64_e32 v[58:59], 0
	v_mov_b64_e32 v[60:61], 0
	v_mov_b64_e32 v[62:63], 0
	v_mov_b64_e32 v[64:65], 0
	v_mov_b64_e32 v[66:67], 0
	v_mov_b64_e32 v[68:69], 0
	v_mov_b64_e32 v[70:71], 0
	v_mov_b64_e32 v[76:77], 0
	v_mov_b64_e32 v[78:79], 0
	v_mov_b64_e32 v[84:85], 0
	v_mov_b64_e32 v[86:87], 0
	v_mov_b64_e32 v[88:89], 0
	v_mov_b64_e32 v[90:91], 0
	v_mov_b64_e32 v[96:97], 0
	v_mov_b64_e32 v[98:99], 0
	v_mov_b64_e32 v[104:105], 0
	v_mov_b64_e32 v[106:107], 0
	v_mov_b64_e32 v[112:113], 0
	v_mov_b64_e32 v[114:115], 0
	v_mov_b64_e32 v[72:73], 0
	v_mov_b64_e32 v[74:75], 0
	v_mov_b64_e32 v[80:81], 0
	v_mov_b64_e32 v[82:83], 0
	v_mov_b64_e32 v[92:93], 0
	v_mov_b64_e32 v[94:95], 0
	v_mov_b64_e32 v[100:101], 0
	v_mov_b64_e32 v[102:103], 0
	v_mov_b64_e32 v[108:109], 0
	v_mov_b64_e32 v[110:111], 0
	v_mov_b64_e32 v[116:117], 0
	v_mov_b64_e32 v[118:119], 0
	v_mov_b64_e32 v[120:121], 0
	v_mov_b64_e32 v[122:123], 0
	v_mov_b64_e32 v[124:125], 0
	v_mov_b64_e32 v[126:127], 0
	s_branch .LBB0_1161

; #define PG8_STAGE(bufoff, gbase, voff) do { _Pragma("unroll") for (int _i = 0; _i < 2; ++_i) \
;         __builtin_amdgcn_global_load_lds((const unsigned*)((const char*)(gbase) + (voff)[_i]), (PG8_LAS unsigned*)(lds + (bufoff) + ldsw + _i * 8192), 16, 0, 0); } while (0)
; #define PG8_LDA(dst, b, h) do { _Pragma("unroll") for (int m = 0; m < 4; ++m) _Pragma("unroll") for (int k = 0; k < 2; ++k) dst[m][k] = *(const PG8_LAS bf16x8*)(lds + PG8_SA(b, h) + aoff + m * 2048 + k * 1024); } while (0)
; #define PG8_LDB(dst, b, h) do { _Pragma("unroll") for (int n = 0; n < 2; ++n) _Pragma("unroll") for (int k = 0; k < 2; ++k) dst[n][k] = *(const PG8_LAS bf16x8*)(lds + PG8_SB(b, h) + boff + n * 2048 + k * 1024); } while (0)
; #define PG8_MMA(ai, bj, At, Bt) do { __builtin_amdgcn_s_setprio(1); _Pragma("unroll") for (int m = 0; m < 4; ++m) _Pragma("unroll") for (int n = 0; n < 2; ++n) _Pragma("unroll") for (int k = 0; k < 2; ++k) \
;         acc[ai][bj][m][n] = __builtin_amdgcn_mfma_f32_16x16x32_bf16(Bt[n][k], At[m][k], acc[ai][bj][m][n], 0, 0, 0); __builtin_amdgcn_s_setprio(0); } while (0)
; #define PG8_WAIT_V(n) asm volatile("s_waitcnt vmcnt(" #n ")" ::: "memory")
; #define PG8_WAIT_L(n) asm volatile("s_waitcnt lgkmcnt(" #n ")" ::: "memory")
; #define PG8_BAR __builtin_amdgcn_s_barrier()
; #define PG8_SCHED __builtin_amdgcn_sched_barrier(0)
; template <class Epi, class Sched, bool ALIGN_EPI = false, bool SP2 = false>
; __device__ __forceinline__ void gemm_phase(PG8_LAS unsigned char* lds, const Gemm g, const Sched& S, const Epi& E) {
;     ...
;             PG8_LDB(B0, 0, 0); PG8_LDB(B1, 0, 1); PG8_SCHED; PG8_LDA(At, 0, 0); PG8_STAGE(PG8_SA(1, 1), a1 + hstepA, voffA);
;             PG8_WAIT_V(8); PG8_WAIT_L(0); PG8_BAR; PG8_MMA(0, 0, At, B0); PG8_MMA(0, 1, At, B1); PG8_BAR; PG8_SCHED;
;             PG8_LDA(At, 0, 1); PG8_STAGE(PG8_SB(0, 0), b2, voffB); PG8_STAGE(PG8_SB(0, 1), b2 + hstepB, voffB); PG8_STAGE(PG8_SA(0, 0), a2, voffA);
;             PG8_WAIT_V(8); PG8_WAIT_L(0); PG8_BAR; PG8_MMA(1, 0, At, B0); PG8_MMA(1, 1, At, B1); PG8_BAR; PG8_SCHED;
.LBB0_1161:
	ds_read_b128 v[166:169], v157
	ds_read_b128 v[170:173], v157 offset:1024
	ds_read_b128 v[174:177], v157 offset:2048
	ds_read_b128 v[178:181], v157 offset:3072
	ds_read_b128 v[182:185], v158
	ds_read_b128 v[186:189], v158 offset:1024
	ds_read_b128 v[190:193], v158 offset:2048
	ds_read_b128 v[194:197], v158 offset:3072
	s_add_u32 s50, s48, 0xffe00080
	s_addc_u32 s51, s49, -1
	s_cmpk_eq_i32 s65, 0x7c
	s_cselect_b32 s53, s41, s51
	s_cselect_b32 s52, s61, s50
	s_cselect_b32 s51, s39, s64
	s_cselect_b32 s50, s62, s63
	s_add_i32 m0, s29, 0xc000
	ds_read_b128 v[198:201], v159
	ds_read_b128 v[202:205], v159 offset:1024
	ds_read_b128 v[206:209], v159 offset:2048
	ds_read_b128 v[210:213], v159 offset:3072
	ds_read_b128 v[214:217], v159 offset:4096
	ds_read_b128 v[218:221], v159 offset:5120
	ds_read_b128 v[222:225], v159 offset:6144
	ds_read_b128 v[226:229], v159 offset:7168
	global_load_lds_dwordx4 v136, s[48:49]
	s_add_i32 m0, s29, 0xe000
	s_nop 0
	global_load_lds_dwordx4 v138, s[48:49]
	s_cmp_eq_u32 s65, -2
	s_cbranch_scc1 .Lrx7_A
	s_waitcnt vmcnt(8)
.Lrx7_A_back:
	s_waitcnt lgkmcnt(0)
	s_barrier
	s_setprio 0
	s_waitcnt lgkmcnt(0)
	v_mfma_f32_16x16x32_bf16 v[124:127], v[166:169], v[198:201], v[124:127]
	v_mfma_f32_16x16x32_bf16 v[120:123], v[174:177], v[198:201], v[120:123]
	v_mfma_f32_16x16x32_bf16 v[116:119], v[166:169], v[206:209], v[116:119]
	v_mfma_f32_16x16x32_bf16 v[108:111], v[174:177], v[206:209], v[108:111]
	v_mfma_f32_16x16x32_bf16 v[100:103], v[166:169], v[214:217], v[100:103]
	v_mfma_f32_16x16x32_bf16 v[92:95], v[174:177], v[214:217], v[92:95]
	v_mfma_f32_16x16x32_bf16 v[80:83], v[166:169], v[222:225], v[80:83]
	v_mfma_f32_16x16x32_bf16 v[72:75], v[174:177], v[222:225], v[72:75]
	v_mfma_f32_16x16x32_bf16 v[124:127], v[170:173], v[202:205], v[124:127]
	v_mfma_f32_16x16x32_bf16 v[120:123], v[178:181], v[202:205], v[120:123]
	v_mfma_f32_16x16x32_bf16 v[116:119], v[170:173], v[210:213], v[116:119]
	v_mfma_f32_16x16x32_bf16 v[108:111], v[178:181], v[210:213], v[108:111]
	v_mfma_f32_16x16x32_bf16 v[100:103], v[170:173], v[218:221], v[100:103]
	v_mfma_f32_16x16x32_bf16 v[92:95], v[178:181], v[218:221], v[92:95]
	v_mfma_f32_16x16x32_bf16 v[80:83], v[170:173], v[226:229], v[80:83]
	v_mfma_f32_16x16x32_bf16 v[72:75], v[178:181], v[226:229], v[72:75]
	v_mfma_f32_16x16x32_bf16 v[112:115], v[182:185], v[198:201], v[112:115]
	v_mfma_f32_16x16x32_bf16 v[104:107], v[190:193], v[198:201], v[104:107]
	v_mfma_f32_16x16x32_bf16 v[96:99], v[182:185], v[206:209], v[96:99]
	v_mfma_f32_16x16x32_bf16 v[88:91], v[190:193], v[206:209], v[88:91]
	v_mfma_f32_16x16x32_bf16 v[84:87], v[182:185], v[214:217], v[84:87]
	v_mfma_f32_16x16x32_bf16 v[76:79], v[190:193], v[214:217], v[76:79]
	v_mfma_f32_16x16x32_bf16 v[68:71], v[182:185], v[222:225], v[68:71]
	v_mfma_f32_16x16x32_bf16 v[64:67], v[190:193], v[222:225], v[64:67]
	v_mfma_f32_16x16x32_bf16 v[112:115], v[186:189], v[202:205], v[112:115]
	v_mfma_f32_16x16x32_bf16 v[104:107], v[194:197], v[202:205], v[104:107]
	v_mfma_f32_16x16x32_bf16 v[96:99], v[186:189], v[210:213], v[96:99]
	v_mfma_f32_16x16x32_bf16 v[88:91], v[194:197], v[210:213], v[88:91]
	v_mfma_f32_16x16x32_bf16 v[84:87], v[186:189], v[218:221], v[84:87]
	v_mfma_f32_16x16x32_bf16 v[76:79], v[194:197], v[218:221], v[76:79]
	v_mfma_f32_16x16x32_bf16 v[68:71], v[186:189], v[226:229], v[68:71]
	v_mfma_f32_16x16x32_bf16 v[64:67], v[194:197], v[226:229], v[64:67]
	s_setprio 1
	s_barrier
	s_add_i32 s66, s54, s28
	v_lshl_add_u64 v[144:145], s[50:51], 0, v[130:131]
	s_mov_b32 m0, s66
	ds_read_b128 v[198:201], v159 offset:16384
	ds_read_b128 v[202:205], v159 offset:17408
	ds_read_b128 v[206:209], v159 offset:18432
	ds_read_b128 v[210:213], v159 offset:19456
	ds_read_b128 v[214:217], v159 offset:20480
	ds_read_b128 v[218:221], v159 offset:21504
	ds_read_b128 v[222:225], v159 offset:22528
	ds_read_b128 v[226:229], v159 offset:23552
	global_load_lds_dwordx4 v130, s[50:51]
	s_add_i32 m0, s66, 0x2000
	s_add_u32 s66, s50, 0x200000
	v_lshl_add_u64 v[160:161], s[50:51], 0, v[134:135]
	s_addc_u32 s67, s51, 0
	s_add_i32 s68, s55, s28
	global_load_lds_dwordx4 v134, s[50:51]
	s_mov_b32 m0, s68
	v_lshl_add_u64 v[232:233], s[52:53], 0, v[132:133]
	global_load_lds_dwordx4 v130, s[66:67]
	s_add_i32 m0, s68, 0x2000
	s_nop 0
	global_load_lds_dwordx4 v134, s[66:67]
	v_lshl_add_u64 v[230:231], s[52:53], 0, v[128:129]
	s_mov_b32 m0, s29
	s_nop 0
	global_load_lds_dwordx4 v128, s[52:53]
	s_mov_b32 m0, s30
	s_nop 0
	global_load_lds_dwordx4 v132, s[52:53]
	s_cmp_eq_u32 s65, -2
	s_cbranch_scc1 .Lrx7_B
	s_waitcnt vmcnt(8)
; #define PG8_STAGE(bufoff, gbase, voff) do { _Pragma("unroll") for (int _i = 0; _i < 2; ++_i) \
;         __builtin_amdgcn_global_load_lds((const unsigned*)((const char*)(gbase) + (voff)[_i]), (PG8_LAS unsigned*)(lds + (bufoff) + ldsw + _i * 8192), 16, 0, 0); } while (0)
; #define PG8_LDA(dst, b, h) do { _Pragma("unroll") for (int m = 0; m < 4; ++m) _Pragma("unroll") for (int k = 0; k < 2; ++k) dst[m][k] = *(const PG8_LAS bf16x8*)(lds + PG8_SA(b, h) + aoff + m * 2048 + k * 1024); } while (0)
; #define PG8_LDB(dst, b, h) do { _Pragma("unroll") for (int n = 0; n < 2; ++n) _Pragma("unroll") for (int k = 0; k < 2; ++k) dst[n][k] = *(const PG8_LAS bf16x8*)(lds + PG8_SB(b, h) + boff + n * 2048 + k * 1024); } while (0)
; #define PG8_MMA(ai, bj, At, Bt) do { __builtin_amdgcn_s_setprio(1); _Pragma("unroll") for (int m = 0; m < 4; ++m) _Pragma("unroll") for (int n = 0; n < 2; ++n) _Pragma("unroll") for (int k = 0; k < 2; ++k) \
;         acc[ai][bj][m][n] = __builtin_amdgcn_mfma_f32_16x16x32_bf16(Bt[n][k], At[m][k], acc[ai][bj][m][n], 0, 0, 0); __builtin_amdgcn_s_setprio(0); } while (0)
; #define PG8_WAIT_V(n) asm volatile("s_waitcnt vmcnt(" #n ")" ::: "memory")
; #define PG8_WAIT_L(n) asm volatile("s_waitcnt lgkmcnt(" #n ")" ::: "memory")
; #define PG8_BAR __builtin_amdgcn_s_barrier()
; #define PG8_SCHED __builtin_amdgcn_sched_barrier(0)
; template <class Epi, class Sched, bool ALIGN_EPI = false, bool SP2 = false>
; __device__ __forceinline__ void gemm_phase(PG8_LAS unsigned char* lds, const Gemm g, const Sched& S, const Epi& E) {
;     ...
;             PG8_WAIT_V(8); PG8_WAIT_L(0); PG8_BAR; PG8_MMA(1, 0, At, B0); PG8_MMA(1, 1, At, B1); PG8_BAR; PG8_SCHED;
;             PG8_LDB(B0, 1, 0); PG8_LDB(B1, 1, 1); PG8_SCHED; PG8_LDA(At, 1, 0); PG8_STAGE(PG8_SA(0, 1), a2 + hstepA, voffA);
;             PG8_WAIT_V(8); PG8_WAIT_L(0); PG8_BAR; PG8_MMA(0, 0, At, B0); PG8_MMA(0, 1, At, B1); PG8_BAR; PG8_SCHED;
.Lrx7_B_back:
	s_waitcnt lgkmcnt(0)
	s_barrier
	s_setprio 0
	s_waitcnt lgkmcnt(0)
	v_mfma_f32_16x16x32_bf16 v[60:63], v[166:169], v[198:201], v[60:63]
	v_mfma_f32_16x16x32_bf16 v[56:59], v[174:177], v[198:201], v[56:59]
	v_mfma_f32_16x16x32_bf16 v[52:55], v[166:169], v[206:209], v[52:55]
	v_mfma_f32_16x16x32_bf16 v[44:47], v[174:177], v[206:209], v[44:47]
	v_mfma_f32_16x16x32_bf16 v[36:39], v[166:169], v[214:217], v[36:39]
	v_mfma_f32_16x16x32_bf16 v[28:31], v[174:177], v[214:217], v[28:31]
	v_mfma_f32_16x16x32_bf16 v[20:23], v[166:169], v[222:225], v[20:23]
	v_mfma_f32_16x16x32_bf16 v[12:15], v[174:177], v[222:225], v[12:15]
	v_mfma_f32_16x16x32_bf16 v[60:63], v[170:173], v[202:205], v[60:63]
	v_mfma_f32_16x16x32_bf16 v[56:59], v[178:181], v[202:205], v[56:59]
	v_mfma_f32_16x16x32_bf16 v[52:55], v[170:173], v[210:213], v[52:55]
	v_mfma_f32_16x16x32_bf16 v[44:47], v[178:181], v[210:213], v[44:47]
	v_mfma_f32_16x16x32_bf16 v[36:39], v[170:173], v[218:221], v[36:39]
	v_mfma_f32_16x16x32_bf16 v[28:31], v[178:181], v[218:221], v[28:31]
	v_mfma_f32_16x16x32_bf16 v[20:23], v[170:173], v[226:229], v[20:23]
	v_mfma_f32_16x16x32_bf16 v[12:15], v[178:181], v[226:229], v[12:15]
	v_mfma_f32_16x16x32_bf16 v[48:51], v[182:185], v[198:201], v[48:51]
	v_mfma_f32_16x16x32_bf16 v[40:43], v[190:193], v[198:201], v[40:43]
	v_mfma_f32_16x16x32_bf16 v[32:35], v[182:185], v[206:209], v[32:35]
	v_mfma_f32_16x16x32_bf16 v[24:27], v[190:193], v[206:209], v[24:27]
	v_mfma_f32_16x16x32_bf16 v[16:19], v[182:185], v[214:217], v[16:19]
	v_mfma_f32_16x16x32_bf16 v[8:11], v[190:193], v[214:217], v[8:11]
	v_mfma_f32_16x16x32_bf16 v[4:7], v[182:185], v[222:225], v[4:7]
	v_mfma_f32_16x16x32_bf16 v[0:3], v[190:193], v[222:225], v[0:3]
	v_mfma_f32_16x16x32_bf16 v[48:51], v[186:189], v[202:205], v[48:51]
	v_mfma_f32_16x16x32_bf16 v[40:43], v[194:197], v[202:205], v[40:43]
	v_mfma_f32_16x16x32_bf16 v[32:35], v[186:189], v[210:213], v[32:35]
	v_mfma_f32_16x16x32_bf16 v[24:27], v[194:197], v[210:213], v[24:27]
	v_mfma_f32_16x16x32_bf16 v[16:19], v[186:189], v[218:221], v[16:19]
	v_mfma_f32_16x16x32_bf16 v[8:11], v[194:197], v[218:221], v[8:11]
	v_mfma_f32_16x16x32_bf16 v[4:7], v[186:189], v[226:229], v[4:7]
	v_mfma_f32_16x16x32_bf16 v[0:3], v[194:197], v[226:229], v[0:3]
	s_setprio 1
	s_barrier
	s_add_i32 s66, 0, 0x18000
	v_add_u32_e32 v163, s66, v155
	s_add_i32 s67, 0, 0x1c000
	ds_read_b128 v[166:169], v163
	ds_read_b128 v[170:173], v163 offset:1024
	ds_read_b128 v[174:177], v163 offset:2048
	ds_read_b128 v[178:181], v163 offset:3072
	v_add_u32_e32 v163, s67, v155
	ds_read_b128 v[182:185], v163
	ds_read_b128 v[186:189], v163 offset:1024
	ds_read_b128 v[190:193], v163 offset:2048
	ds_read_b128 v[194:197], v163 offset:3072
	s_add_u32 s52, s52, 0x200000
	s_addc_u32 s53, s53, 0
	s_mov_b32 m0, s31
	ds_read_b128 v[198:201], v159 offset:32768
	ds_read_b128 v[202:205], v159 offset:33792
	ds_read_b128 v[206:209], v159 offset:34816
	ds_read_b128 v[210:213], v159 offset:35840
	ds_read_b128 v[214:217], v159 offset:36864
	ds_read_b128 v[218:221], v159 offset:37888
	ds_read_b128 v[222:225], v159 offset:38912
	ds_read_b128 v[226:229], v159 offset:39936
	global_load_lds_dwordx4 v128, s[52:53]
	s_mov_b32 m0, s33
	s_nop 0
	global_load_lds_dwordx4 v132, s[52:53]
	s_waitcnt vmcnt(8)
	s_waitcnt lgkmcnt(0)
	s_barrier
	s_setprio 0
	s_waitcnt lgkmcnt(0)
	v_mfma_f32_16x16x32_bf16 v[124:127], v[166:169], v[198:201], v[124:127]
	v_mfma_f32_16x16x32_bf16 v[120:123], v[174:177], v[198:201], v[120:123]
	v_mfma_f32_16x16x32_bf16 v[116:119], v[166:169], v[206:209], v[116:119]
	v_mfma_f32_16x16x32_bf16 v[108:111], v[174:177], v[206:209], v[108:111]
	v_mfma_f32_16x16x32_bf16 v[100:103], v[166:169], v[214:217], v[100:103]
	v_mfma_f32_16x16x32_bf16 v[92:95], v[174:177], v[214:217], v[92:95]
	v_mfma_f32_16x16x32_bf16 v[80:83], v[166:169], v[222:225], v[80:83]
	v_mfma_f32_16x16x32_bf16 v[72:75], v[174:177], v[222:225], v[72:75]
	v_mfma_f32_16x16x32_bf16 v[124:127], v[170:173], v[202:205], v[124:127]
	v_mfma_f32_16x16x32_bf16 v[120:123], v[178:181], v[202:205], v[120:123]
	v_mfma_f32_16x16x32_bf16 v[116:119], v[170:173], v[210:213], v[116:119]
	v_mfma_f32_16x16x32_bf16 v[108:111], v[178:181], v[210:213], v[108:111]
	v_mfma_f32_16x16x32_bf16 v[100:103], v[170:173], v[218:221], v[100:103]
	v_mfma_f32_16x16x32_bf16 v[92:95], v[178:181], v[218:221], v[92:95]
	v_mfma_f32_16x16x32_bf16 v[80:83], v[170:173], v[226:229], v[80:83]
	v_mfma_f32_16x16x32_bf16 v[72:75], v[178:181], v[226:229], v[72:75]
	v_mfma_f32_16x16x32_bf16 v[112:115], v[182:185], v[198:201], v[112:115]
	v_mfma_f32_16x16x32_bf16 v[104:107], v[190:193], v[198:201], v[104:107]
	v_mfma_f32_16x16x32_bf16 v[96:99], v[182:185], v[206:209], v[96:99]
	v_mfma_f32_16x16x32_bf16 v[88:91], v[190:193], v[206:209], v[88:91]
	v_mfma_f32_16x16x32_bf16 v[84:87], v[182:185], v[214:217], v[84:87]
	v_mfma_f32_16x16x32_bf16 v[76:79], v[190:193], v[214:217], v[76:79]
	v_mfma_f32_16x16x32_bf16 v[68:71], v[182:185], v[222:225], v[68:71]
	v_mfma_f32_16x16x32_bf16 v[64:67], v[190:193], v[222:225], v[64:67]
	v_mfma_f32_16x16x32_bf16 v[112:115], v[186:189], v[202:205], v[112:115]
	v_mfma_f32_16x16x32_bf16 v[104:107], v[194:197], v[202:205], v[104:107]
	v_mfma_f32_16x16x32_bf16 v[96:99], v[186:189], v[210:213], v[96:99]
	v_mfma_f32_16x16x32_bf16 v[88:91], v[194:197], v[210:213], v[88:91]
	v_mfma_f32_16x16x32_bf16 v[84:87], v[186:189], v[218:221], v[84:87]
	v_mfma_f32_16x16x32_bf16 v[76:79], v[194:197], v[218:221], v[76:79]
	v_mfma_f32_16x16x32_bf16 v[68:71], v[186:189], v[226:229], v[68:71]
	v_mfma_f32_16x16x32_bf16 v[64:67], v[194:197], v[226:229], v[64:67]
	s_setprio 1
	s_barrier
; #define PG8_STAGE(bufoff, gbase, voff) do { _Pragma("unroll") for (int _i = 0; _i < 2; ++_i) \
;         __builtin_amdgcn_global_load_lds((const unsigned*)((const char*)(gbase) + (voff)[_i]), (PG8_LAS unsigned*)(lds + (bufoff) + ldsw + _i * 8192), 16, 0, 0); } while (0)
; #define PG8_LDA(dst, b, h) do { _Pragma("unroll") for (int m = 0; m < 4; ++m) _Pragma("unroll") for (int k = 0; k < 2; ++k) dst[m][k] = *(const PG8_LAS bf16x8*)(lds + PG8_SA(b, h) + aoff + m * 2048 + k * 1024); } while (0)
; #define PG8_MMA(ai, bj, At, Bt) do { __builtin_amdgcn_s_setprio(1); _Pragma("unroll") for (int m = 0; m < 4; ++m) _Pragma("unroll") for (int n = 0; n < 2; ++n) _Pragma("unroll") for (int k = 0; k < 2; ++k) \
;         acc[ai][bj][m][n] = __builtin_amdgcn_mfma_f32_16x16x32_bf16(Bt[n][k], At[m][k], acc[ai][bj][m][n], 0, 0, 0); __builtin_amdgcn_s_setprio(0); } while (0)
; #define PG8_WAIT_V(n) asm volatile("s_waitcnt vmcnt(" #n ")" ::: "memory")
; #define PG8_WAIT_L(n) asm volatile("s_waitcnt lgkmcnt(" #n ")" ::: "memory")
; #define PG8_BAR __builtin_amdgcn_s_barrier()
; #define PG8_SCHED __builtin_amdgcn_sched_barrier(0)
; template <class Epi, class Sched, bool ALIGN_EPI = false, bool SP2 = false>
; __device__ __forceinline__ void gemm_phase(PG8_LAS unsigned char* lds, const Gemm g, const Sched& S, const Epi& E) {
;     ...
;             PG8_LDA(At, 1, 1); PG8_STAGE(PG8_SB(1, 0), b3, voffB); PG8_STAGE(PG8_SB(1, 1), b3 + hstepB, voffB); PG8_STAGE(PG8_SA(1, 0), a3, voffA);
;             PG8_WAIT_V(8); PG8_WAIT_L(0); PG8_BAR; PG8_MMA(1, 0, At, B0); PG8_MMA(1, 1, At, B1); PG8_BAR; PG8_SCHED;
;     ...
;         if constexpr (ALIGN_EPI) { if (wr == 0) PG8_BAR; }
	s_add_i32 s52, s66, s28
	v_lshl_add_u64 v[144:145], v[144:145], 0, s[10:11]
	s_mov_b32 m0, s52
	ds_read_b128 v[198:201], v159 offset:49152
	ds_read_b128 v[202:205], v159 offset:50176
	ds_read_b128 v[206:209], v159 offset:51200
	ds_read_b128 v[210:213], v159 offset:52224
	ds_read_b128 v[214:217], v159 offset:53248
	ds_read_b128 v[218:221], v159 offset:54272
	ds_read_b128 v[222:225], v159 offset:55296
	ds_read_b128 v[226:229], v159 offset:56320
	global_load_lds_dwordx4 v[144:145], off
	s_add_i32 m0, s52, 0x2000
	s_add_u32 s50, s50, 0x200080
	v_lshl_add_u64 v[144:145], v[160:161], 0, s[10:11]
	s_addc_u32 s51, s51, 0
	s_add_i32 s52, s67, s28
	global_load_lds_dwordx4 v[144:145], off
	s_mov_b32 m0, s52
	s_nop 0
	global_load_lds_dwordx4 v130, s[50:51]
	s_add_i32 m0, s52, 0x2000
	s_nop 0
	global_load_lds_dwordx4 v134, s[50:51]
	v_lshl_add_u64 v[144:145], v[230:231], 0, s[10:11]
	s_mov_b32 m0, s35
	s_nop 0
	global_load_lds_dwordx4 v[144:145], off
	v_lshl_add_u64 v[144:145], v[232:233], 0, s[10:11]
	s_mov_b32 m0, s47
	s_nop 0
	global_load_lds_dwordx4 v[144:145], off
	s_waitcnt vmcnt(8)
	s_waitcnt lgkmcnt(0)
	s_barrier
	s_setprio 0
	s_waitcnt lgkmcnt(0)
	v_mfma_f32_16x16x32_bf16 v[60:63], v[166:169], v[198:201], v[60:63]
	v_mfma_f32_16x16x32_bf16 v[56:59], v[174:177], v[198:201], v[56:59]
	v_mfma_f32_16x16x32_bf16 v[52:55], v[166:169], v[206:209], v[52:55]
	v_mfma_f32_16x16x32_bf16 v[44:47], v[174:177], v[206:209], v[44:47]
	v_mfma_f32_16x16x32_bf16 v[36:39], v[166:169], v[214:217], v[36:39]
	v_mfma_f32_16x16x32_bf16 v[28:31], v[174:177], v[214:217], v[28:31]
	v_mfma_f32_16x16x32_bf16 v[20:23], v[166:169], v[222:225], v[20:23]
	v_mfma_f32_16x16x32_bf16 v[12:15], v[174:177], v[222:225], v[12:15]
	v_mfma_f32_16x16x32_bf16 v[60:63], v[170:173], v[202:205], v[60:63]
	v_mfma_f32_16x16x32_bf16 v[56:59], v[178:181], v[202:205], v[56:59]
	v_mfma_f32_16x16x32_bf16 v[52:55], v[170:173], v[210:213], v[52:55]
	v_mfma_f32_16x16x32_bf16 v[44:47], v[178:181], v[210:213], v[44:47]
	v_mfma_f32_16x16x32_bf16 v[36:39], v[170:173], v[218:221], v[36:39]
	v_mfma_f32_16x16x32_bf16 v[28:31], v[178:181], v[218:221], v[28:31]
	v_mfma_f32_16x16x32_bf16 v[20:23], v[170:173], v[226:229], v[20:23]
	v_mfma_f32_16x16x32_bf16 v[12:15], v[178:181], v[226:229], v[12:15]
	v_mfma_f32_16x16x32_bf16 v[48:51], v[182:185], v[198:201], v[48:51]
	v_mfma_f32_16x16x32_bf16 v[40:43], v[190:193], v[198:201], v[40:43]
	v_mfma_f32_16x16x32_bf16 v[32:35], v[182:185], v[206:209], v[32:35]
	v_mfma_f32_16x16x32_bf16 v[24:27], v[190:193], v[206:209], v[24:27]
	v_mfma_f32_16x16x32_bf16 v[16:19], v[182:185], v[214:217], v[16:19]
	v_mfma_f32_16x16x32_bf16 v[8:11], v[190:193], v[214:217], v[8:11]
	v_mfma_f32_16x16x32_bf16 v[4:7], v[182:185], v[222:225], v[4:7]
	v_mfma_f32_16x16x32_bf16 v[0:3], v[190:193], v[222:225], v[0:3]
	v_mfma_f32_16x16x32_bf16 v[48:51], v[186:189], v[202:205], v[48:51]
	v_mfma_f32_16x16x32_bf16 v[40:43], v[194:197], v[202:205], v[40:43]
	v_mfma_f32_16x16x32_bf16 v[32:35], v[186:189], v[210:213], v[32:35]
	v_mfma_f32_16x16x32_bf16 v[24:27], v[194:197], v[210:213], v[24:27]
	v_mfma_f32_16x16x32_bf16 v[16:19], v[186:189], v[218:221], v[16:19]
	v_mfma_f32_16x16x32_bf16 v[8:11], v[194:197], v[218:221], v[8:11]
	v_mfma_f32_16x16x32_bf16 v[4:7], v[186:189], v[226:229], v[4:7]
	v_mfma_f32_16x16x32_bf16 v[0:3], v[194:197], v[226:229], v[0:3]
	s_setprio 1
	s_barrier
	s_add_i32 s65, s65, 2
	s_add_u32 s48, s48, 0x100
	s_addc_u32 s49, s49, 0
	s_add_u32 s63, s63, 0x100
	s_addc_u32 s64, s64, 0
	s_cmpk_gt_u32 s65, 0x7d
	s_cbranch_scc0 .LBB0_1161
	s_and_b64 vcc, exec, s[16:17]
	s_cbranch_vccz .LBB0_1164
	s_barrier

; #define PG8_STAGE(bufoff, gbase, voff) do { _Pragma("unroll") for (int _i = 0; _i < 2; ++_i) \
;         __builtin_amdgcn_global_load_lds((const unsigned*)((const char*)(gbase) + (voff)[_i]), (PG8_LAS unsigned*)(lds + (bufoff) + ldsw + _i * 8192), 16, 0, 0); } while (0)
; #define PG8_WAIT_V(n) asm volatile("s_waitcnt vmcnt(" #n ")" ::: "memory")
; #define PG8_BAR __builtin_amdgcn_s_barrier()
; template <class Epi, class Sched, bool ALIGN_EPI = false, bool SP2 = false>
; __device__ __forceinline__ void gemm_phase(PG8_LAS unsigned char* lds, const Gemm g, const Sched& S, const Epi& E) {
;     ...
;     for (int i = 0; i < 2; ++i) { int R, C; stage_rc(tid * 16 + i * 8192, R, C); const int Rb = Epi::PERM ? ((R & ~31) + perm32(R & 31)) : R;
;         voffA[i] = (unsigned)(R * g.lda + C) * 2u; voffB[i] = (unsigned)(Rb * g.ldb + C) * 2u; }
;     const size_t kstep = (size_t)(BK * 2);
;     const size_t hstepA = (size_t)HALF * g.lda * 2, hstepB = (size_t)HALF * g.ldb * 2;
;     const size_t tstepA = 2 * hstepA, tstepB = 2 * hstepB;
;     const unsigned ldsw = (unsigned)wid * 1024u;
;     const int aoff = lds_byte(wr * 64 + fr, fq * 8), boff = lds_byte(wc * 32 + fr, fq * 8);
;     ...
;         PG8_STAGE(PG8_SB(0, 0), cB, voffB); PG8_STAGE(PG8_SB(0, 1), cB + hstepB, voffB); PG8_STAGE(PG8_SA(0, 0), cA, voffA); PG8_STAGE(PG8_SA(0, 1), cA + hstepA, voffA);
;         if (wr == 1) PG8_BAR;
;         PG8_WAIT_V(2); PG8_BAR;
;         PG8_STAGE(PG8_SB(1, 0), cB + kstep, voffB); PG8_STAGE(PG8_SA(1, 0), cA + kstep, voffA); PG8_STAGE(PG8_SB(1, 1), cB + hstepB + kstep, voffB);
;         PG8_WAIT_V(6); PG8_BAR;
.LBB0_1327:
	s_lshl_b32 s10, s10, 5
	s_and_b32 s18, s10, 0x60
	s_mov_b64 s[10:11], 0x80
	s_add_i32 m0, s30, 0x18000
	v_lshl_add_u64 v[6:7], v[6:7], 0, s[10:11]
	s_lshl_b32 s15, s14, 13
	s_lshl_b32 s19, s18, 7
	s_waitcnt vmcnt(2)
	s_barrier
	global_load_lds_dwordx4 v[6:7], off
	v_lshl_add_u64 v[2:3], v[2:3], 0, s[10:11]
	s_add_i32 m0, s30, 0x1a000
	s_add_i32 s43, s30, 0x8000
	s_add_i32 s50, s30, 0xa000
	global_load_lds_dwordx4 v[2:3], off
	v_lshl_add_u64 v[0:1], v[0:1], 0, s[10:11]
	s_mov_b32 m0, s43
	s_add_u32 s16, s46, 0x80080
	global_load_lds_dwordx4 v[0:1], off
	v_lshl_add_u64 v[0:1], v[4:5], 0, s[10:11]
	s_mov_b32 m0, s50
	s_addc_u32 s17, s47, 0
	global_load_lds_dwordx4 v[0:1], off
	s_add_i32 m0, s30, 0x1c000
	v_lshl_add_u64 v[0:1], s[16:17], 0, v[132:133]
	global_load_lds_dwordx4 v[0:1], off
	v_lshl_add_u64 v[0:1], s[16:17], 0, v[128:129]
	s_add_i32 m0, s30, 0x1e000
	s_waitcnt lgkmcnt(0)
	s_sext_i32_i8 s57, s4
	global_load_lds_dwordx4 v[0:1], off
	v_and_b32_e32 v0, 15, v162
	v_lshlrev_b32_e32 v1, 1, v11
	v_lshlrev_b32_e32 v2, 2, v162
	v_lshlrev_b32_e32 v3, 6, v162
	s_movk_i32 s4, 0x3c0
	v_lshl_or_b32 v150, s14, 6, v0
	v_lshl_or_b32 v0, v0, 6, v1
	v_and_b32_e32 v2, 32, v2
	v_and_or_b32 v1, v3, s4, v1
	v_bitop3_b32 v151, s19, v1, v2 bitop3:0xf6
	v_lshlrev_b32_e32 v1, 9, v162
	v_bitop3_b32 v0, v0, s15, v2 bitop3:0xde
	v_and_b32_e32 v1, 0x70000, v1
	v_lshlrev_b32_e32 v2, 12, v12
	v_or3_b32 v1, v9, v1, v2
	v_add_u32_e32 v136, v1, v10
	v_lshlrev_b32_e32 v1, 5, v8
	s_waitcnt vmcnt(0)
	s_cmpk_lt_u32 s5, 0x100
	v_and_b32_e32 v1, 0xf0000, v1
	s_cselect_b64 s[14:15], -1, 0
	v_or3_b32 v1, v9, v1, v2
	s_add_i32 s51, 0, 0x10000
	s_add_i32 s52, 0, 0x14000
	v_or_b32_e32 v152, s18, v11
	v_mov_b32_e32 v137, v133
	v_add_u32_e32 v138, v1, v10
	v_mov_b32_e32 v139, v133
	v_mov_b64_e32 v[140:141], 0x420
	v_mov_b64_e32 v[142:143], 0x41f
	v_add_u32_e32 v153, s51, v151
	v_add_u32_e32 v154, s52, v151
	v_add_u32_e32 v155, 0, v0
	s_mov_b32 s53, 0x80000
	s_mov_b64 s[16:17], 0x90000
	s_mov_b32 s54, 0x90000
	s_mov_b64 s[18:19], 0xa0000
	s_mov_b32 s55, 0xa0000
	s_mov_b64 s[20:21], 0xb0000
	s_mov_b32 s56, 0xb0000
	s_barrier
	s_branch .LBB0_1330

; template <class Epi, class Sched, bool ALIGN_EPI = false, bool SP2 = false>
; __device__ __forceinline__ void gemm_phase(PG8_LAS unsigned char* lds, const Gemm g, const Sched& S, const Epi& E) {
;     ...
;         const bool has_next = S.next(ui + 1, nxt);
;         const char* nA = has_next ? (const char*)g.A + (size_t)nxt.pm * tstepA + (size_t)nxt.kz * kzb : cA; const char* nB = has_next ? (const char*)g.Bt + (size_t)nxt.pn * tstepB + (size_t)nxt.kz * kzb : cB;
;         for (int t = 0; t < nt; t += 2) {
;             const bool last = (t == nt - 2);
;             const char* a1 = cA + (size_t)(t + 1) * kstep;
;             const char* a2 = last ? nA : cA + (size_t)(t + 2) * kstep; const char* b2 = last ? nB : cB + (size_t)(t + 2) * kstep;
;             const char* a3 = a2 + kstep; const char* b3 = b2 + kstep;
;     ...
; #pragma unroll
;         for (int a = 0; a < 2; ++a)
; #pragma unroll
;             for (int b = 0; b < 2; ++b)
; #pragma unroll
;                 for (int m = 0; m < 4; ++m)
; #pragma unroll
;                     for (int n = 0; n < 2; ++n) acc[a][b][m][n] = (f32x4){0.f, 0.f, 0.f, 0.f};
;         cur = nxt; cA = nA; cB = nB; ++ui;
.LBB0_1332:
	s_ashr_i32 s37, s36, 31
	s_lshl_b64 s[38:39], s[36:37], 20
	v_readlane_b32 s40, v240, 26
	v_readlane_b32 s41, v240, 27
	s_add_u32 s38, s40, s38
	s_addc_u32 s39, s41, s39
	s_and_b64 s[40:41], s[4:5], exec
	s_cselect_b32 s37, s39, s45
	s_cselect_b32 s58, s38, s44
	s_ashr_i32 s23, s22, 31
	s_lshl_b64 s[40:41], s[22:23], 20
	v_readlane_b32 s48, v240, 24
	v_readlane_b32 s49, v240, 25
	s_add_u32 s40, s48, s40
	s_addc_u32 s41, s49, s41
	s_and_b64 s[48:49], s[4:5], exec
	s_cselect_b32 s23, s41, s47
	s_cselect_b32 s59, s40, s46
	s_add_u32 s44, s44, 0x80080
	s_addc_u32 s45, s45, 0
	s_add_u32 s60, s46, 0x100
	v_mov_b64_e32 v[0:1], 0
	s_addc_u32 s61, s47, 0
	s_mov_b32 s62, -2
	v_mov_b64_e32 v[2:3], 0
	v_mov_b64_e32 v[4:5], 0
	v_mov_b64_e32 v[6:7], 0
	v_mov_b64_e32 v[16:17], 0
	v_mov_b64_e32 v[18:19], 0
	v_mov_b64_e32 v[20:21], 0
	v_mov_b64_e32 v[22:23], 0
	v_mov_b64_e32 v[32:33], 0
	v_mov_b64_e32 v[34:35], 0
	v_mov_b64_e32 v[36:37], 0
	v_mov_b64_e32 v[38:39], 0
	v_mov_b64_e32 v[48:49], 0
	v_mov_b64_e32 v[50:51], 0
	v_mov_b64_e32 v[52:53], 0
	v_mov_b64_e32 v[54:55], 0
	v_mov_b64_e32 v[8:9], 0
	v_mov_b64_e32 v[10:11], 0
	v_mov_b64_e32 v[12:13], 0
	v_mov_b64_e32 v[14:15], 0
	v_mov_b64_e32 v[24:25], 0
	v_mov_b64_e32 v[26:27], 0
	v_mov_b64_e32 v[28:29], 0
	v_mov_b64_e32 v[30:31], 0
	v_mov_b64_e32 v[40:41], 0
	v_mov_b64_e32 v[42:43], 0
	v_mov_b64_e32 v[44:45], 0
	v_mov_b64_e32 v[46:47], 0
	v_mov_b64_e32 v[56:57], 0
	v_mov_b64_e32 v[58:59], 0
	v_mov_b64_e32 v[60:61], 0
	v_mov_b64_e32 v[62:63], 0
	v_mov_b64_e32 v[64:65], 0
	v_mov_b64_e32 v[66:67], 0
	v_mov_b64_e32 v[68:69], 0
	v_mov_b64_e32 v[70:71], 0
	v_mov_b64_e32 v[80:81], 0
	v_mov_b64_e32 v[82:83], 0
	v_mov_b64_e32 v[84:85], 0
	v_mov_b64_e32 v[86:87], 0
	v_mov_b64_e32 v[96:97], 0
	v_mov_b64_e32 v[98:99], 0
	v_mov_b64_e32 v[100:101], 0
	v_mov_b64_e32 v[102:103], 0
	v_mov_b64_e32 v[112:113], 0
	v_mov_b64_e32 v[114:115], 0
	v_mov_b64_e32 v[116:117], 0
	v_mov_b64_e32 v[118:119], 0
	v_mov_b64_e32 v[72:73], 0
	v_mov_b64_e32 v[74:75], 0
	v_mov_b64_e32 v[76:77], 0
	v_mov_b64_e32 v[78:79], 0
	v_mov_b64_e32 v[88:89], 0
	v_mov_b64_e32 v[90:91], 0
	v_mov_b64_e32 v[92:93], 0
	v_mov_b64_e32 v[94:95], 0
	v_mov_b64_e32 v[104:105], 0
	v_mov_b64_e32 v[106:107], 0
	v_mov_b64_e32 v[108:109], 0
	v_mov_b64_e32 v[110:111], 0
	v_mov_b64_e32 v[120:121], 0
	v_mov_b64_e32 v[122:123], 0
	v_mov_b64_e32 v[124:125], 0
	v_mov_b64_e32 v[126:127], 0
	s_branch .LBB0_1333

; #define PG8_STAGE(bufoff, gbase, voff) do { _Pragma("unroll") for (int _i = 0; _i < 2; ++_i) \
;         __builtin_amdgcn_global_load_lds((const unsigned*)((const char*)(gbase) + (voff)[_i]), (PG8_LAS unsigned*)(lds + (bufoff) + ldsw + _i * 8192), 16, 0, 0); } while (0)
; #define PG8_LDA(dst, b, h) do { _Pragma("unroll") for (int m = 0; m < 4; ++m) _Pragma("unroll") for (int k = 0; k < 2; ++k) dst[m][k] = *(const PG8_LAS bf16x8*)(lds + PG8_SA(b, h) + aoff + m * 2048 + k * 1024); } while (0)
; #define PG8_LDB(dst, b, h) do { _Pragma("unroll") for (int n = 0; n < 2; ++n) _Pragma("unroll") for (int k = 0; k < 2; ++k) dst[n][k] = *(const PG8_LAS bf16x8*)(lds + PG8_SB(b, h) + boff + n * 2048 + k * 1024); } while (0)
; #define PG8_MMA(ai, bj, At, Bt) do { __builtin_amdgcn_s_setprio(1); _Pragma("unroll") for (int m = 0; m < 4; ++m) _Pragma("unroll") for (int n = 0; n < 2; ++n) _Pragma("unroll") for (int k = 0; k < 2; ++k) \
;         acc[ai][bj][m][n] = __builtin_amdgcn_mfma_f32_16x16x32_bf16(Bt[n][k], At[m][k], acc[ai][bj][m][n], 0, 0, 0); __builtin_amdgcn_s_setprio(0); } while (0)
; #define PG8_WAIT_V(n) asm volatile("s_waitcnt vmcnt(" #n ")" ::: "memory")
; #define PG8_WAIT_L(n) asm volatile("s_waitcnt lgkmcnt(" #n ")" ::: "memory")
; #define PG8_BAR __builtin_amdgcn_s_barrier()
; #define PG8_SCHED __builtin_amdgcn_sched_barrier(0)
; template <class Epi, class Sched, bool ALIGN_EPI = false, bool SP2 = false>
; __device__ __forceinline__ void gemm_phase(PG8_LAS unsigned char* lds, const Gemm g, const Sched& S, const Epi& E) {
;     ...
;             PG8_LDB(B0, 0, 0); PG8_LDB(B1, 0, 1); PG8_SCHED; PG8_LDA(At, 0, 0); PG8_STAGE(PG8_SA(1, 1), a1 + hstepA, voffA);
;             PG8_WAIT_V(8); PG8_WAIT_L(0); PG8_BAR; PG8_MMA(0, 0, At, B0); PG8_MMA(0, 1, At, B1); PG8_BAR; PG8_SCHED;
;             PG8_LDA(At, 0, 1); PG8_STAGE(PG8_SB(0, 0), b2, voffB); PG8_STAGE(PG8_SB(0, 1), b2 + hstepB, voffB); PG8_STAGE(PG8_SA(0, 0), a2, voffA);
;             PG8_WAIT_V(8); PG8_WAIT_L(0); PG8_BAR; PG8_MMA(1, 0, At, B0); PG8_MMA(1, 1, At, B1); PG8_BAR; PG8_SCHED;
.LBB0_1333:
	ds_read_b128 v[144:147], v153
	ds_read_b128 v[156:159], v153 offset:1024
	ds_read_b128 v[166:169], v153 offset:2048
	ds_read_b128 v[170:173], v153 offset:3072
	ds_read_b128 v[174:177], v154
	ds_read_b128 v[178:181], v154 offset:1024
	ds_read_b128 v[182:185], v154 offset:2048
	ds_read_b128 v[186:189], v154 offset:3072
	s_add_u32 s46, s44, 0xfff80080
	s_addc_u32 s47, s45, -1
	s_cmp_eq_u32 s62, 28
	s_cselect_b32 s49, s37, s47
	s_cselect_b32 s48, s58, s46
	s_cselect_b32 s47, s23, s61
	s_cselect_b32 s46, s59, s60
	s_add_i32 m0, s30, 0xc000
	ds_read_b128 v[190:193], v155
	ds_read_b128 v[194:197], v155 offset:1024
	ds_read_b128 v[198:201], v155 offset:2048
	ds_read_b128 v[202:205], v155 offset:3072
	ds_read_b128 v[206:209], v155 offset:4096
	ds_read_b128 v[210:213], v155 offset:5120
	ds_read_b128 v[214:217], v155 offset:6144
	ds_read_b128 v[218:221], v155 offset:7168
	global_load_lds_dwordx4 v136, s[44:45]
	s_add_i32 m0, s30, 0xe000
	s_nop 0
	global_load_lds_dwordx4 v138, s[44:45]
	s_cmp_eq_u32 s62, -2
	s_cbranch_scc1 .Lrx10_A
	s_waitcnt vmcnt(8)
.Lrx10_A_back:
	s_waitcnt lgkmcnt(0)
	s_barrier
	s_setprio 0
	s_waitcnt lgkmcnt(0)
	v_mfma_f32_16x16x32_bf16 v[124:127], v[144:147], v[190:193], v[124:127]
	v_mfma_f32_16x16x32_bf16 v[120:123], v[166:169], v[190:193], v[120:123]
	v_mfma_f32_16x16x32_bf16 v[108:111], v[144:147], v[198:201], v[108:111]
	v_mfma_f32_16x16x32_bf16 v[104:107], v[166:169], v[198:201], v[104:107]
	v_mfma_f32_16x16x32_bf16 v[92:95], v[144:147], v[206:209], v[92:95]
	v_mfma_f32_16x16x32_bf16 v[88:91], v[166:169], v[206:209], v[88:91]
	v_mfma_f32_16x16x32_bf16 v[76:79], v[144:147], v[214:217], v[76:79]
	v_mfma_f32_16x16x32_bf16 v[72:75], v[166:169], v[214:217], v[72:75]
	v_mfma_f32_16x16x32_bf16 v[124:127], v[156:159], v[194:197], v[124:127]
	v_mfma_f32_16x16x32_bf16 v[120:123], v[170:173], v[194:197], v[120:123]
	v_mfma_f32_16x16x32_bf16 v[108:111], v[156:159], v[202:205], v[108:111]
	v_mfma_f32_16x16x32_bf16 v[104:107], v[170:173], v[202:205], v[104:107]
	v_mfma_f32_16x16x32_bf16 v[92:95], v[156:159], v[210:213], v[92:95]
	v_mfma_f32_16x16x32_bf16 v[88:91], v[170:173], v[210:213], v[88:91]
	v_mfma_f32_16x16x32_bf16 v[76:79], v[156:159], v[218:221], v[76:79]
	v_mfma_f32_16x16x32_bf16 v[72:75], v[170:173], v[218:221], v[72:75]
	v_mfma_f32_16x16x32_bf16 v[116:119], v[174:177], v[190:193], v[116:119]
	v_mfma_f32_16x16x32_bf16 v[112:115], v[182:185], v[190:193], v[112:115]
	v_mfma_f32_16x16x32_bf16 v[100:103], v[174:177], v[198:201], v[100:103]
	v_mfma_f32_16x16x32_bf16 v[96:99], v[182:185], v[198:201], v[96:99]
	v_mfma_f32_16x16x32_bf16 v[84:87], v[174:177], v[206:209], v[84:87]
	v_mfma_f32_16x16x32_bf16 v[80:83], v[182:185], v[206:209], v[80:83]
	v_mfma_f32_16x16x32_bf16 v[68:71], v[174:177], v[214:217], v[68:71]
	v_mfma_f32_16x16x32_bf16 v[64:67], v[182:185], v[214:217], v[64:67]
	v_mfma_f32_16x16x32_bf16 v[116:119], v[178:181], v[194:197], v[116:119]
	v_mfma_f32_16x16x32_bf16 v[112:115], v[186:189], v[194:197], v[112:115]
	v_mfma_f32_16x16x32_bf16 v[100:103], v[178:181], v[202:205], v[100:103]
	v_mfma_f32_16x16x32_bf16 v[96:99], v[186:189], v[202:205], v[96:99]
	v_mfma_f32_16x16x32_bf16 v[84:87], v[178:181], v[210:213], v[84:87]
	v_mfma_f32_16x16x32_bf16 v[80:83], v[186:189], v[210:213], v[80:83]
	v_mfma_f32_16x16x32_bf16 v[68:71], v[178:181], v[218:221], v[68:71]
	v_mfma_f32_16x16x32_bf16 v[64:67], v[186:189], v[218:221], v[64:67]
	s_setprio 1
	s_barrier
	s_add_i32 s63, s51, s28
	v_lshl_add_u64 v[148:149], s[46:47], 0, v[132:133]
	s_mov_b32 m0, s63
	ds_read_b128 v[190:193], v155 offset:16384
	ds_read_b128 v[194:197], v155 offset:17408
	ds_read_b128 v[198:201], v155 offset:18432
	ds_read_b128 v[202:205], v155 offset:19456
	ds_read_b128 v[206:209], v155 offset:20480
	ds_read_b128 v[210:213], v155 offset:21504
	ds_read_b128 v[214:217], v155 offset:22528
	ds_read_b128 v[218:221], v155 offset:23552
	global_load_lds_dwordx4 v132, s[46:47]
	s_add_i32 m0, s63, 0x2000
	s_add_u32 s64, s46, 0x80000
	v_lshl_add_u64 v[160:161], s[46:47], 0, v[128:129]
	s_addc_u32 s65, s47, 0
	s_add_i32 s63, s52, s28
	global_load_lds_dwordx4 v128, s[46:47]
	s_mov_b32 m0, s63
	v_lshl_add_u64 v[224:225], s[48:49], 0, v[130:131]
	global_load_lds_dwordx4 v132, s[64:65]
	s_add_i32 m0, s63, 0x2000
	s_nop 0
	global_load_lds_dwordx4 v128, s[64:65]
	v_lshl_add_u64 v[222:223], s[48:49], 0, v[134:135]
	s_mov_b32 m0, s30
	s_nop 0
	global_load_lds_dwordx4 v134, s[48:49]
	s_mov_b32 m0, s31
	s_nop 0
	global_load_lds_dwordx4 v130, s[48:49]
	s_cmp_eq_u32 s62, -2
	s_cbranch_scc1 .Lrx10_B
	s_waitcnt vmcnt(8)
; #define PG8_STAGE(bufoff, gbase, voff) do { _Pragma("unroll") for (int _i = 0; _i < 2; ++_i) \
;         __builtin_amdgcn_global_load_lds((const unsigned*)((const char*)(gbase) + (voff)[_i]), (PG8_LAS unsigned*)(lds + (bufoff) + ldsw + _i * 8192), 16, 0, 0); } while (0)
; #define PG8_LDA(dst, b, h) do { _Pragma("unroll") for (int m = 0; m < 4; ++m) _Pragma("unroll") for (int k = 0; k < 2; ++k) dst[m][k] = *(const PG8_LAS bf16x8*)(lds + PG8_SA(b, h) + aoff + m * 2048 + k * 1024); } while (0)
; #define PG8_LDB(dst, b, h) do { _Pragma("unroll") for (int n = 0; n < 2; ++n) _Pragma("unroll") for (int k = 0; k < 2; ++k) dst[n][k] = *(const PG8_LAS bf16x8*)(lds + PG8_SB(b, h) + boff + n * 2048 + k * 1024); } while (0)
; #define PG8_MMA(ai, bj, At, Bt) do { __builtin_amdgcn_s_setprio(1); _Pragma("unroll") for (int m = 0; m < 4; ++m) _Pragma("unroll") for (int n = 0; n < 2; ++n) _Pragma("unroll") for (int k = 0; k < 2; ++k) \
;         acc[ai][bj][m][n] = __builtin_amdgcn_mfma_f32_16x16x32_bf16(Bt[n][k], At[m][k], acc[ai][bj][m][n], 0, 0, 0); __builtin_amdgcn_s_setprio(0); } while (0)
; #define PG8_WAIT_V(n) asm volatile("s_waitcnt vmcnt(" #n ")" ::: "memory")
; #define PG8_WAIT_L(n) asm volatile("s_waitcnt lgkmcnt(" #n ")" ::: "memory")
; #define PG8_BAR __builtin_amdgcn_s_barrier()
; #define PG8_SCHED __builtin_amdgcn_sched_barrier(0)
; template <class Epi, class Sched, bool ALIGN_EPI = false, bool SP2 = false>
; __device__ __forceinline__ void gemm_phase(PG8_LAS unsigned char* lds, const Gemm g, const Sched& S, const Epi& E) {
;     ...
;             PG8_WAIT_V(8); PG8_WAIT_L(0); PG8_BAR; PG8_MMA(1, 0, At, B0); PG8_MMA(1, 1, At, B1); PG8_BAR; PG8_SCHED;
;             PG8_LDB(B0, 1, 0); PG8_LDB(B1, 1, 1); PG8_SCHED; PG8_LDA(At, 1, 0); PG8_STAGE(PG8_SA(0, 1), a2 + hstepA, voffA);
;             PG8_WAIT_V(8); PG8_WAIT_L(0); PG8_BAR; PG8_MMA(0, 0, At, B0); PG8_MMA(0, 1, At, B1); PG8_BAR; PG8_SCHED;
.Lrx10_B_back:
	s_waitcnt lgkmcnt(0)
	s_barrier
	s_setprio 0
	s_waitcnt lgkmcnt(0)
	v_mfma_f32_16x16x32_bf16 v[60:63], v[144:147], v[190:193], v[60:63]
	v_mfma_f32_16x16x32_bf16 v[56:59], v[166:169], v[190:193], v[56:59]
	v_mfma_f32_16x16x32_bf16 v[44:47], v[144:147], v[198:201], v[44:47]
	v_mfma_f32_16x16x32_bf16 v[40:43], v[166:169], v[198:201], v[40:43]
	v_mfma_f32_16x16x32_bf16 v[28:31], v[144:147], v[206:209], v[28:31]
	v_mfma_f32_16x16x32_bf16 v[24:27], v[166:169], v[206:209], v[24:27]
	v_mfma_f32_16x16x32_bf16 v[12:15], v[144:147], v[214:217], v[12:15]
	v_mfma_f32_16x16x32_bf16 v[8:11], v[166:169], v[214:217], v[8:11]
	v_mfma_f32_16x16x32_bf16 v[60:63], v[156:159], v[194:197], v[60:63]
	v_mfma_f32_16x16x32_bf16 v[56:59], v[170:173], v[194:197], v[56:59]
	v_mfma_f32_16x16x32_bf16 v[44:47], v[156:159], v[202:205], v[44:47]
	v_mfma_f32_16x16x32_bf16 v[40:43], v[170:173], v[202:205], v[40:43]
	v_mfma_f32_16x16x32_bf16 v[28:31], v[156:159], v[210:213], v[28:31]
	v_mfma_f32_16x16x32_bf16 v[24:27], v[170:173], v[210:213], v[24:27]
	v_mfma_f32_16x16x32_bf16 v[12:15], v[156:159], v[218:221], v[12:15]
	v_mfma_f32_16x16x32_bf16 v[8:11], v[170:173], v[218:221], v[8:11]
	v_mfma_f32_16x16x32_bf16 v[52:55], v[174:177], v[190:193], v[52:55]
	v_mfma_f32_16x16x32_bf16 v[48:51], v[182:185], v[190:193], v[48:51]
	v_mfma_f32_16x16x32_bf16 v[36:39], v[174:177], v[198:201], v[36:39]
	v_mfma_f32_16x16x32_bf16 v[32:35], v[182:185], v[198:201], v[32:35]
	v_mfma_f32_16x16x32_bf16 v[20:23], v[174:177], v[206:209], v[20:23]
	v_mfma_f32_16x16x32_bf16 v[16:19], v[182:185], v[206:209], v[16:19]
	v_mfma_f32_16x16x32_bf16 v[4:7], v[174:177], v[214:217], v[4:7]
	v_mfma_f32_16x16x32_bf16 v[0:3], v[182:185], v[214:217], v[0:3]
	v_mfma_f32_16x16x32_bf16 v[52:55], v[178:181], v[194:197], v[52:55]
	v_mfma_f32_16x16x32_bf16 v[48:51], v[186:189], v[194:197], v[48:51]
	v_mfma_f32_16x16x32_bf16 v[36:39], v[178:181], v[202:205], v[36:39]
	v_mfma_f32_16x16x32_bf16 v[32:35], v[186:189], v[202:205], v[32:35]
	v_mfma_f32_16x16x32_bf16 v[20:23], v[178:181], v[210:213], v[20:23]
	v_mfma_f32_16x16x32_bf16 v[16:19], v[186:189], v[210:213], v[16:19]
	v_mfma_f32_16x16x32_bf16 v[4:7], v[178:181], v[218:221], v[4:7]
	v_mfma_f32_16x16x32_bf16 v[0:3], v[186:189], v[218:221], v[0:3]
	s_setprio 1
	s_barrier
	s_add_i32 s63, 0, 0x18000
	v_add_u32_e32 v163, s63, v151
	s_add_i32 s64, 0, 0x1c000
	ds_read_b128 v[144:147], v163
	ds_read_b128 v[156:159], v163 offset:1024
	ds_read_b128 v[166:169], v163 offset:2048
	ds_read_b128 v[170:173], v163 offset:3072
	v_add_u32_e32 v163, s64, v151
	ds_read_b128 v[174:177], v163
	ds_read_b128 v[178:181], v163 offset:1024
	ds_read_b128 v[182:185], v163 offset:2048
	ds_read_b128 v[186:189], v163 offset:3072
	s_add_u32 s48, s48, 0x80000
	s_addc_u32 s49, s49, 0
	s_mov_b32 m0, s33
	ds_read_b128 v[190:193], v155 offset:32768
	ds_read_b128 v[194:197], v155 offset:33792
	ds_read_b128 v[198:201], v155 offset:34816
	ds_read_b128 v[202:205], v155 offset:35840
	ds_read_b128 v[206:209], v155 offset:36864
	ds_read_b128 v[210:213], v155 offset:37888
	ds_read_b128 v[214:217], v155 offset:38912
	ds_read_b128 v[218:221], v155 offset:39936
	global_load_lds_dwordx4 v134, s[48:49]
	s_mov_b32 m0, s34
	s_nop 0
	global_load_lds_dwordx4 v130, s[48:49]
	s_waitcnt vmcnt(8)
	s_waitcnt lgkmcnt(0)
	s_barrier
	s_setprio 0
	s_waitcnt lgkmcnt(0)
	v_mfma_f32_16x16x32_bf16 v[124:127], v[144:147], v[190:193], v[124:127]
	v_mfma_f32_16x16x32_bf16 v[120:123], v[166:169], v[190:193], v[120:123]
	v_mfma_f32_16x16x32_bf16 v[108:111], v[144:147], v[198:201], v[108:111]
	v_mfma_f32_16x16x32_bf16 v[104:107], v[166:169], v[198:201], v[104:107]
	v_mfma_f32_16x16x32_bf16 v[92:95], v[144:147], v[206:209], v[92:95]
	v_mfma_f32_16x16x32_bf16 v[88:91], v[166:169], v[206:209], v[88:91]
	v_mfma_f32_16x16x32_bf16 v[76:79], v[144:147], v[214:217], v[76:79]
	v_mfma_f32_16x16x32_bf16 v[72:75], v[166:169], v[214:217], v[72:75]
	v_mfma_f32_16x16x32_bf16 v[124:127], v[156:159], v[194:197], v[124:127]
	v_mfma_f32_16x16x32_bf16 v[120:123], v[170:173], v[194:197], v[120:123]
	v_mfma_f32_16x16x32_bf16 v[108:111], v[156:159], v[202:205], v[108:111]
	v_mfma_f32_16x16x32_bf16 v[104:107], v[170:173], v[202:205], v[104:107]
	v_mfma_f32_16x16x32_bf16 v[92:95], v[156:159], v[210:213], v[92:95]
	v_mfma_f32_16x16x32_bf16 v[88:91], v[170:173], v[210:213], v[88:91]
	v_mfma_f32_16x16x32_bf16 v[76:79], v[156:159], v[218:221], v[76:79]
	v_mfma_f32_16x16x32_bf16 v[72:75], v[170:173], v[218:221], v[72:75]
	v_mfma_f32_16x16x32_bf16 v[116:119], v[174:177], v[190:193], v[116:119]
	v_mfma_f32_16x16x32_bf16 v[112:115], v[182:185], v[190:193], v[112:115]
	v_mfma_f32_16x16x32_bf16 v[100:103], v[174:177], v[198:201], v[100:103]
	v_mfma_f32_16x16x32_bf16 v[96:99], v[182:185], v[198:201], v[96:99]
	v_mfma_f32_16x16x32_bf16 v[84:87], v[174:177], v[206:209], v[84:87]
	v_mfma_f32_16x16x32_bf16 v[80:83], v[182:185], v[206:209], v[80:83]
	v_mfma_f32_16x16x32_bf16 v[68:71], v[174:177], v[214:217], v[68:71]
	v_mfma_f32_16x16x32_bf16 v[64:67], v[182:185], v[214:217], v[64:67]
	v_mfma_f32_16x16x32_bf16 v[116:119], v[178:181], v[194:197], v[116:119]
	v_mfma_f32_16x16x32_bf16 v[112:115], v[186:189], v[194:197], v[112:115]
	v_mfma_f32_16x16x32_bf16 v[100:103], v[178:181], v[202:205], v[100:103]
	v_mfma_f32_16x16x32_bf16 v[96:99], v[186:189], v[202:205], v[96:99]
	v_mfma_f32_16x16x32_bf16 v[84:87], v[178:181], v[210:213], v[84:87]
	v_mfma_f32_16x16x32_bf16 v[80:83], v[186:189], v[210:213], v[80:83]
	v_mfma_f32_16x16x32_bf16 v[68:71], v[178:181], v[218:221], v[68:71]
	v_mfma_f32_16x16x32_bf16 v[64:67], v[186:189], v[218:221], v[64:67]
	s_setprio 1
	s_barrier
; #define PG8_STAGE(bufoff, gbase, voff) do { _Pragma("unroll") for (int _i = 0; _i < 2; ++_i) \
;         __builtin_amdgcn_global_load_lds((const unsigned*)((const char*)(gbase) + (voff)[_i]), (PG8_LAS unsigned*)(lds + (bufoff) + ldsw + _i * 8192), 16, 0, 0); } while (0)
; #define PG8_LDA(dst, b, h) do { _Pragma("unroll") for (int m = 0; m < 4; ++m) _Pragma("unroll") for (int k = 0; k < 2; ++k) dst[m][k] = *(const PG8_LAS bf16x8*)(lds + PG8_SA(b, h) + aoff + m * 2048 + k * 1024); } while (0)
; #define PG8_MMA(ai, bj, At, Bt) do { __builtin_amdgcn_s_setprio(1); _Pragma("unroll") for (int m = 0; m < 4; ++m) _Pragma("unroll") for (int n = 0; n < 2; ++n) _Pragma("unroll") for (int k = 0; k < 2; ++k) \
;         acc[ai][bj][m][n] = __builtin_amdgcn_mfma_f32_16x16x32_bf16(Bt[n][k], At[m][k], acc[ai][bj][m][n], 0, 0, 0); __builtin_amdgcn_s_setprio(0); } while (0)
; #define PG8_WAIT_V(n) asm volatile("s_waitcnt vmcnt(" #n ")" ::: "memory")
; #define PG8_WAIT_L(n) asm volatile("s_waitcnt lgkmcnt(" #n ")" ::: "memory")
; #define PG8_BAR __builtin_amdgcn_s_barrier()
; #define PG8_SCHED __builtin_amdgcn_sched_barrier(0)
; template <class Epi, class Sched, bool ALIGN_EPI = false, bool SP2 = false>
; __device__ __forceinline__ void gemm_phase(PG8_LAS unsigned char* lds, const Gemm g, const Sched& S, const Epi& E) {
;     ...
;             PG8_LDA(At, 1, 1); PG8_STAGE(PG8_SB(1, 0), b3, voffB); PG8_STAGE(PG8_SB(1, 1), b3 + hstepB, voffB); PG8_STAGE(PG8_SA(1, 0), a3, voffA);
;             PG8_WAIT_V(8); PG8_WAIT_L(0); PG8_BAR; PG8_MMA(1, 0, At, B0); PG8_MMA(1, 1, At, B1); PG8_BAR; PG8_SCHED;
;     ...
;         if constexpr (ALIGN_EPI) { if (wr == 0) PG8_BAR; }
	s_add_i32 s48, s63, s28
	v_lshl_add_u64 v[148:149], v[148:149], 0, s[10:11]
	s_mov_b32 m0, s48
	ds_read_b128 v[190:193], v155 offset:49152
	ds_read_b128 v[194:197], v155 offset:50176
	ds_read_b128 v[198:201], v155 offset:51200
	ds_read_b128 v[202:205], v155 offset:52224
	ds_read_b128 v[206:209], v155 offset:53248
	ds_read_b128 v[210:213], v155 offset:54272
	ds_read_b128 v[214:217], v155 offset:55296
	ds_read_b128 v[218:221], v155 offset:56320
	global_load_lds_dwordx4 v[148:149], off
	s_add_i32 m0, s48, 0x2000
	s_add_u32 s46, s46, 0x80080
	v_lshl_add_u64 v[148:149], v[160:161], 0, s[10:11]
	s_addc_u32 s47, s47, 0
	s_add_i32 s48, s64, s28
	global_load_lds_dwordx4 v[148:149], off
	s_mov_b32 m0, s48
	s_nop 0
	global_load_lds_dwordx4 v132, s[46:47]
	s_add_i32 m0, s48, 0x2000
	s_nop 0
	global_load_lds_dwordx4 v128, s[46:47]
	v_lshl_add_u64 v[148:149], v[222:223], 0, s[10:11]
	s_mov_b32 m0, s43
	s_nop 0
	global_load_lds_dwordx4 v[148:149], off
	v_lshl_add_u64 v[148:149], v[224:225], 0, s[10:11]
	s_mov_b32 m0, s50
	s_nop 0
	global_load_lds_dwordx4 v[148:149], off
	s_waitcnt vmcnt(8)
	s_waitcnt lgkmcnt(0)
	s_barrier
	s_setprio 0
	s_waitcnt lgkmcnt(0)
	v_mfma_f32_16x16x32_bf16 v[60:63], v[144:147], v[190:193], v[60:63]
	v_mfma_f32_16x16x32_bf16 v[56:59], v[166:169], v[190:193], v[56:59]
	v_mfma_f32_16x16x32_bf16 v[44:47], v[144:147], v[198:201], v[44:47]
	v_mfma_f32_16x16x32_bf16 v[40:43], v[166:169], v[198:201], v[40:43]
	v_mfma_f32_16x16x32_bf16 v[28:31], v[144:147], v[206:209], v[28:31]
	v_mfma_f32_16x16x32_bf16 v[24:27], v[166:169], v[206:209], v[24:27]
	v_mfma_f32_16x16x32_bf16 v[12:15], v[144:147], v[214:217], v[12:15]
	v_mfma_f32_16x16x32_bf16 v[8:11], v[166:169], v[214:217], v[8:11]
	v_mfma_f32_16x16x32_bf16 v[60:63], v[156:159], v[194:197], v[60:63]
	v_mfma_f32_16x16x32_bf16 v[56:59], v[170:173], v[194:197], v[56:59]
	v_mfma_f32_16x16x32_bf16 v[44:47], v[156:159], v[202:205], v[44:47]
	v_mfma_f32_16x16x32_bf16 v[40:43], v[170:173], v[202:205], v[40:43]
	v_mfma_f32_16x16x32_bf16 v[28:31], v[156:159], v[210:213], v[28:31]
	v_mfma_f32_16x16x32_bf16 v[24:27], v[170:173], v[210:213], v[24:27]
	v_mfma_f32_16x16x32_bf16 v[12:15], v[156:159], v[218:221], v[12:15]
	v_mfma_f32_16x16x32_bf16 v[8:11], v[170:173], v[218:221], v[8:11]
	v_mfma_f32_16x16x32_bf16 v[52:55], v[174:177], v[190:193], v[52:55]
	v_mfma_f32_16x16x32_bf16 v[48:51], v[182:185], v[190:193], v[48:51]
	v_mfma_f32_16x16x32_bf16 v[36:39], v[174:177], v[198:201], v[36:39]
	v_mfma_f32_16x16x32_bf16 v[32:35], v[182:185], v[198:201], v[32:35]
	v_mfma_f32_16x16x32_bf16 v[20:23], v[174:177], v[206:209], v[20:23]
	v_mfma_f32_16x16x32_bf16 v[16:19], v[182:185], v[206:209], v[16:19]
	v_mfma_f32_16x16x32_bf16 v[4:7], v[174:177], v[214:217], v[4:7]
	v_mfma_f32_16x16x32_bf16 v[0:3], v[182:185], v[214:217], v[0:3]
	v_mfma_f32_16x16x32_bf16 v[52:55], v[178:181], v[194:197], v[52:55]
	v_mfma_f32_16x16x32_bf16 v[48:51], v[186:189], v[194:197], v[48:51]
	v_mfma_f32_16x16x32_bf16 v[36:39], v[178:181], v[202:205], v[36:39]
	v_mfma_f32_16x16x32_bf16 v[32:35], v[186:189], v[202:205], v[32:35]
	v_mfma_f32_16x16x32_bf16 v[20:23], v[178:181], v[210:213], v[20:23]
	v_mfma_f32_16x16x32_bf16 v[16:19], v[186:189], v[210:213], v[16:19]
	v_mfma_f32_16x16x32_bf16 v[4:7], v[178:181], v[218:221], v[4:7]
	v_mfma_f32_16x16x32_bf16 v[0:3], v[186:189], v[218:221], v[0:3]
	s_setprio 1
	s_barrier
	s_add_i32 s62, s62, 2
	s_add_u32 s44, s44, 0x100
	s_addc_u32 s45, s45, 0
	s_add_u32 s60, s60, 0x100
	s_addc_u32 s61, s61, 0
	s_cmp_gt_u32 s62, 29
	s_cbranch_scc0 .LBB0_1333
	s_and_b64 vcc, exec, s[14:15]
	s_cbranch_vccz .LBB0_1336
	s_barrier
